# GEMM K-loops: within each set of 8 independent MFMAs the 2x4 A/B fragment pairs are visited in snake order so that only one source operand changes between consecutive MFMAs (same accumulators and depe
# speedup vs baseline: 1.0622x; 1.0007x over previous
; #define PG8_STAGE(bufoff, gbase, voff) do { _Pragma("unroll") for (int _i = 0; _i < 2; ++_i) \
;         __builtin_amdgcn_global_load_lds((const unsigned*)((const char*)(gbase) + (voff)[_i]), (PG8_LAS unsigned*)(lds + (bufoff) + ldsw + _i * 8192), 16, 0, 0); } while (0)
; #define PG8_LDA(dst, b, h) do { _Pragma("unroll") for (int m = 0; m < 4; ++m) _Pragma("unroll") for (int k = 0; k < 2; ++k) dst[m][k] = *(const PG8_LAS bf16x8*)(lds + PG8_SA(b, h) + aoff + m * 2048 + k * 1024); } while (0)
; #define PG8_LDB(dst, b, h) do { _Pragma("unroll") for (int n = 0; n < 2; ++n) _Pragma("unroll") for (int k = 0; k < 2; ++k) dst[n][k] = *(const PG8_LAS bf16x8*)(lds + PG8_SB(b, h) + boff + n * 2048 + k * 1024); } while (0)
; #define PG8_MMA(ai, bj, At, Bt) do { __builtin_amdgcn_s_setprio(1); _Pragma("unroll") for (int m = 0; m < 4; ++m) _Pragma("unroll") for (int n = 0; n < 2; ++n) _Pragma("unroll") for (int k = 0; k < 2; ++k) \
;         acc[ai][bj][m][n] = __builtin_amdgcn_mfma_f32_16x16x32_bf16(Bt[n][k], At[m][k], acc[ai][bj][m][n], 0, 0, 0); __builtin_amdgcn_s_setprio(0); } while (0)
; #define PG8_WAIT_V(n) asm volatile("s_waitcnt vmcnt(" #n ")" ::: "memory")
; #define PG8_BAR __builtin_amdgcn_s_barrier()
; template <class Epi, class Sched, bool ALIGN_EPI = false, bool SP2 = false>
; __device__ __forceinline__ void gemm_phase(PG8_LAS unsigned char* lds, const Gemm g, const Sched& S, const Epi& E) {
;     ...
;         for (int t = 0; t < nt; t += 2) {
;             const bool last = (t == nt - 2);
;             const char* a1 = cA + (size_t)(t + 1) * kstep;
;             const char* a2 = last ? nA : cA + (size_t)(t + 2) * kstep; const char* b2 = last ? nB : cB + (size_t)(t + 2) * kstep;
;             const char* a3 = a2 + kstep; const char* b3 = b2 + kstep;
;             if (last && has_next) S.a_ready(nxt);
;             if constexpr (SP2) {
;             PG8_LDB(B0, 0, 0); PG8_LDB(B1, 0, 1); PG8_SCHED; PG8_LDA(At, 0, 0); PG8_STAGE(PG8_SA(1, 1), a1 + hstep, voffA);
;             PG8_WAIT_V(8); PG8_WAIT_L(0); PG8_BAR; PG8_MMA(0, 0, At, B0); PG8_MMA(0, 1, At, B1); PG8_BAR; PG8_SCHED;
;             PG8_LDA(At, 0, 1); PG8_STAGE(PG8_SB(0, 0), b2, voffB); PG8_STAGE(PG8_SB(0, 1), b2 + hstep, voffB); PG8_STAGE(PG8_SA(0, 0), a2, voffA);
;             PG8_WAIT_V(8); PG8_WAIT_L(0); PG8_BAR; PG8_MMA(1, 0, At, B0); PG8_MMA(1, 1, At, B1); PG8_BAR; PG8_SCHED;
.LBB0_162:
	s_add_u32 s10, s44, 0xfffc0080
	s_addc_u32 s11, s45, -1
	s_add_i32 s60, 16, 0x10000
	s_cmp_eq_u32 s59, 12
	s_cselect_b32 s49, s27, s11
	s_cselect_b32 s48, s34, s10
	s_cselect_b32 s47, s25, s58
	s_cselect_b32 s46, s35, s57
	s_add_i32 s10, 16, 0x14000
	v_add_u32_e32 v102, s60, v183
	v_add_u32_e32 v180, s10, v183
	ds_read_b128 v[90:93], v102
	ds_read_b128 v[94:97], v102 offset:1024
	ds_read_b128 v[98:101], v102 offset:2048
	ds_read_b128 v[102:105], v102 offset:3072
	ds_read_b128 v[158:161], v180
	ds_read_b128 v[176:179], v180 offset:1024
	ds_read_b128 v[186:189], v180 offset:2048
	ds_read_b128 v[190:193], v180 offset:3072
	v_lshl_add_u64 v[180:181], s[44:45], 0, v[156:157]
	s_add_i32 m0, s7, 0xc000
	ds_read_b128 v[194:197], v185
	ds_read_b128 v[198:201], v185 offset:1024
	ds_read_b128 v[202:205], v185 offset:2048
	ds_read_b128 v[206:209], v185 offset:3072
	ds_read_b128 v[210:213], v185 offset:4096
	ds_read_b128 v[214:217], v185 offset:5120
	ds_read_b128 v[218:221], v185 offset:6144
	ds_read_b128 v[222:225], v185 offset:7168
	global_load_lds_dwordx4 v[180:181], off
	v_lshl_add_u64 v[180:181], s[44:45], 0, v[154:155]
	s_add_i32 m0, s7, 0xe000
	s_nop 0
	global_load_lds_dwordx4 v[180:181], off
	s_waitcnt vmcnt(8)
	s_waitcnt lgkmcnt(0)
	s_setprio 1
	s_barrier
	v_mfma_f32_16x16x32_bf16 v[142:145], v[90:93], v[194:197], v[142:145]
	v_mfma_f32_16x16x32_bf16 v[138:141], v[98:101], v[194:197], v[138:141]
	v_mfma_f32_16x16x32_bf16 v[122:125], v[98:101], v[202:205], v[122:125]
	v_mfma_f32_16x16x32_bf16 v[126:129], v[90:93], v[202:205], v[126:129]
	v_mfma_f32_16x16x32_bf16 v[110:113], v[90:93], v[210:213], v[110:113]
	v_mfma_f32_16x16x32_bf16 v[106:109], v[98:101], v[210:213], v[106:109]
	v_mfma_f32_16x16x32_bf16 v[74:77], v[98:101], v[218:221], v[74:77]
	v_mfma_f32_16x16x32_bf16 v[78:81], v[90:93], v[218:221], v[78:81]
	v_mfma_f32_16x16x32_bf16 v[142:145], v[94:97], v[198:201], v[142:145]
	v_mfma_f32_16x16x32_bf16 v[138:141], v[102:105], v[198:201], v[138:141]
	v_mfma_f32_16x16x32_bf16 v[122:125], v[102:105], v[206:209], v[122:125]
	v_mfma_f32_16x16x32_bf16 v[126:129], v[94:97], v[206:209], v[126:129]
	v_mfma_f32_16x16x32_bf16 v[110:113], v[94:97], v[214:217], v[110:113]
	v_mfma_f32_16x16x32_bf16 v[106:109], v[102:105], v[214:217], v[106:109]
	v_mfma_f32_16x16x32_bf16 v[74:77], v[102:105], v[222:225], v[74:77]
	v_mfma_f32_16x16x32_bf16 v[78:81], v[94:97], v[222:225], v[78:81]
	v_mfma_f32_16x16x32_bf16 v[134:137], v[158:161], v[194:197], v[134:137]
	v_mfma_f32_16x16x32_bf16 v[130:133], v[186:189], v[194:197], v[130:133]
	v_mfma_f32_16x16x32_bf16 v[114:117], v[186:189], v[202:205], v[114:117]
	v_mfma_f32_16x16x32_bf16 v[118:121], v[158:161], v[202:205], v[118:121]
	v_mfma_f32_16x16x32_bf16 v[86:89], v[158:161], v[210:213], v[86:89]
	v_mfma_f32_16x16x32_bf16 v[82:85], v[186:189], v[210:213], v[82:85]
	v_mfma_f32_16x16x32_bf16 v[66:69], v[186:189], v[218:221], v[66:69]
	v_mfma_f32_16x16x32_bf16 v[70:73], v[158:161], v[218:221], v[70:73]
	v_mfma_f32_16x16x32_bf16 v[134:137], v[176:179], v[198:201], v[134:137]
	v_mfma_f32_16x16x32_bf16 v[130:133], v[190:193], v[198:201], v[130:133]
	v_mfma_f32_16x16x32_bf16 v[114:117], v[190:193], v[206:209], v[114:117]
	v_mfma_f32_16x16x32_bf16 v[118:121], v[176:179], v[206:209], v[118:121]
	v_mfma_f32_16x16x32_bf16 v[86:89], v[176:179], v[214:217], v[86:89]
	v_mfma_f32_16x16x32_bf16 v[82:85], v[190:193], v[214:217], v[82:85]
	v_mfma_f32_16x16x32_bf16 v[66:69], v[190:193], v[222:225], v[66:69]
	v_mfma_f32_16x16x32_bf16 v[70:73], v[176:179], v[222:225], v[70:73]
	s_barrier
	s_setprio 0
	s_add_i32 s11, s60, s6
	v_lshl_add_u64 v[180:181], s[46:47], 0, v[0:1]
	s_mov_b32 m0, s11
	ds_read_b128 v[194:197], v185 offset:16384
	ds_read_b128 v[198:201], v185 offset:17408
	ds_read_b128 v[202:205], v185 offset:18432
	ds_read_b128 v[206:209], v185 offset:19456
	ds_read_b128 v[210:213], v185 offset:20480
	ds_read_b128 v[214:217], v185 offset:21504
	ds_read_b128 v[218:221], v185 offset:22528
	ds_read_b128 v[222:225], v185 offset:23552
	global_load_lds_dwordx4 v[180:181], off
	s_add_i32 m0, s11, 0x2000
	s_add_u32 s60, s46, 0x40000
	v_lshl_add_u64 v[226:227], s[46:47], 0, v[146:147]
	s_addc_u32 s61, s47, 0
	s_add_i32 s10, s10, s6
	global_load_lds_dwordx4 v[226:227], off
	v_lshl_add_u64 v[238:239], s[60:61], 0, v[0:1]
	s_mov_b32 m0, s10
	v_lshl_add_u64 v[240:241], s[48:49], 0, v[148:149]
	global_load_lds_dwordx4 v[238:239], off
	v_lshl_add_u64 v[238:239], s[60:61], 0, v[146:147]
	s_add_i32 m0, s10, 0x2000
	s_nop 0
	global_load_lds_dwordx4 v[238:239], off
	v_lshl_add_u64 v[238:239], s[48:49], 0, v[150:151]
	s_mov_b32 m0, s7
	s_nop 0
	global_load_lds_dwordx4 v[238:239], off
	s_mov_b32 m0, s8
	s_nop 0
	global_load_lds_dwordx4 v[240:241], off
	s_waitcnt vmcnt(8)
	s_waitcnt lgkmcnt(0)
	s_setprio 1
	s_barrier
; #define PG8_STAGE(bufoff, gbase, voff) do { _Pragma("unroll") for (int _i = 0; _i < 2; ++_i) \
;         __builtin_amdgcn_global_load_lds((const unsigned*)((const char*)(gbase) + (voff)[_i]), (PG8_LAS unsigned*)(lds + (bufoff) + ldsw + _i * 8192), 16, 0, 0); } while (0)
; #define PG8_LDA(dst, b, h) do { _Pragma("unroll") for (int m = 0; m < 4; ++m) _Pragma("unroll") for (int k = 0; k < 2; ++k) dst[m][k] = *(const PG8_LAS bf16x8*)(lds + PG8_SA(b, h) + aoff + m * 2048 + k * 1024); } while (0)
; #define PG8_LDB(dst, b, h) do { _Pragma("unroll") for (int n = 0; n < 2; ++n) _Pragma("unroll") for (int k = 0; k < 2; ++k) dst[n][k] = *(const PG8_LAS bf16x8*)(lds + PG8_SB(b, h) + boff + n * 2048 + k * 1024); } while (0)
; #define PG8_MMA(ai, bj, At, Bt) do { __builtin_amdgcn_s_setprio(1); _Pragma("unroll") for (int m = 0; m < 4; ++m) _Pragma("unroll") for (int n = 0; n < 2; ++n) _Pragma("unroll") for (int k = 0; k < 2; ++k) \
;         acc[ai][bj][m][n] = __builtin_amdgcn_mfma_f32_16x16x32_bf16(Bt[n][k], At[m][k], acc[ai][bj][m][n], 0, 0, 0); __builtin_amdgcn_s_setprio(0); } while (0)
; #define PG8_WAIT_V(n) asm volatile("s_waitcnt vmcnt(" #n ")" ::: "memory")
; #define PG8_WAIT_L(n) asm volatile("s_waitcnt lgkmcnt(" #n ")" ::: "memory")
; #define PG8_BAR __builtin_amdgcn_s_barrier()
; #define PG8_SCHED __builtin_amdgcn_sched_barrier(0)
; template <class Epi, class Sched, bool ALIGN_EPI = false, bool SP2 = false>
; __device__ __forceinline__ void gemm_phase(PG8_LAS unsigned char* lds, const Gemm g, const Sched& S, const Epi& E) {
;     ...
;             PG8_WAIT_V(8); PG8_WAIT_L(0); PG8_BAR; PG8_MMA(1, 0, At, B0); PG8_MMA(1, 1, At, B1); PG8_BAR; PG8_SCHED;
;             PG8_LDB(B0, 1, 0); PG8_LDB(B1, 1, 1); PG8_SCHED; PG8_LDA(At, 1, 0); PG8_STAGE(PG8_SA(0, 1), a2 + hstep, voffA);
;             PG8_WAIT_V(8); PG8_WAIT_L(0); PG8_BAR; PG8_MMA(0, 0, At, B0); PG8_MMA(0, 1, At, B1); PG8_BAR; PG8_SCHED;
	v_mfma_f32_16x16x32_bf16 v[62:65], v[90:93], v[194:197], v[62:65]
	v_mfma_f32_16x16x32_bf16 v[58:61], v[98:101], v[194:197], v[58:61]
	v_mfma_f32_16x16x32_bf16 v[42:45], v[98:101], v[202:205], v[42:45]
	v_mfma_f32_16x16x32_bf16 v[46:49], v[90:93], v[202:205], v[46:49]
	v_mfma_f32_16x16x32_bf16 v[30:33], v[90:93], v[210:213], v[30:33]
	v_mfma_f32_16x16x32_bf16 v[26:29], v[98:101], v[210:213], v[26:29]
	v_mfma_f32_16x16x32_bf16 v[10:13], v[98:101], v[218:221], v[10:13]
	v_mfma_f32_16x16x32_bf16 v[14:17], v[90:93], v[218:221], v[14:17]
	v_mfma_f32_16x16x32_bf16 v[62:65], v[94:97], v[198:201], v[62:65]
	v_mfma_f32_16x16x32_bf16 v[58:61], v[102:105], v[198:201], v[58:61]
	v_mfma_f32_16x16x32_bf16 v[42:45], v[102:105], v[206:209], v[42:45]
	v_mfma_f32_16x16x32_bf16 v[46:49], v[94:97], v[206:209], v[46:49]
	v_mfma_f32_16x16x32_bf16 v[30:33], v[94:97], v[214:217], v[30:33]
	v_mfma_f32_16x16x32_bf16 v[26:29], v[102:105], v[214:217], v[26:29]
	v_mfma_f32_16x16x32_bf16 v[10:13], v[102:105], v[222:225], v[10:13]
	v_mfma_f32_16x16x32_bf16 v[14:17], v[94:97], v[222:225], v[14:17]
	v_mfma_f32_16x16x32_bf16 v[54:57], v[158:161], v[194:197], v[54:57]
	v_mfma_f32_16x16x32_bf16 v[50:53], v[186:189], v[194:197], v[50:53]
	v_mfma_f32_16x16x32_bf16 v[34:37], v[186:189], v[202:205], v[34:37]
	v_mfma_f32_16x16x32_bf16 v[38:41], v[158:161], v[202:205], v[38:41]
	v_mfma_f32_16x16x32_bf16 v[22:25], v[158:161], v[210:213], v[22:25]
	v_mfma_f32_16x16x32_bf16 v[18:21], v[186:189], v[210:213], v[18:21]
	v_mfma_f32_16x16x32_bf16 v[2:5], v[186:189], v[218:221], v[2:5]
	v_mfma_f32_16x16x32_bf16 v[6:9], v[158:161], v[218:221], v[6:9]
	v_mfma_f32_16x16x32_bf16 v[54:57], v[176:179], v[198:201], v[54:57]
	v_mfma_f32_16x16x32_bf16 v[50:53], v[190:193], v[198:201], v[50:53]
	v_mfma_f32_16x16x32_bf16 v[34:37], v[190:193], v[206:209], v[34:37]
	v_mfma_f32_16x16x32_bf16 v[38:41], v[176:179], v[206:209], v[38:41]
	v_mfma_f32_16x16x32_bf16 v[22:25], v[176:179], v[214:217], v[22:25]
	v_mfma_f32_16x16x32_bf16 v[18:21], v[190:193], v[214:217], v[18:21]
	v_mfma_f32_16x16x32_bf16 v[2:5], v[190:193], v[222:225], v[2:5]
	v_mfma_f32_16x16x32_bf16 v[6:9], v[176:179], v[222:225], v[6:9]
	s_barrier
	s_setprio 0
	s_add_i32 s10, 16, 0x18000
	s_add_i32 s11, 16, 0x1c000
	v_add_u32_e32 v102, s10, v183
	v_add_u32_e32 v190, s11, v183
	ds_read_b128 v[90:93], v102
	ds_read_b128 v[94:97], v102 offset:1024
	ds_read_b128 v[98:101], v102 offset:2048
	ds_read_b128 v[102:105], v102 offset:3072
	ds_read_b128 v[158:161], v190
	ds_read_b128 v[176:179], v190 offset:1024
	ds_read_b128 v[186:189], v190 offset:2048
	ds_read_b128 v[190:193], v190 offset:3072
	s_add_u32 s48, s48, 0x40000
	s_addc_u32 s49, s49, 0
	s_mov_b32 m0, s9
	v_lshl_add_u64 v[242:243], s[48:49], 0, v[150:151]
	ds_read_b128 v[194:197], v185 offset:32768
	ds_read_b128 v[198:201], v185 offset:33792
	ds_read_b128 v[202:205], v185 offset:34816
	ds_read_b128 v[206:209], v185 offset:35840
	ds_read_b128 v[210:213], v185 offset:36864
	ds_read_b128 v[214:217], v185 offset:37888
	ds_read_b128 v[218:221], v185 offset:38912
	ds_read_b128 v[222:225], v185 offset:39936
	global_load_lds_dwordx4 v[242:243], off
	v_lshl_add_u64 v[242:243], s[48:49], 0, v[148:149]
	s_mov_b32 m0, s50
	s_nop 0
	global_load_lds_dwordx4 v[242:243], off
	s_waitcnt vmcnt(8)
	s_waitcnt lgkmcnt(0)
	s_setprio 1
	s_barrier
	v_mfma_f32_16x16x32_bf16 v[142:145], v[90:93], v[194:197], v[142:145]
	v_mfma_f32_16x16x32_bf16 v[138:141], v[98:101], v[194:197], v[138:141]
	v_mfma_f32_16x16x32_bf16 v[122:125], v[98:101], v[202:205], v[122:125]
	v_mfma_f32_16x16x32_bf16 v[126:129], v[90:93], v[202:205], v[126:129]
	v_mfma_f32_16x16x32_bf16 v[110:113], v[90:93], v[210:213], v[110:113]
	v_mfma_f32_16x16x32_bf16 v[106:109], v[98:101], v[210:213], v[106:109]
	v_mfma_f32_16x16x32_bf16 v[74:77], v[98:101], v[218:221], v[74:77]
	v_mfma_f32_16x16x32_bf16 v[78:81], v[90:93], v[218:221], v[78:81]
	v_mfma_f32_16x16x32_bf16 v[142:145], v[94:97], v[198:201], v[142:145]
	v_mfma_f32_16x16x32_bf16 v[138:141], v[102:105], v[198:201], v[138:141]
	v_mfma_f32_16x16x32_bf16 v[122:125], v[102:105], v[206:209], v[122:125]
	v_mfma_f32_16x16x32_bf16 v[126:129], v[94:97], v[206:209], v[126:129]
	v_mfma_f32_16x16x32_bf16 v[110:113], v[94:97], v[214:217], v[110:113]
	v_mfma_f32_16x16x32_bf16 v[106:109], v[102:105], v[214:217], v[106:109]
	v_mfma_f32_16x16x32_bf16 v[74:77], v[102:105], v[222:225], v[74:77]
	v_mfma_f32_16x16x32_bf16 v[78:81], v[94:97], v[222:225], v[78:81]
	v_mfma_f32_16x16x32_bf16 v[134:137], v[158:161], v[194:197], v[134:137]
	v_mfma_f32_16x16x32_bf16 v[130:133], v[186:189], v[194:197], v[130:133]
	v_mfma_f32_16x16x32_bf16 v[114:117], v[186:189], v[202:205], v[114:117]
	v_mfma_f32_16x16x32_bf16 v[118:121], v[158:161], v[202:205], v[118:121]
	v_mfma_f32_16x16x32_bf16 v[86:89], v[158:161], v[210:213], v[86:89]
	v_mfma_f32_16x16x32_bf16 v[82:85], v[186:189], v[210:213], v[82:85]
	v_mfma_f32_16x16x32_bf16 v[66:69], v[186:189], v[218:221], v[66:69]
	v_mfma_f32_16x16x32_bf16 v[70:73], v[158:161], v[218:221], v[70:73]
	v_mfma_f32_16x16x32_bf16 v[134:137], v[176:179], v[198:201], v[134:137]
	v_mfma_f32_16x16x32_bf16 v[130:133], v[190:193], v[198:201], v[130:133]
	v_mfma_f32_16x16x32_bf16 v[114:117], v[190:193], v[206:209], v[114:117]
	v_mfma_f32_16x16x32_bf16 v[118:121], v[176:179], v[206:209], v[118:121]
	v_mfma_f32_16x16x32_bf16 v[86:89], v[176:179], v[214:217], v[86:89]
	v_mfma_f32_16x16x32_bf16 v[82:85], v[190:193], v[214:217], v[82:85]
	v_mfma_f32_16x16x32_bf16 v[66:69], v[190:193], v[222:225], v[66:69]
	v_mfma_f32_16x16x32_bf16 v[70:73], v[176:179], v[222:225], v[70:73]
	s_barrier
; #define PG8_STAGE(bufoff, gbase, voff) do { _Pragma("unroll") for (int _i = 0; _i < 2; ++_i) \
;         __builtin_amdgcn_global_load_lds((const unsigned*)((const char*)(gbase) + (voff)[_i]), (PG8_LAS unsigned*)(lds + (bufoff) + ldsw + _i * 8192), 16, 0, 0); } while (0)
; #define PG8_LDA(dst, b, h) do { _Pragma("unroll") for (int m = 0; m < 4; ++m) _Pragma("unroll") for (int k = 0; k < 2; ++k) dst[m][k] = *(const PG8_LAS bf16x8*)(lds + PG8_SA(b, h) + aoff + m * 2048 + k * 1024); } while (0)
; #define PG8_MMA(ai, bj, At, Bt) do { __builtin_amdgcn_s_setprio(1); _Pragma("unroll") for (int m = 0; m < 4; ++m) _Pragma("unroll") for (int n = 0; n < 2; ++n) _Pragma("unroll") for (int k = 0; k < 2; ++k) \
;         acc[ai][bj][m][n] = __builtin_amdgcn_mfma_f32_16x16x32_bf16(Bt[n][k], At[m][k], acc[ai][bj][m][n], 0, 0, 0); __builtin_amdgcn_s_setprio(0); } while (0)
; #define PG8_WAIT_V(n) asm volatile("s_waitcnt vmcnt(" #n ")" ::: "memory")
; #define PG8_WAIT_L(n) asm volatile("s_waitcnt lgkmcnt(" #n ")" ::: "memory")
; #define PG8_BAR __builtin_amdgcn_s_barrier()
; #define PG8_SCHED __builtin_amdgcn_sched_barrier(0)
; template <class Epi, class Sched, bool ALIGN_EPI = false, bool SP2 = false>
; __device__ __forceinline__ void gemm_phase(PG8_LAS unsigned char* lds, const Gemm g, const Sched& S, const Epi& E) {
;     ...
;             PG8_LDA(At, 1, 1); PG8_STAGE(PG8_SB(1, 0), b3, voffB); PG8_STAGE(PG8_SB(1, 1), b3 + hstep, voffB); PG8_STAGE(PG8_SA(1, 0), a3, voffA);
;             PG8_WAIT_V(8); PG8_WAIT_L(0); PG8_BAR; PG8_MMA(1, 0, At, B0); PG8_MMA(1, 1, At, B1); PG8_BAR; PG8_SCHED;
;     ...
;         if constexpr (ALIGN_EPI) { if (wr == 0) PG8_BAR; }
	s_setprio 0
	s_add_i32 s10, s10, s6
	v_lshl_add_u64 v[180:181], v[180:181], 0, s[28:29]
	s_mov_b32 m0, s10
	ds_read_b128 v[194:197], v185 offset:49152
	ds_read_b128 v[198:201], v185 offset:50176
	ds_read_b128 v[202:205], v185 offset:51200
	ds_read_b128 v[206:209], v185 offset:52224
	ds_read_b128 v[210:213], v185 offset:53248
	ds_read_b128 v[214:217], v185 offset:54272
	ds_read_b128 v[218:221], v185 offset:55296
	ds_read_b128 v[222:225], v185 offset:56320
	global_load_lds_dwordx4 v[180:181], off
	s_add_i32 m0, s10, 0x2000
	s_add_u32 s46, s46, 0x40080
	v_lshl_add_u64 v[180:181], v[226:227], 0, s[28:29]
	s_addc_u32 s47, s47, 0
	s_add_i32 s10, s11, s6
	global_load_lds_dwordx4 v[180:181], off
	v_lshl_add_u64 v[180:181], s[46:47], 0, v[0:1]
	s_mov_b32 m0, s10
	s_nop 0
	global_load_lds_dwordx4 v[180:181], off
	v_lshl_add_u64 v[180:181], s[46:47], 0, v[146:147]
	s_add_i32 m0, s10, 0x2000
	s_nop 0
	global_load_lds_dwordx4 v[180:181], off
	v_lshl_add_u64 v[180:181], v[238:239], 0, s[28:29]
	s_mov_b32 m0, s52
	s_nop 0
	global_load_lds_dwordx4 v[180:181], off
	v_lshl_add_u64 v[180:181], v[240:241], 0, s[28:29]
	s_mov_b32 m0, s53
	s_nop 0
	global_load_lds_dwordx4 v[180:181], off
	s_waitcnt vmcnt(8)
	s_waitcnt lgkmcnt(0)
	s_setprio 1
	s_barrier
	v_mfma_f32_16x16x32_bf16 v[62:65], v[90:93], v[194:197], v[62:65]
	v_mfma_f32_16x16x32_bf16 v[58:61], v[98:101], v[194:197], v[58:61]
	v_mfma_f32_16x16x32_bf16 v[42:45], v[98:101], v[202:205], v[42:45]
	v_mfma_f32_16x16x32_bf16 v[46:49], v[90:93], v[202:205], v[46:49]
	v_mfma_f32_16x16x32_bf16 v[30:33], v[90:93], v[210:213], v[30:33]
	v_mfma_f32_16x16x32_bf16 v[26:29], v[98:101], v[210:213], v[26:29]
	v_mfma_f32_16x16x32_bf16 v[10:13], v[98:101], v[218:221], v[10:13]
	v_mfma_f32_16x16x32_bf16 v[14:17], v[90:93], v[218:221], v[14:17]
	v_mfma_f32_16x16x32_bf16 v[62:65], v[94:97], v[198:201], v[62:65]
	v_mfma_f32_16x16x32_bf16 v[58:61], v[102:105], v[198:201], v[58:61]
	v_mfma_f32_16x16x32_bf16 v[42:45], v[102:105], v[206:209], v[42:45]
	v_mfma_f32_16x16x32_bf16 v[46:49], v[94:97], v[206:209], v[46:49]
	v_mfma_f32_16x16x32_bf16 v[30:33], v[94:97], v[214:217], v[30:33]
	v_mfma_f32_16x16x32_bf16 v[26:29], v[102:105], v[214:217], v[26:29]
	v_mfma_f32_16x16x32_bf16 v[10:13], v[102:105], v[222:225], v[10:13]
	v_mfma_f32_16x16x32_bf16 v[14:17], v[94:97], v[222:225], v[14:17]
	v_mfma_f32_16x16x32_bf16 v[54:57], v[158:161], v[194:197], v[54:57]
	v_mfma_f32_16x16x32_bf16 v[50:53], v[186:189], v[194:197], v[50:53]
	v_mfma_f32_16x16x32_bf16 v[34:37], v[186:189], v[202:205], v[34:37]
	v_mfma_f32_16x16x32_bf16 v[38:41], v[158:161], v[202:205], v[38:41]
	v_mfma_f32_16x16x32_bf16 v[22:25], v[158:161], v[210:213], v[22:25]
	v_mfma_f32_16x16x32_bf16 v[18:21], v[186:189], v[210:213], v[18:21]
	v_mfma_f32_16x16x32_bf16 v[2:5], v[186:189], v[218:221], v[2:5]
	v_mfma_f32_16x16x32_bf16 v[6:9], v[158:161], v[218:221], v[6:9]
	v_mfma_f32_16x16x32_bf16 v[54:57], v[176:179], v[198:201], v[54:57]
	v_mfma_f32_16x16x32_bf16 v[50:53], v[190:193], v[198:201], v[50:53]
	v_mfma_f32_16x16x32_bf16 v[34:37], v[190:193], v[206:209], v[34:37]
	v_mfma_f32_16x16x32_bf16 v[38:41], v[176:179], v[206:209], v[38:41]
	v_mfma_f32_16x16x32_bf16 v[22:25], v[176:179], v[214:217], v[22:25]
	v_mfma_f32_16x16x32_bf16 v[18:21], v[190:193], v[214:217], v[18:21]
	v_mfma_f32_16x16x32_bf16 v[2:5], v[190:193], v[222:225], v[2:5]
	v_mfma_f32_16x16x32_bf16 v[6:9], v[176:179], v[222:225], v[6:9]
	s_barrier
	s_setprio 0
	s_add_i32 s59, s59, 2
	s_add_u32 s57, s57, 0x100
	s_addc_u32 s58, s58, 0
	s_add_u32 s44, s44, 0x100
	s_addc_u32 s45, s45, 0
	s_cmp_gt_u32 s59, 13
	s_cbranch_scc0 .LBB0_162
	s_and_b64 vcc, exec, s[22:23]
	s_cbranch_vccz .LBB0_165
	s_barrier

; #define PG8_STAGE(bufoff, gbase, voff) do { _Pragma("unroll") for (int _i = 0; _i < 2; ++_i) \
;         __builtin_amdgcn_global_load_lds((const unsigned*)((const char*)(gbase) + (voff)[_i]), (PG8_LAS unsigned*)(lds + (bufoff) + ldsw + _i * 8192), 16, 0, 0); } while (0)
; #define PG8_LDA(dst, b, h) do { _Pragma("unroll") for (int m = 0; m < 4; ++m) _Pragma("unroll") for (int k = 0; k < 2; ++k) dst[m][k] = *(const PG8_LAS bf16x8*)(lds + PG8_SA(b, h) + aoff + m * 2048 + k * 1024); } while (0)
; #define PG8_LDB(dst, b, h) do { _Pragma("unroll") for (int n = 0; n < 2; ++n) _Pragma("unroll") for (int k = 0; k < 2; ++k) dst[n][k] = *(const PG8_LAS bf16x8*)(lds + PG8_SB(b, h) + boff + n * 2048 + k * 1024); } while (0)
; #define PG8_MMA(ai, bj, At, Bt) do { __builtin_amdgcn_s_setprio(1); _Pragma("unroll") for (int m = 0; m < 4; ++m) _Pragma("unroll") for (int n = 0; n < 2; ++n) _Pragma("unroll") for (int k = 0; k < 2; ++k) \
;         acc[ai][bj][m][n] = __builtin_amdgcn_mfma_f32_16x16x32_bf16(Bt[n][k], At[m][k], acc[ai][bj][m][n], 0, 0, 0); __builtin_amdgcn_s_setprio(0); } while (0)
; #define PG8_WAIT_V(n) asm volatile("s_waitcnt vmcnt(" #n ")" ::: "memory")
; #define PG8_BAR __builtin_amdgcn_s_barrier()
; template <class Epi, class Sched, bool ALIGN_EPI = false, bool SP2 = false>
; __device__ __forceinline__ void gemm_phase(PG8_LAS unsigned char* lds, const Gemm g, const Sched& S, const Epi& E) {
;     ...
;         for (int t = 0; t < nt; t += 2) {
;             const bool last = (t == nt - 2);
;             const char* a1 = cA + (size_t)(t + 1) * kstep;
;             const char* a2 = last ? nA : cA + (size_t)(t + 2) * kstep; const char* b2 = last ? nB : cB + (size_t)(t + 2) * kstep;
;             const char* a3 = a2 + kstep; const char* b3 = b2 + kstep;
;             if (last && has_next) S.a_ready(nxt);
;             if constexpr (SP2) {
;             PG8_LDB(B0, 0, 0); PG8_LDB(B1, 0, 1); PG8_SCHED; PG8_LDA(At, 0, 0); PG8_STAGE(PG8_SA(1, 1), a1 + hstep, voffA);
;             PG8_WAIT_V(8); PG8_WAIT_L(0); PG8_BAR; PG8_MMA(0, 0, At, B0); PG8_MMA(0, 1, At, B1); PG8_BAR; PG8_SCHED;
;             PG8_LDA(At, 0, 1); PG8_STAGE(PG8_SB(0, 0), b2, voffB); PG8_STAGE(PG8_SB(0, 1), b2 + hstep, voffB); PG8_STAGE(PG8_SA(0, 0), a2, voffA);
;             PG8_WAIT_V(8); PG8_WAIT_L(0); PG8_BAR; PG8_MMA(1, 0, At, B0); PG8_MMA(1, 1, At, B1); PG8_BAR; PG8_SCHED;
.LBB0_243:
	s_add_u32 s10, s46, 0xfffc0080
	s_addc_u32 s11, s47, -1
	s_add_i32 s58, 16, 0x10000
	s_cmp_eq_u32 s57, 12
	s_cselect_b32 s51, s34, s11
	s_cselect_b32 s50, s35, s10
	s_cselect_b32 s49, s27, s56
	s_cselect_b32 s48, s41, s55
	s_add_i32 s10, 16, 0x14000
	v_add_u32_e32 v156, s58, v141
	v_add_u32_e32 v160, s10, v141
	ds_read_b128 v[144:147], v156
	ds_read_b128 v[148:151], v156 offset:1024
	ds_read_b128 v[152:155], v156 offset:2048
	ds_read_b128 v[156:159], v156 offset:3072
	ds_read_b128 v[176:179], v160
	ds_read_b128 v[180:183], v160 offset:1024
	ds_read_b128 v[184:187], v160 offset:2048
	ds_read_b128 v[188:191], v160 offset:3072
	v_lshl_add_u64 v[160:161], s[46:47], 0, v[138:139]
	s_add_i32 m0, s4, 0xc000
	ds_read_b128 v[192:195], v143
	ds_read_b128 v[196:199], v143 offset:1024
	ds_read_b128 v[200:203], v143 offset:2048
	ds_read_b128 v[204:207], v143 offset:3072
	ds_read_b128 v[208:211], v143 offset:4096
	ds_read_b128 v[212:215], v143 offset:5120
	ds_read_b128 v[216:219], v143 offset:6144
	ds_read_b128 v[220:223], v143 offset:7168
	global_load_lds_dwordx4 v[160:161], off
	v_lshl_add_u64 v[160:161], s[46:47], 0, v[136:137]
	s_add_i32 m0, s4, 0xe000
	s_nop 0
	global_load_lds_dwordx4 v[160:161], off
	s_waitcnt vmcnt(8)
	s_waitcnt lgkmcnt(0)
	s_setprio 1
	s_barrier
	v_mfma_f32_16x16x32_bf16 v[126:129], v[144:147], v[192:195], v[126:129]
	v_mfma_f32_16x16x32_bf16 v[122:125], v[152:155], v[192:195], v[122:125]
	v_mfma_f32_16x16x32_bf16 v[114:117], v[152:155], v[200:203], v[114:117]
	v_mfma_f32_16x16x32_bf16 v[118:121], v[144:147], v[200:203], v[118:121]
	v_mfma_f32_16x16x32_bf16 v[102:105], v[144:147], v[208:211], v[102:105]
	v_mfma_f32_16x16x32_bf16 v[98:101], v[152:155], v[208:211], v[98:101]
	v_mfma_f32_16x16x32_bf16 v[82:85], v[152:155], v[216:219], v[82:85]
	v_mfma_f32_16x16x32_bf16 v[86:89], v[144:147], v[216:219], v[86:89]
	v_mfma_f32_16x16x32_bf16 v[126:129], v[148:151], v[196:199], v[126:129]
	v_mfma_f32_16x16x32_bf16 v[122:125], v[156:159], v[196:199], v[122:125]
	v_mfma_f32_16x16x32_bf16 v[114:117], v[156:159], v[204:207], v[114:117]
	v_mfma_f32_16x16x32_bf16 v[118:121], v[148:151], v[204:207], v[118:121]
	v_mfma_f32_16x16x32_bf16 v[102:105], v[148:151], v[212:215], v[102:105]
	v_mfma_f32_16x16x32_bf16 v[98:101], v[156:159], v[212:215], v[98:101]
	v_mfma_f32_16x16x32_bf16 v[82:85], v[156:159], v[220:223], v[82:85]
	v_mfma_f32_16x16x32_bf16 v[86:89], v[148:151], v[220:223], v[86:89]
	v_mfma_f32_16x16x32_bf16 v[110:113], v[176:179], v[192:195], v[110:113]
	v_mfma_f32_16x16x32_bf16 v[106:109], v[184:187], v[192:195], v[106:109]
	v_mfma_f32_16x16x32_bf16 v[90:93], v[184:187], v[200:203], v[90:93]
	v_mfma_f32_16x16x32_bf16 v[94:97], v[176:179], v[200:203], v[94:97]
	v_mfma_f32_16x16x32_bf16 v[78:81], v[176:179], v[208:211], v[78:81]
	v_mfma_f32_16x16x32_bf16 v[74:77], v[184:187], v[208:211], v[74:77]
	v_mfma_f32_16x16x32_bf16 v[66:69], v[184:187], v[216:219], v[66:69]
	v_mfma_f32_16x16x32_bf16 v[70:73], v[176:179], v[216:219], v[70:73]
	v_mfma_f32_16x16x32_bf16 v[110:113], v[180:183], v[196:199], v[110:113]
	v_mfma_f32_16x16x32_bf16 v[106:109], v[188:191], v[196:199], v[106:109]
	v_mfma_f32_16x16x32_bf16 v[90:93], v[188:191], v[204:207], v[90:93]
	v_mfma_f32_16x16x32_bf16 v[94:97], v[180:183], v[204:207], v[94:97]
	v_mfma_f32_16x16x32_bf16 v[78:81], v[180:183], v[212:215], v[78:81]
	v_mfma_f32_16x16x32_bf16 v[74:77], v[188:191], v[212:215], v[74:77]
	v_mfma_f32_16x16x32_bf16 v[66:69], v[188:191], v[220:223], v[66:69]
	v_mfma_f32_16x16x32_bf16 v[70:73], v[180:183], v[220:223], v[70:73]
	s_barrier
	s_setprio 0
	s_add_i32 s11, s58, s3
	v_lshl_add_u64 v[160:161], s[48:49], 0, v[0:1]
	s_mov_b32 m0, s11
	ds_read_b128 v[192:195], v143 offset:16384
	ds_read_b128 v[196:199], v143 offset:17408
	ds_read_b128 v[200:203], v143 offset:18432
	ds_read_b128 v[204:207], v143 offset:19456
	ds_read_b128 v[208:211], v143 offset:20480
	ds_read_b128 v[212:215], v143 offset:21504
	ds_read_b128 v[216:219], v143 offset:22528
	ds_read_b128 v[220:223], v143 offset:23552
	global_load_lds_dwordx4 v[160:161], off
	s_add_i32 m0, s11, 0x2000
	s_add_u32 s58, s48, 0x40000
	v_lshl_add_u64 v[224:225], s[48:49], 0, v[130:131]
	s_addc_u32 s59, s49, 0
	s_add_i32 s10, s10, s3
	global_load_lds_dwordx4 v[224:225], off
	v_lshl_add_u64 v[226:227], s[58:59], 0, v[0:1]
	s_mov_b32 m0, s10
	v_lshl_add_u64 v[238:239], s[50:51], 0, v[132:133]
	global_load_lds_dwordx4 v[226:227], off
	v_lshl_add_u64 v[226:227], s[58:59], 0, v[130:131]
	s_add_i32 m0, s10, 0x2000
	s_nop 0
	global_load_lds_dwordx4 v[226:227], off
	v_lshl_add_u64 v[226:227], s[50:51], 0, v[134:135]
	s_mov_b32 m0, s4
	s_nop 0
	global_load_lds_dwordx4 v[226:227], off
	s_mov_b32 m0, s5
	s_nop 0
	global_load_lds_dwordx4 v[238:239], off
	s_waitcnt vmcnt(8)
	s_waitcnt lgkmcnt(0)
	s_setprio 1
	s_barrier
; #define PG8_STAGE(bufoff, gbase, voff) do { _Pragma("unroll") for (int _i = 0; _i < 2; ++_i) \
;         __builtin_amdgcn_global_load_lds((const unsigned*)((const char*)(gbase) + (voff)[_i]), (PG8_LAS unsigned*)(lds + (bufoff) + ldsw + _i * 8192), 16, 0, 0); } while (0)
; #define PG8_LDA(dst, b, h) do { _Pragma("unroll") for (int m = 0; m < 4; ++m) _Pragma("unroll") for (int k = 0; k < 2; ++k) dst[m][k] = *(const PG8_LAS bf16x8*)(lds + PG8_SA(b, h) + aoff + m * 2048 + k * 1024); } while (0)
; #define PG8_LDB(dst, b, h) do { _Pragma("unroll") for (int n = 0; n < 2; ++n) _Pragma("unroll") for (int k = 0; k < 2; ++k) dst[n][k] = *(const PG8_LAS bf16x8*)(lds + PG8_SB(b, h) + boff + n * 2048 + k * 1024); } while (0)
; #define PG8_MMA(ai, bj, At, Bt) do { __builtin_amdgcn_s_setprio(1); _Pragma("unroll") for (int m = 0; m < 4; ++m) _Pragma("unroll") for (int n = 0; n < 2; ++n) _Pragma("unroll") for (int k = 0; k < 2; ++k) \
;         acc[ai][bj][m][n] = __builtin_amdgcn_mfma_f32_16x16x32_bf16(Bt[n][k], At[m][k], acc[ai][bj][m][n], 0, 0, 0); __builtin_amdgcn_s_setprio(0); } while (0)
; #define PG8_WAIT_V(n) asm volatile("s_waitcnt vmcnt(" #n ")" ::: "memory")
; #define PG8_WAIT_L(n) asm volatile("s_waitcnt lgkmcnt(" #n ")" ::: "memory")
; #define PG8_BAR __builtin_amdgcn_s_barrier()
; #define PG8_SCHED __builtin_amdgcn_sched_barrier(0)
; template <class Epi, class Sched, bool ALIGN_EPI = false, bool SP2 = false>
; __device__ __forceinline__ void gemm_phase(PG8_LAS unsigned char* lds, const Gemm g, const Sched& S, const Epi& E) {
;     ...
;             PG8_WAIT_V(8); PG8_WAIT_L(0); PG8_BAR; PG8_MMA(1, 0, At, B0); PG8_MMA(1, 1, At, B1); PG8_BAR; PG8_SCHED;
;             PG8_LDB(B0, 1, 0); PG8_LDB(B1, 1, 1); PG8_SCHED; PG8_LDA(At, 1, 0); PG8_STAGE(PG8_SA(0, 1), a2 + hstep, voffA);
;             PG8_WAIT_V(8); PG8_WAIT_L(0); PG8_BAR; PG8_MMA(0, 0, At, B0); PG8_MMA(0, 1, At, B1); PG8_BAR; PG8_SCHED;
	v_mfma_f32_16x16x32_bf16 v[62:65], v[144:147], v[192:195], v[62:65]
	v_mfma_f32_16x16x32_bf16 v[58:61], v[152:155], v[192:195], v[58:61]
	v_mfma_f32_16x16x32_bf16 v[50:53], v[152:155], v[200:203], v[50:53]
	v_mfma_f32_16x16x32_bf16 v[54:57], v[144:147], v[200:203], v[54:57]
	v_mfma_f32_16x16x32_bf16 v[38:41], v[144:147], v[208:211], v[38:41]
	v_mfma_f32_16x16x32_bf16 v[34:37], v[152:155], v[208:211], v[34:37]
	v_mfma_f32_16x16x32_bf16 v[18:21], v[152:155], v[216:219], v[18:21]
	v_mfma_f32_16x16x32_bf16 v[22:25], v[144:147], v[216:219], v[22:25]
	v_mfma_f32_16x16x32_bf16 v[62:65], v[148:151], v[196:199], v[62:65]
	v_mfma_f32_16x16x32_bf16 v[58:61], v[156:159], v[196:199], v[58:61]
	v_mfma_f32_16x16x32_bf16 v[50:53], v[156:159], v[204:207], v[50:53]
	v_mfma_f32_16x16x32_bf16 v[54:57], v[148:151], v[204:207], v[54:57]
	v_mfma_f32_16x16x32_bf16 v[38:41], v[148:151], v[212:215], v[38:41]
	v_mfma_f32_16x16x32_bf16 v[34:37], v[156:159], v[212:215], v[34:37]
	v_mfma_f32_16x16x32_bf16 v[18:21], v[156:159], v[220:223], v[18:21]
	v_mfma_f32_16x16x32_bf16 v[22:25], v[148:151], v[220:223], v[22:25]
	v_mfma_f32_16x16x32_bf16 v[46:49], v[176:179], v[192:195], v[46:49]
	v_mfma_f32_16x16x32_bf16 v[42:45], v[184:187], v[192:195], v[42:45]
	v_mfma_f32_16x16x32_bf16 v[26:29], v[184:187], v[200:203], v[26:29]
	v_mfma_f32_16x16x32_bf16 v[30:33], v[176:179], v[200:203], v[30:33]
	v_mfma_f32_16x16x32_bf16 v[14:17], v[176:179], v[208:211], v[14:17]
	v_mfma_f32_16x16x32_bf16 v[10:13], v[184:187], v[208:211], v[10:13]
	v_mfma_f32_16x16x32_bf16 v[2:5], v[184:187], v[216:219], v[2:5]
	v_mfma_f32_16x16x32_bf16 v[6:9], v[176:179], v[216:219], v[6:9]
	v_mfma_f32_16x16x32_bf16 v[46:49], v[180:183], v[196:199], v[46:49]
	v_mfma_f32_16x16x32_bf16 v[42:45], v[188:191], v[196:199], v[42:45]
	v_mfma_f32_16x16x32_bf16 v[26:29], v[188:191], v[204:207], v[26:29]
	v_mfma_f32_16x16x32_bf16 v[30:33], v[180:183], v[204:207], v[30:33]
	v_mfma_f32_16x16x32_bf16 v[14:17], v[180:183], v[212:215], v[14:17]
	v_mfma_f32_16x16x32_bf16 v[10:13], v[188:191], v[212:215], v[10:13]
	v_mfma_f32_16x16x32_bf16 v[2:5], v[188:191], v[220:223], v[2:5]
	v_mfma_f32_16x16x32_bf16 v[6:9], v[180:183], v[220:223], v[6:9]
	s_barrier
	s_setprio 0
	s_add_i32 s10, 16, 0x18000
	s_add_i32 s11, 16, 0x1c000
	v_add_u32_e32 v156, s10, v141
	v_add_u32_e32 v188, s11, v141
	ds_read_b128 v[144:147], v156
	ds_read_b128 v[148:151], v156 offset:1024
	ds_read_b128 v[152:155], v156 offset:2048
	ds_read_b128 v[156:159], v156 offset:3072
	ds_read_b128 v[176:179], v188
	ds_read_b128 v[180:183], v188 offset:1024
	ds_read_b128 v[184:187], v188 offset:2048
	ds_read_b128 v[188:191], v188 offset:3072
	s_add_u32 s50, s50, 0x40000
	s_addc_u32 s51, s51, 0
	s_mov_b32 m0, s6
	v_lshl_add_u64 v[240:241], s[50:51], 0, v[134:135]
	ds_read_b128 v[192:195], v143 offset:32768
	ds_read_b128 v[196:199], v143 offset:33792
	ds_read_b128 v[200:203], v143 offset:34816
	ds_read_b128 v[204:207], v143 offset:35840
	ds_read_b128 v[208:211], v143 offset:36864
	ds_read_b128 v[212:215], v143 offset:37888
	ds_read_b128 v[216:219], v143 offset:38912
	ds_read_b128 v[220:223], v143 offset:39936
	global_load_lds_dwordx4 v[240:241], off
	v_lshl_add_u64 v[240:241], s[50:51], 0, v[132:133]
	s_mov_b32 m0, s7
	s_nop 0
	global_load_lds_dwordx4 v[240:241], off
	s_waitcnt vmcnt(8)
	s_waitcnt lgkmcnt(0)
	s_setprio 1
	s_barrier
	v_mfma_f32_16x16x32_bf16 v[126:129], v[144:147], v[192:195], v[126:129]
	v_mfma_f32_16x16x32_bf16 v[122:125], v[152:155], v[192:195], v[122:125]
	v_mfma_f32_16x16x32_bf16 v[114:117], v[152:155], v[200:203], v[114:117]
	v_mfma_f32_16x16x32_bf16 v[118:121], v[144:147], v[200:203], v[118:121]
	v_mfma_f32_16x16x32_bf16 v[102:105], v[144:147], v[208:211], v[102:105]
	v_mfma_f32_16x16x32_bf16 v[98:101], v[152:155], v[208:211], v[98:101]
	v_mfma_f32_16x16x32_bf16 v[82:85], v[152:155], v[216:219], v[82:85]
	v_mfma_f32_16x16x32_bf16 v[86:89], v[144:147], v[216:219], v[86:89]
	v_mfma_f32_16x16x32_bf16 v[126:129], v[148:151], v[196:199], v[126:129]
	v_mfma_f32_16x16x32_bf16 v[122:125], v[156:159], v[196:199], v[122:125]
	v_mfma_f32_16x16x32_bf16 v[114:117], v[156:159], v[204:207], v[114:117]
	v_mfma_f32_16x16x32_bf16 v[118:121], v[148:151], v[204:207], v[118:121]
	v_mfma_f32_16x16x32_bf16 v[102:105], v[148:151], v[212:215], v[102:105]
	v_mfma_f32_16x16x32_bf16 v[98:101], v[156:159], v[212:215], v[98:101]
	v_mfma_f32_16x16x32_bf16 v[82:85], v[156:159], v[220:223], v[82:85]
	v_mfma_f32_16x16x32_bf16 v[86:89], v[148:151], v[220:223], v[86:89]
	v_mfma_f32_16x16x32_bf16 v[110:113], v[176:179], v[192:195], v[110:113]
	v_mfma_f32_16x16x32_bf16 v[106:109], v[184:187], v[192:195], v[106:109]
	v_mfma_f32_16x16x32_bf16 v[90:93], v[184:187], v[200:203], v[90:93]
	v_mfma_f32_16x16x32_bf16 v[94:97], v[176:179], v[200:203], v[94:97]
	v_mfma_f32_16x16x32_bf16 v[78:81], v[176:179], v[208:211], v[78:81]
	v_mfma_f32_16x16x32_bf16 v[74:77], v[184:187], v[208:211], v[74:77]
	v_mfma_f32_16x16x32_bf16 v[66:69], v[184:187], v[216:219], v[66:69]
	v_mfma_f32_16x16x32_bf16 v[70:73], v[176:179], v[216:219], v[70:73]
	v_mfma_f32_16x16x32_bf16 v[110:113], v[180:183], v[196:199], v[110:113]
	v_mfma_f32_16x16x32_bf16 v[106:109], v[188:191], v[196:199], v[106:109]
	v_mfma_f32_16x16x32_bf16 v[90:93], v[188:191], v[204:207], v[90:93]
	v_mfma_f32_16x16x32_bf16 v[94:97], v[180:183], v[204:207], v[94:97]
	v_mfma_f32_16x16x32_bf16 v[78:81], v[180:183], v[212:215], v[78:81]
	v_mfma_f32_16x16x32_bf16 v[74:77], v[188:191], v[212:215], v[74:77]
	v_mfma_f32_16x16x32_bf16 v[66:69], v[188:191], v[220:223], v[66:69]
	v_mfma_f32_16x16x32_bf16 v[70:73], v[180:183], v[220:223], v[70:73]
	s_barrier
; #define PG8_STAGE(bufoff, gbase, voff) do { _Pragma("unroll") for (int _i = 0; _i < 2; ++_i) \
;         __builtin_amdgcn_global_load_lds((const unsigned*)((const char*)(gbase) + (voff)[_i]), (PG8_LAS unsigned*)(lds + (bufoff) + ldsw + _i * 8192), 16, 0, 0); } while (0)
; #define PG8_LDA(dst, b, h) do { _Pragma("unroll") for (int m = 0; m < 4; ++m) _Pragma("unroll") for (int k = 0; k < 2; ++k) dst[m][k] = *(const PG8_LAS bf16x8*)(lds + PG8_SA(b, h) + aoff + m * 2048 + k * 1024); } while (0)
; #define PG8_MMA(ai, bj, At, Bt) do { __builtin_amdgcn_s_setprio(1); _Pragma("unroll") for (int m = 0; m < 4; ++m) _Pragma("unroll") for (int n = 0; n < 2; ++n) _Pragma("unroll") for (int k = 0; k < 2; ++k) \
;         acc[ai][bj][m][n] = __builtin_amdgcn_mfma_f32_16x16x32_bf16(Bt[n][k], At[m][k], acc[ai][bj][m][n], 0, 0, 0); __builtin_amdgcn_s_setprio(0); } while (0)
; #define PG8_WAIT_V(n) asm volatile("s_waitcnt vmcnt(" #n ")" ::: "memory")
; #define PG8_WAIT_L(n) asm volatile("s_waitcnt lgkmcnt(" #n ")" ::: "memory")
; #define PG8_BAR __builtin_amdgcn_s_barrier()
; #define PG8_SCHED __builtin_amdgcn_sched_barrier(0)
; template <class Epi, class Sched, bool ALIGN_EPI = false, bool SP2 = false>
; __device__ __forceinline__ void gemm_phase(PG8_LAS unsigned char* lds, const Gemm g, const Sched& S, const Epi& E) {
;     ...
;             PG8_LDA(At, 1, 1); PG8_STAGE(PG8_SB(1, 0), b3, voffB); PG8_STAGE(PG8_SB(1, 1), b3 + hstep, voffB); PG8_STAGE(PG8_SA(1, 0), a3, voffA);
;             PG8_WAIT_V(8); PG8_WAIT_L(0); PG8_BAR; PG8_MMA(1, 0, At, B0); PG8_MMA(1, 1, At, B1); PG8_BAR; PG8_SCHED;
;     ...
;         if constexpr (ALIGN_EPI) { if (wr == 0) PG8_BAR; }
	s_setprio 0
	s_add_i32 s10, s10, s3
	v_lshl_add_u64 v[160:161], v[160:161], 0, s[28:29]
	s_mov_b32 m0, s10
	ds_read_b128 v[192:195], v143 offset:49152
	ds_read_b128 v[196:199], v143 offset:50176
	ds_read_b128 v[200:203], v143 offset:51200
	ds_read_b128 v[204:207], v143 offset:52224
	ds_read_b128 v[208:211], v143 offset:53248
	ds_read_b128 v[212:215], v143 offset:54272
	ds_read_b128 v[216:219], v143 offset:55296
	ds_read_b128 v[220:223], v143 offset:56320
	global_load_lds_dwordx4 v[160:161], off
	s_add_i32 m0, s10, 0x2000
	s_add_u32 s48, s48, 0x40080
	v_lshl_add_u64 v[160:161], v[224:225], 0, s[28:29]
	s_addc_u32 s49, s49, 0
	s_add_i32 s10, s11, s3
	global_load_lds_dwordx4 v[160:161], off
	v_lshl_add_u64 v[160:161], s[48:49], 0, v[0:1]
	s_mov_b32 m0, s10
	s_nop 0
	global_load_lds_dwordx4 v[160:161], off
	v_lshl_add_u64 v[160:161], s[48:49], 0, v[130:131]
	s_add_i32 m0, s10, 0x2000
	s_nop 0
	global_load_lds_dwordx4 v[160:161], off
	v_lshl_add_u64 v[160:161], v[226:227], 0, s[28:29]
	s_mov_b32 m0, s8
	s_nop 0
	global_load_lds_dwordx4 v[160:161], off
	v_lshl_add_u64 v[160:161], v[238:239], 0, s[28:29]
	s_mov_b32 m0, s9
	s_nop 0
	global_load_lds_dwordx4 v[160:161], off
	s_waitcnt vmcnt(8)
	s_waitcnt lgkmcnt(0)
	s_setprio 1
	s_barrier
	v_mfma_f32_16x16x32_bf16 v[62:65], v[144:147], v[192:195], v[62:65]
	v_mfma_f32_16x16x32_bf16 v[58:61], v[152:155], v[192:195], v[58:61]
	v_mfma_f32_16x16x32_bf16 v[50:53], v[152:155], v[200:203], v[50:53]
	v_mfma_f32_16x16x32_bf16 v[54:57], v[144:147], v[200:203], v[54:57]
	v_mfma_f32_16x16x32_bf16 v[38:41], v[144:147], v[208:211], v[38:41]
	v_mfma_f32_16x16x32_bf16 v[34:37], v[152:155], v[208:211], v[34:37]
	v_mfma_f32_16x16x32_bf16 v[18:21], v[152:155], v[216:219], v[18:21]
	v_mfma_f32_16x16x32_bf16 v[22:25], v[144:147], v[216:219], v[22:25]
	v_mfma_f32_16x16x32_bf16 v[62:65], v[148:151], v[196:199], v[62:65]
	v_mfma_f32_16x16x32_bf16 v[58:61], v[156:159], v[196:199], v[58:61]
	v_mfma_f32_16x16x32_bf16 v[50:53], v[156:159], v[204:207], v[50:53]
	v_mfma_f32_16x16x32_bf16 v[54:57], v[148:151], v[204:207], v[54:57]
	v_mfma_f32_16x16x32_bf16 v[38:41], v[148:151], v[212:215], v[38:41]
	v_mfma_f32_16x16x32_bf16 v[34:37], v[156:159], v[212:215], v[34:37]
	v_mfma_f32_16x16x32_bf16 v[18:21], v[156:159], v[220:223], v[18:21]
	v_mfma_f32_16x16x32_bf16 v[22:25], v[148:151], v[220:223], v[22:25]
	v_mfma_f32_16x16x32_bf16 v[46:49], v[176:179], v[192:195], v[46:49]
	v_mfma_f32_16x16x32_bf16 v[42:45], v[184:187], v[192:195], v[42:45]
	v_mfma_f32_16x16x32_bf16 v[26:29], v[184:187], v[200:203], v[26:29]
	v_mfma_f32_16x16x32_bf16 v[30:33], v[176:179], v[200:203], v[30:33]
	v_mfma_f32_16x16x32_bf16 v[14:17], v[176:179], v[208:211], v[14:17]
	v_mfma_f32_16x16x32_bf16 v[10:13], v[184:187], v[208:211], v[10:13]
	v_mfma_f32_16x16x32_bf16 v[2:5], v[184:187], v[216:219], v[2:5]
	v_mfma_f32_16x16x32_bf16 v[6:9], v[176:179], v[216:219], v[6:9]
	v_mfma_f32_16x16x32_bf16 v[46:49], v[180:183], v[196:199], v[46:49]
	v_mfma_f32_16x16x32_bf16 v[42:45], v[188:191], v[196:199], v[42:45]
	v_mfma_f32_16x16x32_bf16 v[26:29], v[188:191], v[204:207], v[26:29]
	v_mfma_f32_16x16x32_bf16 v[30:33], v[180:183], v[204:207], v[30:33]
	v_mfma_f32_16x16x32_bf16 v[14:17], v[180:183], v[212:215], v[14:17]
	v_mfma_f32_16x16x32_bf16 v[10:13], v[188:191], v[212:215], v[10:13]
	v_mfma_f32_16x16x32_bf16 v[2:5], v[188:191], v[220:223], v[2:5]
	v_mfma_f32_16x16x32_bf16 v[6:9], v[180:183], v[220:223], v[6:9]
	s_barrier
	s_setprio 0
	s_add_i32 s57, s57, 2
	s_add_u32 s55, s55, 0x100
	s_addc_u32 s56, s56, 0
	s_add_u32 s46, s46, 0x100
	s_addc_u32 s47, s47, 0
	s_cmp_gt_u32 s57, 13
	s_cbranch_scc0 .LBB0_243
	s_and_b64 vcc, exec, s[24:25]
	s_cbranch_vccz .LBB0_246
	s_barrier

; #define PG8_STAGE(bufoff, gbase, voff) do { _Pragma("unroll") for (int _i = 0; _i < 2; ++_i) \
;         __builtin_amdgcn_global_load_lds((const unsigned*)((const char*)(gbase) + (voff)[_i]), (PG8_LAS unsigned*)(lds + (bufoff) + ldsw + _i * 8192), 16, 0, 0); } while (0)
; #define PG8_LDA(dst, b, h) do { _Pragma("unroll") for (int m = 0; m < 4; ++m) _Pragma("unroll") for (int k = 0; k < 2; ++k) dst[m][k] = *(const PG8_LAS bf16x8*)(lds + PG8_SA(b, h) + aoff + m * 2048 + k * 1024); } while (0)
; #define PG8_LDB(dst, b, h) do { _Pragma("unroll") for (int n = 0; n < 2; ++n) _Pragma("unroll") for (int k = 0; k < 2; ++k) dst[n][k] = *(const PG8_LAS bf16x8*)(lds + PG8_SB(b, h) + boff + n * 2048 + k * 1024); } while (0)
; #define PG8_MMA(ai, bj, At, Bt) do { __builtin_amdgcn_s_setprio(1); _Pragma("unroll") for (int m = 0; m < 4; ++m) _Pragma("unroll") for (int n = 0; n < 2; ++n) _Pragma("unroll") for (int k = 0; k < 2; ++k) \
;         acc[ai][bj][m][n] = __builtin_amdgcn_mfma_f32_16x16x32_bf16(Bt[n][k], At[m][k], acc[ai][bj][m][n], 0, 0, 0); __builtin_amdgcn_s_setprio(0); } while (0)
; #define PG8_WAIT_V(n) asm volatile("s_waitcnt vmcnt(" #n ")" ::: "memory")
; #define PG8_BAR __builtin_amdgcn_s_barrier()
; template <class Epi, class Sched, bool ALIGN_EPI = false, bool SP2 = false>
; __device__ __forceinline__ void gemm_phase(PG8_LAS unsigned char* lds, const Gemm g, const Sched& S, const Epi& E) {
;     ...
;         for (int t = 0; t < nt; t += 2) {
;             const bool last = (t == nt - 2);
;             const char* a1 = cA + (size_t)(t + 1) * kstep;
;             const char* a2 = last ? nA : cA + (size_t)(t + 2) * kstep; const char* b2 = last ? nB : cB + (size_t)(t + 2) * kstep;
;             const char* a3 = a2 + kstep; const char* b3 = b2 + kstep;
;             if (last && has_next) S.a_ready(nxt);
;             if constexpr (SP2) {
;             PG8_LDB(B0, 0, 0); PG8_LDB(B1, 0, 1); PG8_SCHED; PG8_LDA(At, 0, 0); PG8_STAGE(PG8_SA(1, 1), a1 + hstep, voffA);
;             PG8_WAIT_V(8); PG8_WAIT_L(0); PG8_BAR; PG8_MMA(0, 0, At, B0); PG8_MMA(0, 1, At, B1); PG8_BAR; PG8_SCHED;
;             PG8_LDA(At, 0, 1); PG8_STAGE(PG8_SB(0, 0), b2, voffB); PG8_STAGE(PG8_SB(0, 1), b2 + hstep, voffB); PG8_STAGE(PG8_SA(0, 0), a2, voffA);
;             PG8_WAIT_V(8); PG8_WAIT_L(0); PG8_BAR; PG8_MMA(1, 0, At, B0); PG8_MMA(1, 1, At, B1); PG8_BAR; PG8_SCHED;
.LBB0_915:
	s_add_u32 s10, s42, 0xfffc0080
	s_addc_u32 s11, s43, -1
	s_add_i32 s35, 16, 0x10000
	s_cmp_eq_u32 s34, 12
	s_cselect_b32 s73, s0, s11
	s_cselect_b32 s72, s8, s10
	s_cselect_b32 s69, s9, s27
	s_cselect_b32 s68, s23, s25
	s_add_i32 s45, 16, 0x14000
	v_add_u32_e32 v78, s35, v197
	v_add_u32_e32 v94, s45, v197
	ds_read_b128 v[58:61], v78
	ds_read_b128 v[62:65], v78 offset:1024
	ds_read_b128 v[74:77], v78 offset:2048
	ds_read_b128 v[78:81], v78 offset:3072
	ds_read_b128 v[82:85], v94
	ds_read_b128 v[86:89], v94 offset:1024
	ds_read_b128 v[90:93], v94 offset:2048
	ds_read_b128 v[94:97], v94 offset:3072
	v_lshl_add_u64 v[194:195], s[42:43], 0, v[184:185]
	s_add_i32 m0, s77, 0xc000
	ds_read_b128 v[186:189], v199
	ds_read_b128 v[190:193], v199 offset:1024
	ds_read_b128 v[200:203], v199 offset:2048
	ds_read_b128 v[204:207], v199 offset:3072
	ds_read_b128 v[208:211], v199 offset:4096
	ds_read_b128 v[212:215], v199 offset:5120
	ds_read_b128 v[216:219], v199 offset:6144
	ds_read_b128 v[220:223], v199 offset:7168
	global_load_lds_dwordx4 v[194:195], off
	v_lshl_add_u64 v[194:195], s[42:43], 0, v[182:183]
	s_add_i32 m0, s77, 0xe000
	s_nop 0
	global_load_lds_dwordx4 v[194:195], off
	s_waitcnt vmcnt(8)
	s_waitcnt lgkmcnt(0)
	s_setprio 1
	s_barrier
	v_mfma_f32_16x16x32_bf16 v[158:161], v[58:61], v[186:189], v[158:161]
	v_mfma_f32_16x16x32_bf16 v[154:157], v[74:77], v[186:189], v[154:157]
	v_mfma_f32_16x16x32_bf16 v[138:141], v[74:77], v[200:203], v[138:141]
	v_mfma_f32_16x16x32_bf16 v[142:145], v[58:61], v[200:203], v[142:145]
	v_mfma_f32_16x16x32_bf16 v[126:129], v[58:61], v[208:211], v[126:129]
	v_mfma_f32_16x16x32_bf16 v[122:125], v[74:77], v[208:211], v[122:125]
	v_mfma_f32_16x16x32_bf16 v[106:109], v[74:77], v[216:219], v[106:109]
	v_mfma_f32_16x16x32_bf16 v[110:113], v[58:61], v[216:219], v[110:113]
	v_mfma_f32_16x16x32_bf16 v[158:161], v[62:65], v[190:193], v[158:161]
	v_mfma_f32_16x16x32_bf16 v[154:157], v[78:81], v[190:193], v[154:157]
	v_mfma_f32_16x16x32_bf16 v[138:141], v[78:81], v[204:207], v[138:141]
	v_mfma_f32_16x16x32_bf16 v[142:145], v[62:65], v[204:207], v[142:145]
	v_mfma_f32_16x16x32_bf16 v[126:129], v[62:65], v[212:215], v[126:129]
	v_mfma_f32_16x16x32_bf16 v[122:125], v[78:81], v[212:215], v[122:125]
	v_mfma_f32_16x16x32_bf16 v[106:109], v[78:81], v[220:223], v[106:109]
	v_mfma_f32_16x16x32_bf16 v[110:113], v[62:65], v[220:223], v[110:113]
	v_mfma_f32_16x16x32_bf16 v[150:153], v[82:85], v[186:189], v[150:153]
	v_mfma_f32_16x16x32_bf16 v[146:149], v[90:93], v[186:189], v[146:149]
	v_mfma_f32_16x16x32_bf16 v[130:133], v[90:93], v[200:203], v[130:133]
	v_mfma_f32_16x16x32_bf16 v[134:137], v[82:85], v[200:203], v[134:137]
	v_mfma_f32_16x16x32_bf16 v[118:121], v[82:85], v[208:211], v[118:121]
	v_mfma_f32_16x16x32_bf16 v[114:117], v[90:93], v[208:211], v[114:117]
	v_mfma_f32_16x16x32_bf16 v[98:101], v[90:93], v[216:219], v[98:101]
	v_mfma_f32_16x16x32_bf16 v[102:105], v[82:85], v[216:219], v[102:105]
	v_mfma_f32_16x16x32_bf16 v[150:153], v[86:89], v[190:193], v[150:153]
	v_mfma_f32_16x16x32_bf16 v[146:149], v[94:97], v[190:193], v[146:149]
	v_mfma_f32_16x16x32_bf16 v[130:133], v[94:97], v[204:207], v[130:133]
	v_mfma_f32_16x16x32_bf16 v[134:137], v[86:89], v[204:207], v[134:137]
	v_mfma_f32_16x16x32_bf16 v[118:121], v[86:89], v[212:215], v[118:121]
	v_mfma_f32_16x16x32_bf16 v[114:117], v[94:97], v[212:215], v[114:117]
	v_mfma_f32_16x16x32_bf16 v[98:101], v[94:97], v[220:223], v[98:101]
	v_mfma_f32_16x16x32_bf16 v[102:105], v[86:89], v[220:223], v[102:105]
	s_barrier
	s_setprio 0
	s_add_i32 s10, s35, s76
	v_lshl_add_u64 v[194:195], s[68:69], 0, v[0:1]
	s_mov_b32 m0, s10
	ds_read_b128 v[186:189], v199 offset:16384
	ds_read_b128 v[190:193], v199 offset:17408
	ds_read_b128 v[200:203], v199 offset:18432
	ds_read_b128 v[204:207], v199 offset:19456
	ds_read_b128 v[208:211], v199 offset:20480
	ds_read_b128 v[212:215], v199 offset:21504
	ds_read_b128 v[216:219], v199 offset:22528
	ds_read_b128 v[220:223], v199 offset:23552
	global_load_lds_dwordx4 v[194:195], off
	s_add_i32 m0, s10, 0x2000
	s_add_u32 s10, s68, 0x40000
	v_lshl_add_u64 v[224:225], s[68:69], 0, v[180:181]
	s_addc_u32 s11, s69, 0
	s_add_i32 s35, s45, s76
	global_load_lds_dwordx4 v[224:225], off
	v_lshl_add_u64 v[226:227], s[10:11], 0, v[0:1]
	s_mov_b32 m0, s35
	v_lshl_add_u64 v[238:239], s[72:73], 0, v[178:179]
	global_load_lds_dwordx4 v[226:227], off
	v_lshl_add_u64 v[226:227], s[10:11], 0, v[180:181]
	s_add_i32 m0, s35, 0x2000
	s_nop 0
	global_load_lds_dwordx4 v[226:227], off
	v_lshl_add_u64 v[226:227], s[72:73], 0, v[176:177]
	s_mov_b32 m0, s77
	s_nop 0
	global_load_lds_dwordx4 v[226:227], off
	s_mov_b32 m0, s2
	s_nop 0
	global_load_lds_dwordx4 v[238:239], off
	s_waitcnt vmcnt(8)
	s_waitcnt lgkmcnt(0)
	s_setprio 1
	s_barrier
; #define PG8_STAGE(bufoff, gbase, voff) do { _Pragma("unroll") for (int _i = 0; _i < 2; ++_i) \
;         __builtin_amdgcn_global_load_lds((const unsigned*)((const char*)(gbase) + (voff)[_i]), (PG8_LAS unsigned*)(lds + (bufoff) + ldsw + _i * 8192), 16, 0, 0); } while (0)
; #define PG8_LDA(dst, b, h) do { _Pragma("unroll") for (int m = 0; m < 4; ++m) _Pragma("unroll") for (int k = 0; k < 2; ++k) dst[m][k] = *(const PG8_LAS bf16x8*)(lds + PG8_SA(b, h) + aoff + m * 2048 + k * 1024); } while (0)
; #define PG8_LDB(dst, b, h) do { _Pragma("unroll") for (int n = 0; n < 2; ++n) _Pragma("unroll") for (int k = 0; k < 2; ++k) dst[n][k] = *(const PG8_LAS bf16x8*)(lds + PG8_SB(b, h) + boff + n * 2048 + k * 1024); } while (0)
; #define PG8_MMA(ai, bj, At, Bt) do { __builtin_amdgcn_s_setprio(1); _Pragma("unroll") for (int m = 0; m < 4; ++m) _Pragma("unroll") for (int n = 0; n < 2; ++n) _Pragma("unroll") for (int k = 0; k < 2; ++k) \
;         acc[ai][bj][m][n] = __builtin_amdgcn_mfma_f32_16x16x32_bf16(Bt[n][k], At[m][k], acc[ai][bj][m][n], 0, 0, 0); __builtin_amdgcn_s_setprio(0); } while (0)
; #define PG8_WAIT_V(n) asm volatile("s_waitcnt vmcnt(" #n ")" ::: "memory")
; #define PG8_WAIT_L(n) asm volatile("s_waitcnt lgkmcnt(" #n ")" ::: "memory")
; #define PG8_BAR __builtin_amdgcn_s_barrier()
; #define PG8_SCHED __builtin_amdgcn_sched_barrier(0)
; template <class Epi, class Sched, bool ALIGN_EPI = false, bool SP2 = false>
; __device__ __forceinline__ void gemm_phase(PG8_LAS unsigned char* lds, const Gemm g, const Sched& S, const Epi& E) {
;     ...
;             PG8_WAIT_V(8); PG8_WAIT_L(0); PG8_BAR; PG8_MMA(1, 0, At, B0); PG8_MMA(1, 1, At, B1); PG8_BAR; PG8_SCHED;
;             PG8_LDB(B0, 1, 0); PG8_LDB(B1, 1, 1); PG8_SCHED; PG8_LDA(At, 1, 0); PG8_STAGE(PG8_SA(0, 1), a2 + hstep, voffA);
;             PG8_WAIT_V(8); PG8_WAIT_L(0); PG8_BAR; PG8_MMA(0, 0, At, B0); PG8_MMA(0, 1, At, B1); PG8_BAR; PG8_SCHED;
	v_mfma_f32_16x16x32_bf16 v[70:73], v[58:61], v[186:189], v[70:73]
	v_mfma_f32_16x16x32_bf16 v[66:69], v[74:77], v[186:189], v[66:69]
	v_mfma_f32_16x16x32_bf16 v[42:45], v[74:77], v[200:203], v[42:45]
	v_mfma_f32_16x16x32_bf16 v[46:49], v[58:61], v[200:203], v[46:49]
	v_mfma_f32_16x16x32_bf16 v[30:33], v[58:61], v[208:211], v[30:33]
	v_mfma_f32_16x16x32_bf16 v[26:29], v[74:77], v[208:211], v[26:29]
	v_mfma_f32_16x16x32_bf16 v[10:13], v[74:77], v[216:219], v[10:13]
	v_mfma_f32_16x16x32_bf16 v[14:17], v[58:61], v[216:219], v[14:17]
	v_mfma_f32_16x16x32_bf16 v[70:73], v[62:65], v[190:193], v[70:73]
	v_mfma_f32_16x16x32_bf16 v[66:69], v[78:81], v[190:193], v[66:69]
	v_mfma_f32_16x16x32_bf16 v[42:45], v[78:81], v[204:207], v[42:45]
	v_mfma_f32_16x16x32_bf16 v[46:49], v[62:65], v[204:207], v[46:49]
	v_mfma_f32_16x16x32_bf16 v[30:33], v[62:65], v[212:215], v[30:33]
	v_mfma_f32_16x16x32_bf16 v[26:29], v[78:81], v[212:215], v[26:29]
	v_mfma_f32_16x16x32_bf16 v[10:13], v[78:81], v[220:223], v[10:13]
	v_mfma_f32_16x16x32_bf16 v[14:17], v[62:65], v[220:223], v[14:17]
	v_mfma_f32_16x16x32_bf16 v[54:57], v[82:85], v[186:189], v[54:57]
	v_mfma_f32_16x16x32_bf16 v[50:53], v[90:93], v[186:189], v[50:53]
	v_mfma_f32_16x16x32_bf16 v[34:37], v[90:93], v[200:203], v[34:37]
	v_mfma_f32_16x16x32_bf16 v[38:41], v[82:85], v[200:203], v[38:41]
	v_mfma_f32_16x16x32_bf16 v[22:25], v[82:85], v[208:211], v[22:25]
	v_mfma_f32_16x16x32_bf16 v[18:21], v[90:93], v[208:211], v[18:21]
	v_mfma_f32_16x16x32_bf16 v[2:5], v[90:93], v[216:219], v[2:5]
	v_mfma_f32_16x16x32_bf16 v[6:9], v[82:85], v[216:219], v[6:9]
	v_mfma_f32_16x16x32_bf16 v[54:57], v[86:89], v[190:193], v[54:57]
	v_mfma_f32_16x16x32_bf16 v[50:53], v[94:97], v[190:193], v[50:53]
	v_mfma_f32_16x16x32_bf16 v[34:37], v[94:97], v[204:207], v[34:37]
	v_mfma_f32_16x16x32_bf16 v[38:41], v[86:89], v[204:207], v[38:41]
	v_mfma_f32_16x16x32_bf16 v[22:25], v[86:89], v[212:215], v[22:25]
	v_mfma_f32_16x16x32_bf16 v[18:21], v[94:97], v[212:215], v[18:21]
	v_mfma_f32_16x16x32_bf16 v[2:5], v[94:97], v[220:223], v[2:5]
	v_mfma_f32_16x16x32_bf16 v[6:9], v[86:89], v[220:223], v[6:9]
	s_barrier
	s_setprio 0
	s_add_i32 s35, 16, 0x18000
	s_add_i32 s45, 16, 0x1c000
	v_add_u32_e32 v78, s35, v197
	v_add_u32_e32 v94, s45, v197
	ds_read_b128 v[58:61], v78
	ds_read_b128 v[62:65], v78 offset:1024
	ds_read_b128 v[74:77], v78 offset:2048
	ds_read_b128 v[78:81], v78 offset:3072
	ds_read_b128 v[82:85], v94
	ds_read_b128 v[86:89], v94 offset:1024
	ds_read_b128 v[90:93], v94 offset:2048
	ds_read_b128 v[94:97], v94 offset:3072
	s_add_u32 s10, s72, 0x40000
	s_addc_u32 s11, s73, 0
	s_mov_b32 m0, s3
	v_lshl_add_u64 v[240:241], s[10:11], 0, v[176:177]
	ds_read_b128 v[186:189], v199 offset:32768
	ds_read_b128 v[190:193], v199 offset:33792
	ds_read_b128 v[200:203], v199 offset:34816
	ds_read_b128 v[204:207], v199 offset:35840
	ds_read_b128 v[208:211], v199 offset:36864
	ds_read_b128 v[212:215], v199 offset:37888
	ds_read_b128 v[216:219], v199 offset:38912
	ds_read_b128 v[220:223], v199 offset:39936
	global_load_lds_dwordx4 v[240:241], off
	v_lshl_add_u64 v[240:241], s[10:11], 0, v[178:179]
	s_mov_b32 m0, s78
	s_nop 0
	global_load_lds_dwordx4 v[240:241], off
	s_waitcnt vmcnt(8)
	s_waitcnt lgkmcnt(0)
	s_setprio 1
	s_barrier
	v_mfma_f32_16x16x32_bf16 v[158:161], v[58:61], v[186:189], v[158:161]
	v_mfma_f32_16x16x32_bf16 v[154:157], v[74:77], v[186:189], v[154:157]
	v_mfma_f32_16x16x32_bf16 v[138:141], v[74:77], v[200:203], v[138:141]
	v_mfma_f32_16x16x32_bf16 v[142:145], v[58:61], v[200:203], v[142:145]
	v_mfma_f32_16x16x32_bf16 v[126:129], v[58:61], v[208:211], v[126:129]
	v_mfma_f32_16x16x32_bf16 v[122:125], v[74:77], v[208:211], v[122:125]
	v_mfma_f32_16x16x32_bf16 v[106:109], v[74:77], v[216:219], v[106:109]
	v_mfma_f32_16x16x32_bf16 v[110:113], v[58:61], v[216:219], v[110:113]
	v_mfma_f32_16x16x32_bf16 v[158:161], v[62:65], v[190:193], v[158:161]
	v_mfma_f32_16x16x32_bf16 v[154:157], v[78:81], v[190:193], v[154:157]
	v_mfma_f32_16x16x32_bf16 v[138:141], v[78:81], v[204:207], v[138:141]
	v_mfma_f32_16x16x32_bf16 v[142:145], v[62:65], v[204:207], v[142:145]
	v_mfma_f32_16x16x32_bf16 v[126:129], v[62:65], v[212:215], v[126:129]
	v_mfma_f32_16x16x32_bf16 v[122:125], v[78:81], v[212:215], v[122:125]
	v_mfma_f32_16x16x32_bf16 v[106:109], v[78:81], v[220:223], v[106:109]
	v_mfma_f32_16x16x32_bf16 v[110:113], v[62:65], v[220:223], v[110:113]
	v_mfma_f32_16x16x32_bf16 v[150:153], v[82:85], v[186:189], v[150:153]
	v_mfma_f32_16x16x32_bf16 v[146:149], v[90:93], v[186:189], v[146:149]
	v_mfma_f32_16x16x32_bf16 v[130:133], v[90:93], v[200:203], v[130:133]
	v_mfma_f32_16x16x32_bf16 v[134:137], v[82:85], v[200:203], v[134:137]
	v_mfma_f32_16x16x32_bf16 v[118:121], v[82:85], v[208:211], v[118:121]
	v_mfma_f32_16x16x32_bf16 v[114:117], v[90:93], v[208:211], v[114:117]
	v_mfma_f32_16x16x32_bf16 v[98:101], v[90:93], v[216:219], v[98:101]
	v_mfma_f32_16x16x32_bf16 v[102:105], v[82:85], v[216:219], v[102:105]
	v_mfma_f32_16x16x32_bf16 v[150:153], v[86:89], v[190:193], v[150:153]
	v_mfma_f32_16x16x32_bf16 v[146:149], v[94:97], v[190:193], v[146:149]
	v_mfma_f32_16x16x32_bf16 v[130:133], v[94:97], v[204:207], v[130:133]
	v_mfma_f32_16x16x32_bf16 v[134:137], v[86:89], v[204:207], v[134:137]
	v_mfma_f32_16x16x32_bf16 v[118:121], v[86:89], v[212:215], v[118:121]
	v_mfma_f32_16x16x32_bf16 v[114:117], v[94:97], v[212:215], v[114:117]
	v_mfma_f32_16x16x32_bf16 v[98:101], v[94:97], v[220:223], v[98:101]
	v_mfma_f32_16x16x32_bf16 v[102:105], v[86:89], v[220:223], v[102:105]
	s_barrier
; #define PG8_STAGE(bufoff, gbase, voff) do { _Pragma("unroll") for (int _i = 0; _i < 2; ++_i) \
;         __builtin_amdgcn_global_load_lds((const unsigned*)((const char*)(gbase) + (voff)[_i]), (PG8_LAS unsigned*)(lds + (bufoff) + ldsw + _i * 8192), 16, 0, 0); } while (0)
; #define PG8_LDA(dst, b, h) do { _Pragma("unroll") for (int m = 0; m < 4; ++m) _Pragma("unroll") for (int k = 0; k < 2; ++k) dst[m][k] = *(const PG8_LAS bf16x8*)(lds + PG8_SA(b, h) + aoff + m * 2048 + k * 1024); } while (0)
; #define PG8_MMA(ai, bj, At, Bt) do { __builtin_amdgcn_s_setprio(1); _Pragma("unroll") for (int m = 0; m < 4; ++m) _Pragma("unroll") for (int n = 0; n < 2; ++n) _Pragma("unroll") for (int k = 0; k < 2; ++k) \
;         acc[ai][bj][m][n] = __builtin_amdgcn_mfma_f32_16x16x32_bf16(Bt[n][k], At[m][k], acc[ai][bj][m][n], 0, 0, 0); __builtin_amdgcn_s_setprio(0); } while (0)
; #define PG8_WAIT_V(n) asm volatile("s_waitcnt vmcnt(" #n ")" ::: "memory")
; #define PG8_WAIT_L(n) asm volatile("s_waitcnt lgkmcnt(" #n ")" ::: "memory")
; #define PG8_BAR __builtin_amdgcn_s_barrier()
; #define PG8_SCHED __builtin_amdgcn_sched_barrier(0)
; template <class Epi, class Sched, bool ALIGN_EPI = false, bool SP2 = false>
; __device__ __forceinline__ void gemm_phase(PG8_LAS unsigned char* lds, const Gemm g, const Sched& S, const Epi& E) {
;     ...
;         for (int t = 0; t < nt; t += 2) {
;     ...
;             PG8_LDA(At, 1, 1); PG8_STAGE(PG8_SB(1, 0), b3, voffB); PG8_STAGE(PG8_SB(1, 1), b3 + hstep, voffB); PG8_STAGE(PG8_SA(1, 0), a3, voffA);
;             PG8_WAIT_V(8); PG8_WAIT_L(0); PG8_BAR; PG8_MMA(1, 0, At, B0); PG8_MMA(1, 1, At, B1); PG8_BAR; PG8_SCHED;
	s_setprio 0
	s_add_i32 s10, s35, s76
	v_lshl_add_u64 v[194:195], v[194:195], 0, s[28:29]
	s_mov_b32 m0, s10
	ds_read_b128 v[186:189], v199 offset:49152
	ds_read_b128 v[190:193], v199 offset:50176
	ds_read_b128 v[200:203], v199 offset:51200
	ds_read_b128 v[204:207], v199 offset:52224
	ds_read_b128 v[208:211], v199 offset:53248
	ds_read_b128 v[212:215], v199 offset:54272
	ds_read_b128 v[216:219], v199 offset:55296
	ds_read_b128 v[220:223], v199 offset:56320
	global_load_lds_dwordx4 v[194:195], off
	s_add_i32 m0, s10, 0x2000
	s_add_u32 s10, s68, 0x40080
	v_lshl_add_u64 v[194:195], v[224:225], 0, s[28:29]
	s_addc_u32 s11, s69, 0
	s_add_i32 s35, s45, s76
	global_load_lds_dwordx4 v[194:195], off
	v_lshl_add_u64 v[194:195], s[10:11], 0, v[0:1]
	s_mov_b32 m0, s35
	s_nop 0
	global_load_lds_dwordx4 v[194:195], off
	v_lshl_add_u64 v[194:195], s[10:11], 0, v[180:181]
	s_add_i32 m0, s35, 0x2000
	s_nop 0
	global_load_lds_dwordx4 v[194:195], off
	v_lshl_add_u64 v[194:195], v[226:227], 0, s[28:29]
	s_mov_b32 m0, s94
	s_nop 0
	global_load_lds_dwordx4 v[194:195], off
	v_lshl_add_u64 v[194:195], v[238:239], 0, s[28:29]
	s_mov_b32 m0, s95
	s_nop 0
	global_load_lds_dwordx4 v[194:195], off
	s_waitcnt vmcnt(8)
	s_waitcnt lgkmcnt(0)
	s_setprio 1
	s_barrier
	v_mfma_f32_16x16x32_bf16 v[70:73], v[58:61], v[186:189], v[70:73]
	v_mfma_f32_16x16x32_bf16 v[66:69], v[74:77], v[186:189], v[66:69]
	v_mfma_f32_16x16x32_bf16 v[42:45], v[74:77], v[200:203], v[42:45]
	v_mfma_f32_16x16x32_bf16 v[46:49], v[58:61], v[200:203], v[46:49]
	v_mfma_f32_16x16x32_bf16 v[30:33], v[58:61], v[208:211], v[30:33]
	v_mfma_f32_16x16x32_bf16 v[26:29], v[74:77], v[208:211], v[26:29]
	v_mfma_f32_16x16x32_bf16 v[10:13], v[74:77], v[216:219], v[10:13]
	v_mfma_f32_16x16x32_bf16 v[14:17], v[58:61], v[216:219], v[14:17]
	v_mfma_f32_16x16x32_bf16 v[70:73], v[62:65], v[190:193], v[70:73]
	v_mfma_f32_16x16x32_bf16 v[66:69], v[78:81], v[190:193], v[66:69]
	v_mfma_f32_16x16x32_bf16 v[42:45], v[78:81], v[204:207], v[42:45]
	v_mfma_f32_16x16x32_bf16 v[46:49], v[62:65], v[204:207], v[46:49]
	v_mfma_f32_16x16x32_bf16 v[30:33], v[62:65], v[212:215], v[30:33]
	v_mfma_f32_16x16x32_bf16 v[26:29], v[78:81], v[212:215], v[26:29]
	v_mfma_f32_16x16x32_bf16 v[10:13], v[78:81], v[220:223], v[10:13]
	v_mfma_f32_16x16x32_bf16 v[14:17], v[62:65], v[220:223], v[14:17]
	v_mfma_f32_16x16x32_bf16 v[54:57], v[82:85], v[186:189], v[54:57]
	v_mfma_f32_16x16x32_bf16 v[50:53], v[90:93], v[186:189], v[50:53]
	v_mfma_f32_16x16x32_bf16 v[34:37], v[90:93], v[200:203], v[34:37]
	v_mfma_f32_16x16x32_bf16 v[38:41], v[82:85], v[200:203], v[38:41]
	v_mfma_f32_16x16x32_bf16 v[22:25], v[82:85], v[208:211], v[22:25]
	v_mfma_f32_16x16x32_bf16 v[18:21], v[90:93], v[208:211], v[18:21]
	v_mfma_f32_16x16x32_bf16 v[2:5], v[90:93], v[216:219], v[2:5]
	v_mfma_f32_16x16x32_bf16 v[6:9], v[82:85], v[216:219], v[6:9]
	v_mfma_f32_16x16x32_bf16 v[54:57], v[86:89], v[190:193], v[54:57]
	v_mfma_f32_16x16x32_bf16 v[50:53], v[94:97], v[190:193], v[50:53]
	v_mfma_f32_16x16x32_bf16 v[34:37], v[94:97], v[204:207], v[34:37]
	v_mfma_f32_16x16x32_bf16 v[38:41], v[86:89], v[204:207], v[38:41]
	v_mfma_f32_16x16x32_bf16 v[22:25], v[86:89], v[212:215], v[22:25]
	v_mfma_f32_16x16x32_bf16 v[18:21], v[94:97], v[212:215], v[18:21]
	v_mfma_f32_16x16x32_bf16 v[2:5], v[94:97], v[220:223], v[2:5]
	v_mfma_f32_16x16x32_bf16 v[6:9], v[86:89], v[220:223], v[6:9]
	s_barrier
	s_setprio 0
	s_add_i32 s34, s34, 2
	s_add_u32 s25, s25, 0x100
	s_addc_u32 s27, s27, 0
	s_add_u32 s42, s42, 0x100
	s_addc_u32 s43, s43, 0
	s_cmp_gt_u32 s34, 13
	s_cbranch_scc0 .LBB0_915
	s_and_b64 vcc, exec, s[20:21]
	s_cbranch_vccz .LBB0_918
	s_barrier

; #define PG8_STAGE(bufoff, gbase, voff) do { _Pragma("unroll") for (int _i = 0; _i < 2; ++_i) \
;         __builtin_amdgcn_global_load_lds((const unsigned*)((const char*)(gbase) + (voff)[_i]), (PG8_LAS unsigned*)(lds + (bufoff) + ldsw + _i * 8192), 16, 0, 0); } while (0)
; #define PG8_LDA(dst, b, h) do { _Pragma("unroll") for (int m = 0; m < 4; ++m) _Pragma("unroll") for (int k = 0; k < 2; ++k) dst[m][k] = *(const PG8_LAS bf16x8*)(lds + PG8_SA(b, h) + aoff + m * 2048 + k * 1024); } while (0)
; #define PG8_LDB(dst, b, h) do { _Pragma("unroll") for (int n = 0; n < 2; ++n) _Pragma("unroll") for (int k = 0; k < 2; ++k) dst[n][k] = *(const PG8_LAS bf16x8*)(lds + PG8_SB(b, h) + boff + n * 2048 + k * 1024); } while (0)
; #define PG8_MMA(ai, bj, At, Bt) do { __builtin_amdgcn_s_setprio(1); _Pragma("unroll") for (int m = 0; m < 4; ++m) _Pragma("unroll") for (int n = 0; n < 2; ++n) _Pragma("unroll") for (int k = 0; k < 2; ++k) \
;         acc[ai][bj][m][n] = __builtin_amdgcn_mfma_f32_16x16x32_bf16(Bt[n][k], At[m][k], acc[ai][bj][m][n], 0, 0, 0); __builtin_amdgcn_s_setprio(0); } while (0)
; #define PG8_WAIT_V(n) asm volatile("s_waitcnt vmcnt(" #n ")" ::: "memory")
; #define PG8_WAIT_L(n) asm volatile("s_waitcnt lgkmcnt(" #n ")" ::: "memory")
; #define PG8_BAR __builtin_amdgcn_s_barrier()
; #define PG8_SCHED __builtin_amdgcn_sched_barrier(0)
; template <class Epi, class Sched, bool ALIGN_EPI = false, bool SP2 = false>
; __device__ __forceinline__ void gemm_phase(PG8_LAS unsigned char* lds, const Gemm g, const Sched& S, const Epi& E) {
;     ...
;             const bool last = (t == nt - 2);
;             const char* a1 = cA + (size_t)(t + 1) * kstep;
;             const char* a2 = last ? nA : cA + (size_t)(t + 2) * kstep; const char* b2 = last ? nB : cB + (size_t)(t + 2) * kstep;
;             const char* a3 = a2 + kstep; const char* b3 = b2 + kstep;
;             if (last && has_next) S.a_ready(nxt);
;             if constexpr (SP2) {
;             PG8_LDB(B0, 0, 0); PG8_LDB(B1, 0, 1); PG8_SCHED; PG8_LDA(At, 0, 0); PG8_STAGE(PG8_SA(1, 1), a1 + hstep, voffA);
;             PG8_WAIT_V(8); PG8_WAIT_L(0); PG8_BAR; PG8_MMA(0, 0, At, B0); PG8_MMA(0, 1, At, B1); PG8_BAR; PG8_SCHED;
;             PG8_LDA(At, 0, 1); PG8_STAGE(PG8_SB(0, 0), b2, voffB); PG8_STAGE(PG8_SB(0, 1), b2 + hstep, voffB); PG8_STAGE(PG8_SA(0, 0), a2, voffA);
.LBB0_1033:
	s_add_u32 s10, s50, 0xfffc0080
	s_addc_u32 s11, s51, -1
	s_add_i32 s69, 16, 0x10000
	s_cmp_eq_u32 s68, 12
	s_cselect_b32 s61, s34, s11
	s_cselect_b32 s60, s35, s10
	s_cselect_b32 s59, s27, s67
	s_cselect_b32 s58, s43, s66
	s_add_i32 s72, 16, 0x14000
	v_add_u32_e32 v142, s69, v177
	v_add_u32_e32 v188, s72, v177
	ds_read_b128 v[130:133], v142
	ds_read_b128 v[134:137], v142 offset:1024
	ds_read_b128 v[138:141], v142 offset:2048
	ds_read_b128 v[142:145], v142 offset:3072
	ds_read_b128 v[158:161], v188
	ds_read_b128 v[180:183], v188 offset:1024
	ds_read_b128 v[184:187], v188 offset:2048
	ds_read_b128 v[188:191], v188 offset:3072
	v_lshl_add_u64 v[224:225], s[50:51], 0, v[156:157]
	s_add_i32 m0, s9, 0xc000
	ds_read_b128 v[192:195], v179
	ds_read_b128 v[196:199], v179 offset:1024
	ds_read_b128 v[200:203], v179 offset:2048
	ds_read_b128 v[204:207], v179 offset:3072
	ds_read_b128 v[208:211], v179 offset:4096
	ds_read_b128 v[212:215], v179 offset:5120
	ds_read_b128 v[216:219], v179 offset:6144
	ds_read_b128 v[220:223], v179 offset:7168
	global_load_lds_dwordx4 v[224:225], off
	v_lshl_add_u64 v[224:225], s[50:51], 0, v[154:155]
	s_add_i32 m0, s9, 0xe000
	s_nop 0
	global_load_lds_dwordx4 v[224:225], off
	s_waitcnt vmcnt(8)
	s_waitcnt lgkmcnt(0)
	s_setprio 1
	s_barrier
	v_mfma_f32_16x16x32_bf16 v[126:129], v[130:133], v[192:195], v[126:129]
	v_mfma_f32_16x16x32_bf16 v[122:125], v[138:141], v[192:195], v[122:125]
	v_mfma_f32_16x16x32_bf16 v[106:109], v[138:141], v[200:203], v[106:109]
	v_mfma_f32_16x16x32_bf16 v[110:113], v[130:133], v[200:203], v[110:113]
	v_mfma_f32_16x16x32_bf16 v[94:97], v[130:133], v[208:211], v[94:97]
	v_mfma_f32_16x16x32_bf16 v[90:93], v[138:141], v[208:211], v[90:93]
	v_mfma_f32_16x16x32_bf16 v[74:77], v[138:141], v[216:219], v[74:77]
	v_mfma_f32_16x16x32_bf16 v[78:81], v[130:133], v[216:219], v[78:81]
	v_mfma_f32_16x16x32_bf16 v[126:129], v[134:137], v[196:199], v[126:129]
	v_mfma_f32_16x16x32_bf16 v[122:125], v[142:145], v[196:199], v[122:125]
	v_mfma_f32_16x16x32_bf16 v[106:109], v[142:145], v[204:207], v[106:109]
	v_mfma_f32_16x16x32_bf16 v[110:113], v[134:137], v[204:207], v[110:113]
	v_mfma_f32_16x16x32_bf16 v[94:97], v[134:137], v[212:215], v[94:97]
	v_mfma_f32_16x16x32_bf16 v[90:93], v[142:145], v[212:215], v[90:93]
	v_mfma_f32_16x16x32_bf16 v[74:77], v[142:145], v[220:223], v[74:77]
	v_mfma_f32_16x16x32_bf16 v[78:81], v[134:137], v[220:223], v[78:81]
	v_mfma_f32_16x16x32_bf16 v[118:121], v[158:161], v[192:195], v[118:121]
	v_mfma_f32_16x16x32_bf16 v[114:117], v[184:187], v[192:195], v[114:117]
	v_mfma_f32_16x16x32_bf16 v[98:101], v[184:187], v[200:203], v[98:101]
	v_mfma_f32_16x16x32_bf16 v[102:105], v[158:161], v[200:203], v[102:105]
	v_mfma_f32_16x16x32_bf16 v[86:89], v[158:161], v[208:211], v[86:89]
	v_mfma_f32_16x16x32_bf16 v[82:85], v[184:187], v[208:211], v[82:85]
	v_mfma_f32_16x16x32_bf16 v[66:69], v[184:187], v[216:219], v[66:69]
	v_mfma_f32_16x16x32_bf16 v[70:73], v[158:161], v[216:219], v[70:73]
	v_mfma_f32_16x16x32_bf16 v[118:121], v[180:183], v[196:199], v[118:121]
	v_mfma_f32_16x16x32_bf16 v[114:117], v[188:191], v[196:199], v[114:117]
	v_mfma_f32_16x16x32_bf16 v[98:101], v[188:191], v[204:207], v[98:101]
	v_mfma_f32_16x16x32_bf16 v[102:105], v[180:183], v[204:207], v[102:105]
	v_mfma_f32_16x16x32_bf16 v[86:89], v[180:183], v[212:215], v[86:89]
	v_mfma_f32_16x16x32_bf16 v[82:85], v[188:191], v[212:215], v[82:85]
	v_mfma_f32_16x16x32_bf16 v[66:69], v[188:191], v[220:223], v[66:69]
	v_mfma_f32_16x16x32_bf16 v[70:73], v[180:183], v[220:223], v[70:73]
	s_barrier
	s_setprio 0
	s_add_i32 s10, s69, s6
	v_lshl_add_u64 v[224:225], s[58:59], 0, v[0:1]
	s_mov_b32 m0, s10
	ds_read_b128 v[192:195], v179 offset:16384
	ds_read_b128 v[196:199], v179 offset:17408
	ds_read_b128 v[200:203], v179 offset:18432
	ds_read_b128 v[204:207], v179 offset:19456
	ds_read_b128 v[208:211], v179 offset:20480
	ds_read_b128 v[212:215], v179 offset:21504
	ds_read_b128 v[216:219], v179 offset:22528
	ds_read_b128 v[220:223], v179 offset:23552
	global_load_lds_dwordx4 v[224:225], off
	s_add_i32 m0, s10, 0x2000
	s_add_u32 s10, s58, 0x40000
	v_lshl_add_u64 v[226:227], s[58:59], 0, v[146:147]
	s_addc_u32 s11, s59, 0
	s_add_i32 s69, s72, s6
	global_load_lds_dwordx4 v[226:227], off
	v_lshl_add_u64 v[238:239], s[10:11], 0, v[0:1]
	s_mov_b32 m0, s69
	v_lshl_add_u64 v[240:241], s[60:61], 0, v[148:149]
	global_load_lds_dwordx4 v[238:239], off
	v_lshl_add_u64 v[238:239], s[10:11], 0, v[146:147]
	s_add_i32 m0, s69, 0x2000
	s_nop 0
	global_load_lds_dwordx4 v[238:239], off
	v_lshl_add_u64 v[238:239], s[60:61], 0, v[150:151]
	s_mov_b32 m0, s9
	s_nop 0
	global_load_lds_dwordx4 v[238:239], off
	s_mov_b32 m0, s54
	s_nop 0
	global_load_lds_dwordx4 v[240:241], off
	s_waitcnt vmcnt(8)
	s_waitcnt lgkmcnt(0)
	s_setprio 1
	s_barrier
; #define PG8_STAGE(bufoff, gbase, voff) do { _Pragma("unroll") for (int _i = 0; _i < 2; ++_i) \
;         __builtin_amdgcn_global_load_lds((const unsigned*)((const char*)(gbase) + (voff)[_i]), (PG8_LAS unsigned*)(lds + (bufoff) + ldsw + _i * 8192), 16, 0, 0); } while (0)
; #define PG8_LDA(dst, b, h) do { _Pragma("unroll") for (int m = 0; m < 4; ++m) _Pragma("unroll") for (int k = 0; k < 2; ++k) dst[m][k] = *(const PG8_LAS bf16x8*)(lds + PG8_SA(b, h) + aoff + m * 2048 + k * 1024); } while (0)
; #define PG8_LDB(dst, b, h) do { _Pragma("unroll") for (int n = 0; n < 2; ++n) _Pragma("unroll") for (int k = 0; k < 2; ++k) dst[n][k] = *(const PG8_LAS bf16x8*)(lds + PG8_SB(b, h) + boff + n * 2048 + k * 1024); } while (0)
; #define PG8_MMA(ai, bj, At, Bt) do { __builtin_amdgcn_s_setprio(1); _Pragma("unroll") for (int m = 0; m < 4; ++m) _Pragma("unroll") for (int n = 0; n < 2; ++n) _Pragma("unroll") for (int k = 0; k < 2; ++k) \
;         acc[ai][bj][m][n] = __builtin_amdgcn_mfma_f32_16x16x32_bf16(Bt[n][k], At[m][k], acc[ai][bj][m][n], 0, 0, 0); __builtin_amdgcn_s_setprio(0); } while (0)
; #define PG8_WAIT_V(n) asm volatile("s_waitcnt vmcnt(" #n ")" ::: "memory")
; #define PG8_WAIT_L(n) asm volatile("s_waitcnt lgkmcnt(" #n ")" ::: "memory")
; #define PG8_BAR __builtin_amdgcn_s_barrier()
; #define PG8_SCHED __builtin_amdgcn_sched_barrier(0)
; template <class Epi, class Sched, bool ALIGN_EPI = false, bool SP2 = false>
; __device__ __forceinline__ void gemm_phase(PG8_LAS unsigned char* lds, const Gemm g, const Sched& S, const Epi& E) {
;     ...
;             PG8_WAIT_V(8); PG8_WAIT_L(0); PG8_BAR; PG8_MMA(1, 0, At, B0); PG8_MMA(1, 1, At, B1); PG8_BAR; PG8_SCHED;
;             PG8_LDB(B0, 1, 0); PG8_LDB(B1, 1, 1); PG8_SCHED; PG8_LDA(At, 1, 0); PG8_STAGE(PG8_SA(0, 1), a2 + hstep, voffA);
;             PG8_WAIT_V(8); PG8_WAIT_L(0); PG8_BAR; PG8_MMA(0, 0, At, B0); PG8_MMA(0, 1, At, B1); PG8_BAR; PG8_SCHED;
	v_mfma_f32_16x16x32_bf16 v[62:65], v[130:133], v[192:195], v[62:65]
	v_mfma_f32_16x16x32_bf16 v[58:61], v[138:141], v[192:195], v[58:61]
	v_mfma_f32_16x16x32_bf16 v[42:45], v[138:141], v[200:203], v[42:45]
	v_mfma_f32_16x16x32_bf16 v[46:49], v[130:133], v[200:203], v[46:49]
	v_mfma_f32_16x16x32_bf16 v[30:33], v[130:133], v[208:211], v[30:33]
	v_mfma_f32_16x16x32_bf16 v[26:29], v[138:141], v[208:211], v[26:29]
	v_mfma_f32_16x16x32_bf16 v[10:13], v[138:141], v[216:219], v[10:13]
	v_mfma_f32_16x16x32_bf16 v[14:17], v[130:133], v[216:219], v[14:17]
	v_mfma_f32_16x16x32_bf16 v[62:65], v[134:137], v[196:199], v[62:65]
	v_mfma_f32_16x16x32_bf16 v[58:61], v[142:145], v[196:199], v[58:61]
	v_mfma_f32_16x16x32_bf16 v[42:45], v[142:145], v[204:207], v[42:45]
	v_mfma_f32_16x16x32_bf16 v[46:49], v[134:137], v[204:207], v[46:49]
	v_mfma_f32_16x16x32_bf16 v[30:33], v[134:137], v[212:215], v[30:33]
	v_mfma_f32_16x16x32_bf16 v[26:29], v[142:145], v[212:215], v[26:29]
	v_mfma_f32_16x16x32_bf16 v[10:13], v[142:145], v[220:223], v[10:13]
	v_mfma_f32_16x16x32_bf16 v[14:17], v[134:137], v[220:223], v[14:17]
	v_mfma_f32_16x16x32_bf16 v[54:57], v[158:161], v[192:195], v[54:57]
	v_mfma_f32_16x16x32_bf16 v[50:53], v[184:187], v[192:195], v[50:53]
	v_mfma_f32_16x16x32_bf16 v[34:37], v[184:187], v[200:203], v[34:37]
	v_mfma_f32_16x16x32_bf16 v[38:41], v[158:161], v[200:203], v[38:41]
	v_mfma_f32_16x16x32_bf16 v[22:25], v[158:161], v[208:211], v[22:25]
	v_mfma_f32_16x16x32_bf16 v[18:21], v[184:187], v[208:211], v[18:21]
	v_mfma_f32_16x16x32_bf16 v[2:5], v[184:187], v[216:219], v[2:5]
	v_mfma_f32_16x16x32_bf16 v[6:9], v[158:161], v[216:219], v[6:9]
	v_mfma_f32_16x16x32_bf16 v[54:57], v[180:183], v[196:199], v[54:57]
	v_mfma_f32_16x16x32_bf16 v[50:53], v[188:191], v[196:199], v[50:53]
	v_mfma_f32_16x16x32_bf16 v[34:37], v[188:191], v[204:207], v[34:37]
	v_mfma_f32_16x16x32_bf16 v[38:41], v[180:183], v[204:207], v[38:41]
	v_mfma_f32_16x16x32_bf16 v[22:25], v[180:183], v[212:215], v[22:25]
	v_mfma_f32_16x16x32_bf16 v[18:21], v[188:191], v[212:215], v[18:21]
	v_mfma_f32_16x16x32_bf16 v[2:5], v[188:191], v[220:223], v[2:5]
	v_mfma_f32_16x16x32_bf16 v[6:9], v[180:183], v[220:223], v[6:9]
	s_barrier
	s_setprio 0
	s_add_i32 s69, 16, 0x18000
	s_add_i32 s72, 16, 0x1c000
	v_add_u32_e32 v142, s69, v177
	v_add_u32_e32 v188, s72, v177
	ds_read_b128 v[130:133], v142
	ds_read_b128 v[134:137], v142 offset:1024
	ds_read_b128 v[138:141], v142 offset:2048
	ds_read_b128 v[142:145], v142 offset:3072
	ds_read_b128 v[158:161], v188
	ds_read_b128 v[180:183], v188 offset:1024
	ds_read_b128 v[184:187], v188 offset:2048
	ds_read_b128 v[188:191], v188 offset:3072
	s_add_u32 s10, s60, 0x40000
	s_addc_u32 s11, s61, 0
	s_mov_b32 m0, s55
	v_lshl_add_u64 v[242:243], s[10:11], 0, v[150:151]
	ds_read_b128 v[192:195], v179 offset:32768
	ds_read_b128 v[196:199], v179 offset:33792
	ds_read_b128 v[200:203], v179 offset:34816
	ds_read_b128 v[204:207], v179 offset:35840
	ds_read_b128 v[208:211], v179 offset:36864
	ds_read_b128 v[212:215], v179 offset:37888
	ds_read_b128 v[216:219], v179 offset:38912
	ds_read_b128 v[220:223], v179 offset:39936
	global_load_lds_dwordx4 v[242:243], off
	v_lshl_add_u64 v[242:243], s[10:11], 0, v[148:149]
	s_mov_b32 m0, s56
	s_nop 0
	global_load_lds_dwordx4 v[242:243], off
	s_waitcnt vmcnt(8)
	s_waitcnt lgkmcnt(0)
	s_setprio 1
	s_barrier
	v_mfma_f32_16x16x32_bf16 v[126:129], v[130:133], v[192:195], v[126:129]
	v_mfma_f32_16x16x32_bf16 v[122:125], v[138:141], v[192:195], v[122:125]
	v_mfma_f32_16x16x32_bf16 v[106:109], v[138:141], v[200:203], v[106:109]
	v_mfma_f32_16x16x32_bf16 v[110:113], v[130:133], v[200:203], v[110:113]
	v_mfma_f32_16x16x32_bf16 v[94:97], v[130:133], v[208:211], v[94:97]
	v_mfma_f32_16x16x32_bf16 v[90:93], v[138:141], v[208:211], v[90:93]
	v_mfma_f32_16x16x32_bf16 v[74:77], v[138:141], v[216:219], v[74:77]
	v_mfma_f32_16x16x32_bf16 v[78:81], v[130:133], v[216:219], v[78:81]
	v_mfma_f32_16x16x32_bf16 v[126:129], v[134:137], v[196:199], v[126:129]
	v_mfma_f32_16x16x32_bf16 v[122:125], v[142:145], v[196:199], v[122:125]
	v_mfma_f32_16x16x32_bf16 v[106:109], v[142:145], v[204:207], v[106:109]
	v_mfma_f32_16x16x32_bf16 v[110:113], v[134:137], v[204:207], v[110:113]
	v_mfma_f32_16x16x32_bf16 v[94:97], v[134:137], v[212:215], v[94:97]
	v_mfma_f32_16x16x32_bf16 v[90:93], v[142:145], v[212:215], v[90:93]
	v_mfma_f32_16x16x32_bf16 v[74:77], v[142:145], v[220:223], v[74:77]
	v_mfma_f32_16x16x32_bf16 v[78:81], v[134:137], v[220:223], v[78:81]
	v_mfma_f32_16x16x32_bf16 v[118:121], v[158:161], v[192:195], v[118:121]
	v_mfma_f32_16x16x32_bf16 v[114:117], v[184:187], v[192:195], v[114:117]
	v_mfma_f32_16x16x32_bf16 v[98:101], v[184:187], v[200:203], v[98:101]
	v_mfma_f32_16x16x32_bf16 v[102:105], v[158:161], v[200:203], v[102:105]
	v_mfma_f32_16x16x32_bf16 v[86:89], v[158:161], v[208:211], v[86:89]
	v_mfma_f32_16x16x32_bf16 v[82:85], v[184:187], v[208:211], v[82:85]
	v_mfma_f32_16x16x32_bf16 v[66:69], v[184:187], v[216:219], v[66:69]
	v_mfma_f32_16x16x32_bf16 v[70:73], v[158:161], v[216:219], v[70:73]
	v_mfma_f32_16x16x32_bf16 v[118:121], v[180:183], v[196:199], v[118:121]
	v_mfma_f32_16x16x32_bf16 v[114:117], v[188:191], v[196:199], v[114:117]
	v_mfma_f32_16x16x32_bf16 v[98:101], v[188:191], v[204:207], v[98:101]
	v_mfma_f32_16x16x32_bf16 v[102:105], v[180:183], v[204:207], v[102:105]
	v_mfma_f32_16x16x32_bf16 v[86:89], v[180:183], v[212:215], v[86:89]
	v_mfma_f32_16x16x32_bf16 v[82:85], v[188:191], v[212:215], v[82:85]
	v_mfma_f32_16x16x32_bf16 v[66:69], v[188:191], v[220:223], v[66:69]
	v_mfma_f32_16x16x32_bf16 v[70:73], v[180:183], v[220:223], v[70:73]
	s_barrier
; #define PG8_STAGE(bufoff, gbase, voff) do { _Pragma("unroll") for (int _i = 0; _i < 2; ++_i) \
;         __builtin_amdgcn_global_load_lds((const unsigned*)((const char*)(gbase) + (voff)[_i]), (PG8_LAS unsigned*)(lds + (bufoff) + ldsw + _i * 8192), 16, 0, 0); } while (0)
; #define PG8_LDA(dst, b, h) do { _Pragma("unroll") for (int m = 0; m < 4; ++m) _Pragma("unroll") for (int k = 0; k < 2; ++k) dst[m][k] = *(const PG8_LAS bf16x8*)(lds + PG8_SA(b, h) + aoff + m * 2048 + k * 1024); } while (0)
; #define PG8_MMA(ai, bj, At, Bt) do { __builtin_amdgcn_s_setprio(1); _Pragma("unroll") for (int m = 0; m < 4; ++m) _Pragma("unroll") for (int n = 0; n < 2; ++n) _Pragma("unroll") for (int k = 0; k < 2; ++k) \
;         acc[ai][bj][m][n] = __builtin_amdgcn_mfma_f32_16x16x32_bf16(Bt[n][k], At[m][k], acc[ai][bj][m][n], 0, 0, 0); __builtin_amdgcn_s_setprio(0); } while (0)
; #define PG8_WAIT_V(n) asm volatile("s_waitcnt vmcnt(" #n ")" ::: "memory")
; #define PG8_WAIT_L(n) asm volatile("s_waitcnt lgkmcnt(" #n ")" ::: "memory")
; #define PG8_BAR __builtin_amdgcn_s_barrier()
; #define PG8_SCHED __builtin_amdgcn_sched_barrier(0)
; template <class Epi, class Sched, bool ALIGN_EPI = false, bool SP2 = false>
; __device__ __forceinline__ void gemm_phase(PG8_LAS unsigned char* lds, const Gemm g, const Sched& S, const Epi& E) {
;     ...
;         for (int t = 0; t < nt; t += 2) {
;     ...
;             PG8_LDA(At, 1, 1); PG8_STAGE(PG8_SB(1, 0), b3, voffB); PG8_STAGE(PG8_SB(1, 1), b3 + hstep, voffB); PG8_STAGE(PG8_SA(1, 0), a3, voffA);
;             PG8_WAIT_V(8); PG8_WAIT_L(0); PG8_BAR; PG8_MMA(1, 0, At, B0); PG8_MMA(1, 1, At, B1); PG8_BAR; PG8_SCHED;
	s_setprio 0
	s_add_i32 s10, s69, s6
	v_lshl_add_u64 v[224:225], v[224:225], 0, s[28:29]
	s_mov_b32 m0, s10
	ds_read_b128 v[192:195], v179 offset:49152
	ds_read_b128 v[196:199], v179 offset:50176
	ds_read_b128 v[200:203], v179 offset:51200
	ds_read_b128 v[204:207], v179 offset:52224
	ds_read_b128 v[208:211], v179 offset:53248
	ds_read_b128 v[212:215], v179 offset:54272
	ds_read_b128 v[216:219], v179 offset:55296
	ds_read_b128 v[220:223], v179 offset:56320
	global_load_lds_dwordx4 v[224:225], off
	s_add_i32 m0, s10, 0x2000
	s_add_u32 s10, s58, 0x40080
	v_lshl_add_u64 v[224:225], v[226:227], 0, s[28:29]
	s_addc_u32 s11, s59, 0
	s_add_i32 s58, s72, s6
	global_load_lds_dwordx4 v[224:225], off
	v_lshl_add_u64 v[224:225], s[10:11], 0, v[0:1]
	s_mov_b32 m0, s58
	s_nop 0
	global_load_lds_dwordx4 v[224:225], off
	v_lshl_add_u64 v[224:225], s[10:11], 0, v[146:147]
	s_add_i32 m0, s58, 0x2000
	s_nop 0
	global_load_lds_dwordx4 v[224:225], off
	v_lshl_add_u64 v[224:225], v[238:239], 0, s[28:29]
	s_mov_b32 m0, s63
	s_nop 0
	global_load_lds_dwordx4 v[224:225], off
	v_lshl_add_u64 v[224:225], v[240:241], 0, s[28:29]
	s_mov_b32 m0, s64
	s_nop 0
	global_load_lds_dwordx4 v[224:225], off
	s_waitcnt vmcnt(8)
	s_waitcnt lgkmcnt(0)
	s_setprio 1
	s_barrier
	v_mfma_f32_16x16x32_bf16 v[62:65], v[130:133], v[192:195], v[62:65]
	v_mfma_f32_16x16x32_bf16 v[58:61], v[138:141], v[192:195], v[58:61]
	v_mfma_f32_16x16x32_bf16 v[42:45], v[138:141], v[200:203], v[42:45]
	v_mfma_f32_16x16x32_bf16 v[46:49], v[130:133], v[200:203], v[46:49]
	v_mfma_f32_16x16x32_bf16 v[30:33], v[130:133], v[208:211], v[30:33]
	v_mfma_f32_16x16x32_bf16 v[26:29], v[138:141], v[208:211], v[26:29]
	v_mfma_f32_16x16x32_bf16 v[10:13], v[138:141], v[216:219], v[10:13]
	v_mfma_f32_16x16x32_bf16 v[14:17], v[130:133], v[216:219], v[14:17]
	v_mfma_f32_16x16x32_bf16 v[62:65], v[134:137], v[196:199], v[62:65]
	v_mfma_f32_16x16x32_bf16 v[58:61], v[142:145], v[196:199], v[58:61]
	v_mfma_f32_16x16x32_bf16 v[42:45], v[142:145], v[204:207], v[42:45]
	v_mfma_f32_16x16x32_bf16 v[46:49], v[134:137], v[204:207], v[46:49]
	v_mfma_f32_16x16x32_bf16 v[30:33], v[134:137], v[212:215], v[30:33]
	v_mfma_f32_16x16x32_bf16 v[26:29], v[142:145], v[212:215], v[26:29]
	v_mfma_f32_16x16x32_bf16 v[10:13], v[142:145], v[220:223], v[10:13]
	v_mfma_f32_16x16x32_bf16 v[14:17], v[134:137], v[220:223], v[14:17]
	v_mfma_f32_16x16x32_bf16 v[54:57], v[158:161], v[192:195], v[54:57]
	v_mfma_f32_16x16x32_bf16 v[50:53], v[184:187], v[192:195], v[50:53]
	v_mfma_f32_16x16x32_bf16 v[34:37], v[184:187], v[200:203], v[34:37]
	v_mfma_f32_16x16x32_bf16 v[38:41], v[158:161], v[200:203], v[38:41]
	v_mfma_f32_16x16x32_bf16 v[22:25], v[158:161], v[208:211], v[22:25]
	v_mfma_f32_16x16x32_bf16 v[18:21], v[184:187], v[208:211], v[18:21]
	v_mfma_f32_16x16x32_bf16 v[2:5], v[184:187], v[216:219], v[2:5]
	v_mfma_f32_16x16x32_bf16 v[6:9], v[158:161], v[216:219], v[6:9]
	v_mfma_f32_16x16x32_bf16 v[54:57], v[180:183], v[196:199], v[54:57]
	v_mfma_f32_16x16x32_bf16 v[50:53], v[188:191], v[196:199], v[50:53]
	v_mfma_f32_16x16x32_bf16 v[34:37], v[188:191], v[204:207], v[34:37]
	v_mfma_f32_16x16x32_bf16 v[38:41], v[180:183], v[204:207], v[38:41]
	v_mfma_f32_16x16x32_bf16 v[22:25], v[180:183], v[212:215], v[22:25]
	v_mfma_f32_16x16x32_bf16 v[18:21], v[188:191], v[212:215], v[18:21]
	v_mfma_f32_16x16x32_bf16 v[2:5], v[188:191], v[220:223], v[2:5]
	v_mfma_f32_16x16x32_bf16 v[6:9], v[180:183], v[220:223], v[6:9]
	s_barrier
	s_setprio 0
	s_add_i32 s68, s68, 2
	s_add_u32 s66, s66, 0x100
	s_addc_u32 s67, s67, 0
	s_add_u32 s50, s50, 0x100
	s_addc_u32 s51, s51, 0
	s_cmp_gt_u32 s68, 13
	s_cbranch_scc0 .LBB0_1033
	s_and_b64 vcc, exec, s[24:25]
	s_cbranch_vccz .LBB0_1036
	s_barrier

; #define PG8_STAGE(bufoff, gbase, voff) do { _Pragma("unroll") for (int _i = 0; _i < 2; ++_i) \
;         __builtin_amdgcn_global_load_lds((const unsigned*)((const char*)(gbase) + (voff)[_i]), (PG8_LAS unsigned*)(lds + (bufoff) + ldsw + _i * 8192), 16, 0, 0); } while (0)
; #define PG8_LDA(dst, b, h) do { _Pragma("unroll") for (int m = 0; m < 4; ++m) _Pragma("unroll") for (int k = 0; k < 2; ++k) dst[m][k] = *(const PG8_LAS bf16x8*)(lds + PG8_SA(b, h) + aoff + m * 2048 + k * 1024); } while (0)
; #define PG8_LDB(dst, b, h) do { _Pragma("unroll") for (int n = 0; n < 2; ++n) _Pragma("unroll") for (int k = 0; k < 2; ++k) dst[n][k] = *(const PG8_LAS bf16x8*)(lds + PG8_SB(b, h) + boff + n * 2048 + k * 1024); } while (0)
; #define PG8_MMA(ai, bj, At, Bt) do { __builtin_amdgcn_s_setprio(1); _Pragma("unroll") for (int m = 0; m < 4; ++m) _Pragma("unroll") for (int n = 0; n < 2; ++n) _Pragma("unroll") for (int k = 0; k < 2; ++k) \
;         acc[ai][bj][m][n] = __builtin_amdgcn_mfma_f32_16x16x32_bf16(Bt[n][k], At[m][k], acc[ai][bj][m][n], 0, 0, 0); __builtin_amdgcn_s_setprio(0); } while (0)
; #define PG8_WAIT_V(n) asm volatile("s_waitcnt vmcnt(" #n ")" ::: "memory")
; #define PG8_WAIT_L(n) asm volatile("s_waitcnt lgkmcnt(" #n ")" ::: "memory")
; #define PG8_BAR __builtin_amdgcn_s_barrier()
; #define PG8_SCHED __builtin_amdgcn_sched_barrier(0)
; template <class Epi, class Sched, bool ALIGN_EPI = false, bool SP2 = false>
; __device__ __forceinline__ void gemm_phase(PG8_LAS unsigned char* lds, const Gemm g, const Sched& S, const Epi& E) {
;     ...
;             const bool last = (t == nt - 2);
;             const char* a1 = cA + (size_t)(t + 1) * kstep;
;             const char* a2 = last ? nA : cA + (size_t)(t + 2) * kstep; const char* b2 = last ? nB : cB + (size_t)(t + 2) * kstep;
;             const char* a3 = a2 + kstep; const char* b3 = b2 + kstep;
;             if (last && has_next) S.a_ready(nxt);
;             if constexpr (SP2) {
;             PG8_LDB(B0, 0, 0); PG8_LDB(B1, 0, 1); PG8_SCHED; PG8_LDA(At, 0, 0); PG8_STAGE(PG8_SA(1, 1), a1 + hstep, voffA);
;             PG8_WAIT_V(8); PG8_WAIT_L(0); PG8_BAR; PG8_MMA(0, 0, At, B0); PG8_MMA(0, 1, At, B1); PG8_BAR; PG8_SCHED;
;             PG8_LDA(At, 0, 1); PG8_STAGE(PG8_SB(0, 0), b2, voffB); PG8_STAGE(PG8_SB(0, 1), b2 + hstep, voffB); PG8_STAGE(PG8_SA(0, 0), a2, voffA);
.LBB0_1208:
	s_add_u32 s42, s24, 0x100
	s_addc_u32 s43, s25, 0
	s_add_i32 s10, 16, 0x10000
	s_cmp_eq_u32 s73, 40
	s_cselect_b32 s69, s23, s43
	s_cselect_b32 s68, s22, s42
	s_cselect_b32 s45, s27, s72
	s_cselect_b32 s44, s26, s35
	s_add_i32 vcc_lo, 16, 0x14000
	v_add_u32_e32 v78, s10, v197
	v_add_u32_e32 v94, vcc_lo, v197
	ds_read_b128 v[58:61], v78
	ds_read_b128 v[62:65], v78 offset:1024
	ds_read_b128 v[74:77], v78 offset:2048
	ds_read_b128 v[78:81], v78 offset:3072
	ds_read_b128 v[82:85], v94
	ds_read_b128 v[86:89], v94 offset:1024
	ds_read_b128 v[90:93], v94 offset:2048
	ds_read_b128 v[94:97], v94 offset:3072
	v_lshl_add_u64 v[194:195], s[24:25], 0, v[184:185]
	s_add_i32 m0, s95, 0xc000
	ds_read_b128 v[186:189], v199
	ds_read_b128 v[190:193], v199 offset:1024
	ds_read_b128 v[200:203], v199 offset:2048
	ds_read_b128 v[204:207], v199 offset:3072
	ds_read_b128 v[208:211], v199 offset:4096
	ds_read_b128 v[212:215], v199 offset:5120
	ds_read_b128 v[216:219], v199 offset:6144
	ds_read_b128 v[220:223], v199 offset:7168
	global_load_lds_dwordx4 v[194:195], off
	v_lshl_add_u64 v[194:195], s[24:25], 0, v[182:183]
	s_add_i32 m0, s95, 0xe000
	s_nop 0
	global_load_lds_dwordx4 v[194:195], off
	s_waitcnt vmcnt(8)
	s_waitcnt lgkmcnt(0)
	s_setprio 1
	s_barrier
	v_mfma_f32_16x16x32_bf16 v[158:161], v[58:61], v[186:189], v[158:161]
	v_mfma_f32_16x16x32_bf16 v[154:157], v[74:77], v[186:189], v[154:157]
	v_mfma_f32_16x16x32_bf16 v[138:141], v[74:77], v[200:203], v[138:141]
	v_mfma_f32_16x16x32_bf16 v[142:145], v[58:61], v[200:203], v[142:145]
	v_mfma_f32_16x16x32_bf16 v[126:129], v[58:61], v[208:211], v[126:129]
	v_mfma_f32_16x16x32_bf16 v[122:125], v[74:77], v[208:211], v[122:125]
	v_mfma_f32_16x16x32_bf16 v[106:109], v[74:77], v[216:219], v[106:109]
	v_mfma_f32_16x16x32_bf16 v[110:113], v[58:61], v[216:219], v[110:113]
	v_mfma_f32_16x16x32_bf16 v[158:161], v[62:65], v[190:193], v[158:161]
	v_mfma_f32_16x16x32_bf16 v[154:157], v[78:81], v[190:193], v[154:157]
	v_mfma_f32_16x16x32_bf16 v[138:141], v[78:81], v[204:207], v[138:141]
	v_mfma_f32_16x16x32_bf16 v[142:145], v[62:65], v[204:207], v[142:145]
	v_mfma_f32_16x16x32_bf16 v[126:129], v[62:65], v[212:215], v[126:129]
	v_mfma_f32_16x16x32_bf16 v[122:125], v[78:81], v[212:215], v[122:125]
	v_mfma_f32_16x16x32_bf16 v[106:109], v[78:81], v[220:223], v[106:109]
	v_mfma_f32_16x16x32_bf16 v[110:113], v[62:65], v[220:223], v[110:113]
	v_mfma_f32_16x16x32_bf16 v[150:153], v[82:85], v[186:189], v[150:153]
	v_mfma_f32_16x16x32_bf16 v[146:149], v[90:93], v[186:189], v[146:149]
	v_mfma_f32_16x16x32_bf16 v[130:133], v[90:93], v[200:203], v[130:133]
	v_mfma_f32_16x16x32_bf16 v[134:137], v[82:85], v[200:203], v[134:137]
	v_mfma_f32_16x16x32_bf16 v[118:121], v[82:85], v[208:211], v[118:121]
	v_mfma_f32_16x16x32_bf16 v[114:117], v[90:93], v[208:211], v[114:117]
	v_mfma_f32_16x16x32_bf16 v[98:101], v[90:93], v[216:219], v[98:101]
	v_mfma_f32_16x16x32_bf16 v[102:105], v[82:85], v[216:219], v[102:105]
	v_mfma_f32_16x16x32_bf16 v[150:153], v[86:89], v[190:193], v[150:153]
	v_mfma_f32_16x16x32_bf16 v[146:149], v[94:97], v[190:193], v[146:149]
	v_mfma_f32_16x16x32_bf16 v[130:133], v[94:97], v[204:207], v[130:133]
	v_mfma_f32_16x16x32_bf16 v[134:137], v[86:89], v[204:207], v[134:137]
	v_mfma_f32_16x16x32_bf16 v[118:121], v[86:89], v[212:215], v[118:121]
	v_mfma_f32_16x16x32_bf16 v[114:117], v[94:97], v[212:215], v[114:117]
	v_mfma_f32_16x16x32_bf16 v[98:101], v[94:97], v[220:223], v[98:101]
	v_mfma_f32_16x16x32_bf16 v[102:105], v[86:89], v[220:223], v[102:105]
	s_barrier
	s_setprio 0
	s_add_i32 s10, s10, s94
	v_lshl_add_u64 v[194:195], s[44:45], 0, v[0:1]
	s_mov_b32 m0, s10
	ds_read_b128 v[186:189], v199 offset:16384
	ds_read_b128 v[190:193], v199 offset:17408
	ds_read_b128 v[200:203], v199 offset:18432
	ds_read_b128 v[204:207], v199 offset:19456
	ds_read_b128 v[208:211], v199 offset:20480
	ds_read_b128 v[212:215], v199 offset:21504
	ds_read_b128 v[216:219], v199 offset:22528
	ds_read_b128 v[220:223], v199 offset:23552
	global_load_lds_dwordx4 v[194:195], off
	s_add_i32 m0, s10, 0x2000
	s_add_u32 s10, s44, 0xb0000
	v_lshl_add_u64 v[224:225], s[44:45], 0, v[180:181]
	s_addc_u32 s11, s45, 0
	s_add_i32 s24, vcc_lo, s94
	global_load_lds_dwordx4 v[224:225], off
	v_lshl_add_u64 v[226:227], s[10:11], 0, v[0:1]
	s_mov_b32 m0, s24
	v_lshl_add_u64 v[238:239], s[68:69], 0, v[178:179]
	global_load_lds_dwordx4 v[226:227], off
	v_lshl_add_u64 v[226:227], s[10:11], 0, v[180:181]
	s_add_i32 m0, s24, 0x2000
	s_nop 0
	global_load_lds_dwordx4 v[226:227], off
	v_lshl_add_u64 v[226:227], s[68:69], 0, v[176:177]
	s_mov_b32 m0, s95
	s_nop 0
	global_load_lds_dwordx4 v[226:227], off
	s_mov_b32 m0, s2
	s_nop 0
	global_load_lds_dwordx4 v[238:239], off
	s_waitcnt vmcnt(8)
	s_waitcnt lgkmcnt(0)
	s_setprio 1
	s_barrier
; #define PG8_STAGE(bufoff, gbase, voff) do { _Pragma("unroll") for (int _i = 0; _i < 2; ++_i) \
;         __builtin_amdgcn_global_load_lds((const unsigned*)((const char*)(gbase) + (voff)[_i]), (PG8_LAS unsigned*)(lds + (bufoff) + ldsw + _i * 8192), 16, 0, 0); } while (0)
; #define PG8_LDA(dst, b, h) do { _Pragma("unroll") for (int m = 0; m < 4; ++m) _Pragma("unroll") for (int k = 0; k < 2; ++k) dst[m][k] = *(const PG8_LAS bf16x8*)(lds + PG8_SA(b, h) + aoff + m * 2048 + k * 1024); } while (0)
; #define PG8_LDB(dst, b, h) do { _Pragma("unroll") for (int n = 0; n < 2; ++n) _Pragma("unroll") for (int k = 0; k < 2; ++k) dst[n][k] = *(const PG8_LAS bf16x8*)(lds + PG8_SB(b, h) + boff + n * 2048 + k * 1024); } while (0)
; #define PG8_MMA(ai, bj, At, Bt) do { __builtin_amdgcn_s_setprio(1); _Pragma("unroll") for (int m = 0; m < 4; ++m) _Pragma("unroll") for (int n = 0; n < 2; ++n) _Pragma("unroll") for (int k = 0; k < 2; ++k) \
;         acc[ai][bj][m][n] = __builtin_amdgcn_mfma_f32_16x16x32_bf16(Bt[n][k], At[m][k], acc[ai][bj][m][n], 0, 0, 0); __builtin_amdgcn_s_setprio(0); } while (0)
; #define PG8_WAIT_V(n) asm volatile("s_waitcnt vmcnt(" #n ")" ::: "memory")
; #define PG8_WAIT_L(n) asm volatile("s_waitcnt lgkmcnt(" #n ")" ::: "memory")
; #define PG8_BAR __builtin_amdgcn_s_barrier()
; #define PG8_SCHED __builtin_amdgcn_sched_barrier(0)
; template <class Epi, class Sched, bool ALIGN_EPI = false, bool SP2 = false>
; __device__ __forceinline__ void gemm_phase(PG8_LAS unsigned char* lds, const Gemm g, const Sched& S, const Epi& E) {
;     ...
;             PG8_WAIT_V(8); PG8_WAIT_L(0); PG8_BAR; PG8_MMA(1, 0, At, B0); PG8_MMA(1, 1, At, B1); PG8_BAR; PG8_SCHED;
;             PG8_LDB(B0, 1, 0); PG8_LDB(B1, 1, 1); PG8_SCHED; PG8_LDA(At, 1, 0); PG8_STAGE(PG8_SA(0, 1), a2 + hstep, voffA);
;             PG8_WAIT_V(8); PG8_WAIT_L(0); PG8_BAR; PG8_MMA(0, 0, At, B0); PG8_MMA(0, 1, At, B1); PG8_BAR; PG8_SCHED;
	v_mfma_f32_16x16x32_bf16 v[70:73], v[58:61], v[186:189], v[70:73]
	v_mfma_f32_16x16x32_bf16 v[66:69], v[74:77], v[186:189], v[66:69]
	v_mfma_f32_16x16x32_bf16 v[42:45], v[74:77], v[200:203], v[42:45]
	v_mfma_f32_16x16x32_bf16 v[46:49], v[58:61], v[200:203], v[46:49]
	v_mfma_f32_16x16x32_bf16 v[30:33], v[58:61], v[208:211], v[30:33]
	v_mfma_f32_16x16x32_bf16 v[26:29], v[74:77], v[208:211], v[26:29]
	v_mfma_f32_16x16x32_bf16 v[10:13], v[74:77], v[216:219], v[10:13]
	v_mfma_f32_16x16x32_bf16 v[14:17], v[58:61], v[216:219], v[14:17]
	v_mfma_f32_16x16x32_bf16 v[70:73], v[62:65], v[190:193], v[70:73]
	v_mfma_f32_16x16x32_bf16 v[66:69], v[78:81], v[190:193], v[66:69]
	v_mfma_f32_16x16x32_bf16 v[42:45], v[78:81], v[204:207], v[42:45]
	v_mfma_f32_16x16x32_bf16 v[46:49], v[62:65], v[204:207], v[46:49]
	v_mfma_f32_16x16x32_bf16 v[30:33], v[62:65], v[212:215], v[30:33]
	v_mfma_f32_16x16x32_bf16 v[26:29], v[78:81], v[212:215], v[26:29]
	v_mfma_f32_16x16x32_bf16 v[10:13], v[78:81], v[220:223], v[10:13]
	v_mfma_f32_16x16x32_bf16 v[14:17], v[62:65], v[220:223], v[14:17]
	v_mfma_f32_16x16x32_bf16 v[54:57], v[82:85], v[186:189], v[54:57]
	v_mfma_f32_16x16x32_bf16 v[50:53], v[90:93], v[186:189], v[50:53]
	v_mfma_f32_16x16x32_bf16 v[34:37], v[90:93], v[200:203], v[34:37]
	v_mfma_f32_16x16x32_bf16 v[38:41], v[82:85], v[200:203], v[38:41]
	v_mfma_f32_16x16x32_bf16 v[22:25], v[82:85], v[208:211], v[22:25]
	v_mfma_f32_16x16x32_bf16 v[18:21], v[90:93], v[208:211], v[18:21]
	v_mfma_f32_16x16x32_bf16 v[2:5], v[90:93], v[216:219], v[2:5]
	v_mfma_f32_16x16x32_bf16 v[6:9], v[82:85], v[216:219], v[6:9]
	v_mfma_f32_16x16x32_bf16 v[54:57], v[86:89], v[190:193], v[54:57]
	v_mfma_f32_16x16x32_bf16 v[50:53], v[94:97], v[190:193], v[50:53]
	v_mfma_f32_16x16x32_bf16 v[34:37], v[94:97], v[204:207], v[34:37]
	v_mfma_f32_16x16x32_bf16 v[38:41], v[86:89], v[204:207], v[38:41]
	v_mfma_f32_16x16x32_bf16 v[22:25], v[86:89], v[212:215], v[22:25]
	v_mfma_f32_16x16x32_bf16 v[18:21], v[94:97], v[212:215], v[18:21]
	v_mfma_f32_16x16x32_bf16 v[2:5], v[94:97], v[220:223], v[2:5]
	v_mfma_f32_16x16x32_bf16 v[6:9], v[86:89], v[220:223], v[6:9]
	s_barrier
	s_setprio 0
	s_add_i32 s24, 16, 0x18000
	s_add_i32 s25, 16, 0x1c000
	v_add_u32_e32 v78, s24, v197
	v_add_u32_e32 v94, s25, v197
	ds_read_b128 v[58:61], v78
	ds_read_b128 v[62:65], v78 offset:1024
	ds_read_b128 v[74:77], v78 offset:2048
	ds_read_b128 v[78:81], v78 offset:3072
	ds_read_b128 v[82:85], v94
	ds_read_b128 v[86:89], v94 offset:1024
	ds_read_b128 v[90:93], v94 offset:2048
	ds_read_b128 v[94:97], v94 offset:3072
	s_add_u32 s10, s68, 0xb0000
	s_addc_u32 s11, s69, 0
	s_mov_b32 m0, s3
	v_lshl_add_u64 v[240:241], s[10:11], 0, v[176:177]
	ds_read_b128 v[186:189], v199 offset:32768
	ds_read_b128 v[190:193], v199 offset:33792
	ds_read_b128 v[200:203], v199 offset:34816
	ds_read_b128 v[204:207], v199 offset:35840
	ds_read_b128 v[208:211], v199 offset:36864
	ds_read_b128 v[212:215], v199 offset:37888
	ds_read_b128 v[216:219], v199 offset:38912
	ds_read_b128 v[220:223], v199 offset:39936
	global_load_lds_dwordx4 v[240:241], off
	v_lshl_add_u64 v[240:241], s[10:11], 0, v[178:179]
	s_mov_b32 m0, s96
	s_nop 0
	global_load_lds_dwordx4 v[240:241], off
	s_waitcnt vmcnt(8)
	s_waitcnt lgkmcnt(0)
	s_setprio 1
	s_barrier
	v_mfma_f32_16x16x32_bf16 v[158:161], v[58:61], v[186:189], v[158:161]
	v_mfma_f32_16x16x32_bf16 v[154:157], v[74:77], v[186:189], v[154:157]
	v_mfma_f32_16x16x32_bf16 v[138:141], v[74:77], v[200:203], v[138:141]
	v_mfma_f32_16x16x32_bf16 v[142:145], v[58:61], v[200:203], v[142:145]
	v_mfma_f32_16x16x32_bf16 v[126:129], v[58:61], v[208:211], v[126:129]
	v_mfma_f32_16x16x32_bf16 v[122:125], v[74:77], v[208:211], v[122:125]
	v_mfma_f32_16x16x32_bf16 v[106:109], v[74:77], v[216:219], v[106:109]
	v_mfma_f32_16x16x32_bf16 v[110:113], v[58:61], v[216:219], v[110:113]
	v_mfma_f32_16x16x32_bf16 v[158:161], v[62:65], v[190:193], v[158:161]
	v_mfma_f32_16x16x32_bf16 v[154:157], v[78:81], v[190:193], v[154:157]
	v_mfma_f32_16x16x32_bf16 v[138:141], v[78:81], v[204:207], v[138:141]
	v_mfma_f32_16x16x32_bf16 v[142:145], v[62:65], v[204:207], v[142:145]
	v_mfma_f32_16x16x32_bf16 v[126:129], v[62:65], v[212:215], v[126:129]
	v_mfma_f32_16x16x32_bf16 v[122:125], v[78:81], v[212:215], v[122:125]
	v_mfma_f32_16x16x32_bf16 v[106:109], v[78:81], v[220:223], v[106:109]
	v_mfma_f32_16x16x32_bf16 v[110:113], v[62:65], v[220:223], v[110:113]
	v_mfma_f32_16x16x32_bf16 v[150:153], v[82:85], v[186:189], v[150:153]
	v_mfma_f32_16x16x32_bf16 v[146:149], v[90:93], v[186:189], v[146:149]
	v_mfma_f32_16x16x32_bf16 v[130:133], v[90:93], v[200:203], v[130:133]
	v_mfma_f32_16x16x32_bf16 v[134:137], v[82:85], v[200:203], v[134:137]
	v_mfma_f32_16x16x32_bf16 v[118:121], v[82:85], v[208:211], v[118:121]
	v_mfma_f32_16x16x32_bf16 v[114:117], v[90:93], v[208:211], v[114:117]
	v_mfma_f32_16x16x32_bf16 v[98:101], v[90:93], v[216:219], v[98:101]
	v_mfma_f32_16x16x32_bf16 v[102:105], v[82:85], v[216:219], v[102:105]
	v_mfma_f32_16x16x32_bf16 v[150:153], v[86:89], v[190:193], v[150:153]
	v_mfma_f32_16x16x32_bf16 v[146:149], v[94:97], v[190:193], v[146:149]
	v_mfma_f32_16x16x32_bf16 v[130:133], v[94:97], v[204:207], v[130:133]
	v_mfma_f32_16x16x32_bf16 v[134:137], v[86:89], v[204:207], v[134:137]
	v_mfma_f32_16x16x32_bf16 v[118:121], v[86:89], v[212:215], v[118:121]
	v_mfma_f32_16x16x32_bf16 v[114:117], v[94:97], v[212:215], v[114:117]
	v_mfma_f32_16x16x32_bf16 v[98:101], v[94:97], v[220:223], v[98:101]
	v_mfma_f32_16x16x32_bf16 v[102:105], v[86:89], v[220:223], v[102:105]
	s_barrier
; #define PG8_STAGE(bufoff, gbase, voff) do { _Pragma("unroll") for (int _i = 0; _i < 2; ++_i) \
;         __builtin_amdgcn_global_load_lds((const unsigned*)((const char*)(gbase) + (voff)[_i]), (PG8_LAS unsigned*)(lds + (bufoff) + ldsw + _i * 8192), 16, 0, 0); } while (0)
; #define PG8_LDA(dst, b, h) do { _Pragma("unroll") for (int m = 0; m < 4; ++m) _Pragma("unroll") for (int k = 0; k < 2; ++k) dst[m][k] = *(const PG8_LAS bf16x8*)(lds + PG8_SA(b, h) + aoff + m * 2048 + k * 1024); } while (0)
; #define PG8_MMA(ai, bj, At, Bt) do { __builtin_amdgcn_s_setprio(1); _Pragma("unroll") for (int m = 0; m < 4; ++m) _Pragma("unroll") for (int n = 0; n < 2; ++n) _Pragma("unroll") for (int k = 0; k < 2; ++k) \
;         acc[ai][bj][m][n] = __builtin_amdgcn_mfma_f32_16x16x32_bf16(Bt[n][k], At[m][k], acc[ai][bj][m][n], 0, 0, 0); __builtin_amdgcn_s_setprio(0); } while (0)
; #define PG8_WAIT_V(n) asm volatile("s_waitcnt vmcnt(" #n ")" ::: "memory")
; #define PG8_WAIT_L(n) asm volatile("s_waitcnt lgkmcnt(" #n ")" ::: "memory")
; #define PG8_BAR __builtin_amdgcn_s_barrier()
; #define PG8_SCHED __builtin_amdgcn_sched_barrier(0)
; template <class Epi, class Sched, bool ALIGN_EPI = false, bool SP2 = false>
; __device__ __forceinline__ void gemm_phase(PG8_LAS unsigned char* lds, const Gemm g, const Sched& S, const Epi& E) {
;     ...
;         for (int t = 0; t < nt; t += 2) {
;     ...
;             PG8_LDA(At, 1, 1); PG8_STAGE(PG8_SB(1, 0), b3, voffB); PG8_STAGE(PG8_SB(1, 1), b3 + hstep, voffB); PG8_STAGE(PG8_SA(1, 0), a3, voffA);
;             PG8_WAIT_V(8); PG8_WAIT_L(0); PG8_BAR; PG8_MMA(1, 0, At, B0); PG8_MMA(1, 1, At, B1); PG8_BAR; PG8_SCHED;
	s_setprio 0
	s_add_i32 s10, s24, s94
	v_lshl_add_u64 v[194:195], v[194:195], 0, s[28:29]
	s_mov_b32 m0, s10
	ds_read_b128 v[186:189], v199 offset:49152
	ds_read_b128 v[190:193], v199 offset:50176
	ds_read_b128 v[200:203], v199 offset:51200
	ds_read_b128 v[204:207], v199 offset:52224
	ds_read_b128 v[208:211], v199 offset:53248
	ds_read_b128 v[212:215], v199 offset:54272
	ds_read_b128 v[216:219], v199 offset:55296
	ds_read_b128 v[220:223], v199 offset:56320
	global_load_lds_dwordx4 v[194:195], off
	s_add_i32 m0, s10, 0x2000
	s_add_u32 s10, s44, 0xb0080
	v_lshl_add_u64 v[194:195], v[224:225], 0, s[28:29]
	s_addc_u32 s11, s45, 0
	s_add_i32 s24, s25, s94
	global_load_lds_dwordx4 v[194:195], off
	v_lshl_add_u64 v[194:195], s[10:11], 0, v[0:1]
	s_mov_b32 m0, s24
	s_nop 0
	global_load_lds_dwordx4 v[194:195], off
	v_lshl_add_u64 v[194:195], s[10:11], 0, v[180:181]
	s_add_i32 m0, s24, 0x2000
	s_nop 0
	global_load_lds_dwordx4 v[194:195], off
	v_lshl_add_u64 v[194:195], v[226:227], 0, s[28:29]
	s_mov_b32 m0, s57
	s_nop 0
	global_load_lds_dwordx4 v[194:195], off
	v_lshl_add_u64 v[194:195], v[238:239], 0, s[28:29]
	s_mov_b32 m0, s78
	s_nop 0
	global_load_lds_dwordx4 v[194:195], off
	s_waitcnt vmcnt(8)
	s_waitcnt lgkmcnt(0)
	s_setprio 1
	s_barrier
	v_mfma_f32_16x16x32_bf16 v[70:73], v[58:61], v[186:189], v[70:73]
	v_mfma_f32_16x16x32_bf16 v[66:69], v[74:77], v[186:189], v[66:69]
	v_mfma_f32_16x16x32_bf16 v[42:45], v[74:77], v[200:203], v[42:45]
	v_mfma_f32_16x16x32_bf16 v[46:49], v[58:61], v[200:203], v[46:49]
	v_mfma_f32_16x16x32_bf16 v[30:33], v[58:61], v[208:211], v[30:33]
	v_mfma_f32_16x16x32_bf16 v[26:29], v[74:77], v[208:211], v[26:29]
	v_mfma_f32_16x16x32_bf16 v[10:13], v[74:77], v[216:219], v[10:13]
	v_mfma_f32_16x16x32_bf16 v[14:17], v[58:61], v[216:219], v[14:17]
	v_mfma_f32_16x16x32_bf16 v[70:73], v[62:65], v[190:193], v[70:73]
	v_mfma_f32_16x16x32_bf16 v[66:69], v[78:81], v[190:193], v[66:69]
	v_mfma_f32_16x16x32_bf16 v[42:45], v[78:81], v[204:207], v[42:45]
	v_mfma_f32_16x16x32_bf16 v[46:49], v[62:65], v[204:207], v[46:49]
	v_mfma_f32_16x16x32_bf16 v[30:33], v[62:65], v[212:215], v[30:33]
	v_mfma_f32_16x16x32_bf16 v[26:29], v[78:81], v[212:215], v[26:29]
	v_mfma_f32_16x16x32_bf16 v[10:13], v[78:81], v[220:223], v[10:13]
	v_mfma_f32_16x16x32_bf16 v[14:17], v[62:65], v[220:223], v[14:17]
	v_mfma_f32_16x16x32_bf16 v[54:57], v[82:85], v[186:189], v[54:57]
	v_mfma_f32_16x16x32_bf16 v[50:53], v[90:93], v[186:189], v[50:53]
	v_mfma_f32_16x16x32_bf16 v[34:37], v[90:93], v[200:203], v[34:37]
	v_mfma_f32_16x16x32_bf16 v[38:41], v[82:85], v[200:203], v[38:41]
	v_mfma_f32_16x16x32_bf16 v[22:25], v[82:85], v[208:211], v[22:25]
	v_mfma_f32_16x16x32_bf16 v[18:21], v[90:93], v[208:211], v[18:21]
	v_mfma_f32_16x16x32_bf16 v[2:5], v[90:93], v[216:219], v[2:5]
	v_mfma_f32_16x16x32_bf16 v[6:9], v[82:85], v[216:219], v[6:9]
	v_mfma_f32_16x16x32_bf16 v[54:57], v[86:89], v[190:193], v[54:57]
	v_mfma_f32_16x16x32_bf16 v[50:53], v[94:97], v[190:193], v[50:53]
	v_mfma_f32_16x16x32_bf16 v[34:37], v[94:97], v[204:207], v[34:37]
	v_mfma_f32_16x16x32_bf16 v[38:41], v[86:89], v[204:207], v[38:41]
	v_mfma_f32_16x16x32_bf16 v[22:25], v[86:89], v[212:215], v[22:25]
	v_mfma_f32_16x16x32_bf16 v[18:21], v[94:97], v[212:215], v[18:21]
	v_mfma_f32_16x16x32_bf16 v[2:5], v[94:97], v[220:223], v[2:5]
	v_mfma_f32_16x16x32_bf16 v[6:9], v[86:89], v[220:223], v[6:9]
	s_barrier
	s_setprio 0
	s_add_i32 s73, s73, 2
	s_add_u32 s35, s35, 0x100
	s_addc_u32 s72, s72, 0
	s_cmp_gt_u32 s73, 41
	s_mov_b64 s[24:25], s[42:43]
	s_cbranch_scc0 .LBB0_1208
	s_and_b64 vcc, exec, s[20:21]
	s_cbranch_vccz .LBB0_1211
	s_barrier

; #define PG8_STAGE(bufoff, gbase, voff) do { _Pragma("unroll") for (int _i = 0; _i < 2; ++_i) \
;         __builtin_amdgcn_global_load_lds((const unsigned*)((const char*)(gbase) + (voff)[_i]), (PG8_LAS unsigned*)(lds + (bufoff) + ldsw + _i * 8192), 16, 0, 0); } while (0)
; #define PG8_LDA(dst, b, h) do { _Pragma("unroll") for (int m = 0; m < 4; ++m) _Pragma("unroll") for (int k = 0; k < 2; ++k) dst[m][k] = *(const PG8_LAS bf16x8*)(lds + PG8_SA(b, h) + aoff + m * 2048 + k * 1024); } while (0)
; #define PG8_LDB(dst, b, h) do { _Pragma("unroll") for (int n = 0; n < 2; ++n) _Pragma("unroll") for (int k = 0; k < 2; ++k) dst[n][k] = *(const PG8_LAS bf16x8*)(lds + PG8_SB(b, h) + boff + n * 2048 + k * 1024); } while (0)
; #define PG8_MMA(ai, bj, At, Bt) do { __builtin_amdgcn_s_setprio(1); _Pragma("unroll") for (int m = 0; m < 4; ++m) _Pragma("unroll") for (int n = 0; n < 2; ++n) _Pragma("unroll") for (int k = 0; k < 2; ++k) \
;         acc[ai][bj][m][n] = __builtin_amdgcn_mfma_f32_16x16x32_bf16(Bt[n][k], At[m][k], acc[ai][bj][m][n], 0, 0, 0); __builtin_amdgcn_s_setprio(0); } while (0)
; #define PG8_WAIT_V(n) asm volatile("s_waitcnt vmcnt(" #n ")" ::: "memory")
; #define PG8_WAIT_L(n) asm volatile("s_waitcnt lgkmcnt(" #n ")" ::: "memory")
; #define PG8_BAR __builtin_amdgcn_s_barrier()
; #define PG8_SCHED __builtin_amdgcn_sched_barrier(0)
; template <class Epi, class Sched, bool ALIGN_EPI = false, bool SP2 = false>
; __device__ __forceinline__ void gemm_phase(PG8_LAS unsigned char* lds, const Gemm g, const Sched& S, const Epi& E) {
;     ...
;             const bool last = (t == nt - 2);
;             const char* a1 = cA + (size_t)(t + 1) * kstep;
;             const char* a2 = last ? nA : cA + (size_t)(t + 2) * kstep; const char* b2 = last ? nB : cB + (size_t)(t + 2) * kstep;
;             const char* a3 = a2 + kstep; const char* b3 = b2 + kstep;
;             if (last && has_next) S.a_ready(nxt);
;             if constexpr (SP2) {
;             PG8_LDB(B0, 0, 0); PG8_LDB(B1, 0, 1); PG8_SCHED; PG8_LDA(At, 0, 0); PG8_STAGE(PG8_SA(1, 1), a1 + hstep, voffA);
;             PG8_WAIT_V(8); PG8_WAIT_L(0); PG8_BAR; PG8_MMA(0, 0, At, B0); PG8_MMA(0, 1, At, B1); PG8_BAR; PG8_SCHED;
;             PG8_LDA(At, 0, 1); PG8_STAGE(PG8_SB(0, 0), b2, voffB); PG8_STAGE(PG8_SB(0, 1), b2 + hstep, voffB); PG8_STAGE(PG8_SA(0, 0), a2, voffA);
.LBB0_1275:
	s_add_u32 s10, s40, 0xfffc0080
	s_addc_u32 s11, s41, -1
	s_add_i32 s64, 16, 0x10000
	s_cmp_eq_u32 s63, 12
	s_cselect_b32 s51, s34, s11
	s_cselect_b32 s50, s35, s10
	s_cselect_b32 s49, s27, s62
	s_cselect_b32 s48, s43, s59
	s_add_i32 s65, 16, 0x14000
	v_add_u32_e32 v142, s64, v179
	v_add_u32_e32 v176, s65, v179
	ds_read_b128 v[130:133], v142
	ds_read_b128 v[134:137], v142 offset:1024
	ds_read_b128 v[138:141], v142 offset:2048
	ds_read_b128 v[142:145], v142 offset:3072
	ds_read_b128 v[158:161], v176
	ds_read_b128 v[182:185], v176 offset:1024
	ds_read_b128 v[186:189], v176 offset:2048
	ds_read_b128 v[190:193], v176 offset:3072
	v_lshl_add_u64 v[176:177], s[40:41], 0, v[156:157]
	s_add_i32 m0, s4, 0xc000
	ds_read_b128 v[194:197], v181
	ds_read_b128 v[198:201], v181 offset:1024
	ds_read_b128 v[202:205], v181 offset:2048
	ds_read_b128 v[206:209], v181 offset:3072
	ds_read_b128 v[210:213], v181 offset:4096
	ds_read_b128 v[214:217], v181 offset:5120
	ds_read_b128 v[218:221], v181 offset:6144
	ds_read_b128 v[222:225], v181 offset:7168
	global_load_lds_dwordx4 v[176:177], off
	v_lshl_add_u64 v[176:177], s[40:41], 0, v[154:155]
	s_add_i32 m0, s4, 0xe000
	s_nop 0
	global_load_lds_dwordx4 v[176:177], off
	s_waitcnt vmcnt(8)
	s_waitcnt lgkmcnt(0)
	s_setprio 1
	s_barrier
	v_mfma_f32_16x16x32_bf16 v[126:129], v[130:133], v[194:197], v[126:129]
	v_mfma_f32_16x16x32_bf16 v[122:125], v[138:141], v[194:197], v[122:125]
	v_mfma_f32_16x16x32_bf16 v[106:109], v[138:141], v[202:205], v[106:109]
	v_mfma_f32_16x16x32_bf16 v[110:113], v[130:133], v[202:205], v[110:113]
	v_mfma_f32_16x16x32_bf16 v[94:97], v[130:133], v[210:213], v[94:97]
	v_mfma_f32_16x16x32_bf16 v[90:93], v[138:141], v[210:213], v[90:93]
	v_mfma_f32_16x16x32_bf16 v[74:77], v[138:141], v[218:221], v[74:77]
	v_mfma_f32_16x16x32_bf16 v[78:81], v[130:133], v[218:221], v[78:81]
	v_mfma_f32_16x16x32_bf16 v[126:129], v[134:137], v[198:201], v[126:129]
	v_mfma_f32_16x16x32_bf16 v[122:125], v[142:145], v[198:201], v[122:125]
	v_mfma_f32_16x16x32_bf16 v[106:109], v[142:145], v[206:209], v[106:109]
	v_mfma_f32_16x16x32_bf16 v[110:113], v[134:137], v[206:209], v[110:113]
	v_mfma_f32_16x16x32_bf16 v[94:97], v[134:137], v[214:217], v[94:97]
	v_mfma_f32_16x16x32_bf16 v[90:93], v[142:145], v[214:217], v[90:93]
	v_mfma_f32_16x16x32_bf16 v[74:77], v[142:145], v[222:225], v[74:77]
	v_mfma_f32_16x16x32_bf16 v[78:81], v[134:137], v[222:225], v[78:81]
	v_mfma_f32_16x16x32_bf16 v[118:121], v[158:161], v[194:197], v[118:121]
	v_mfma_f32_16x16x32_bf16 v[114:117], v[186:189], v[194:197], v[114:117]
	v_mfma_f32_16x16x32_bf16 v[98:101], v[186:189], v[202:205], v[98:101]
	v_mfma_f32_16x16x32_bf16 v[102:105], v[158:161], v[202:205], v[102:105]
	v_mfma_f32_16x16x32_bf16 v[86:89], v[158:161], v[210:213], v[86:89]
	v_mfma_f32_16x16x32_bf16 v[82:85], v[186:189], v[210:213], v[82:85]
	v_mfma_f32_16x16x32_bf16 v[66:69], v[186:189], v[218:221], v[66:69]
	v_mfma_f32_16x16x32_bf16 v[70:73], v[158:161], v[218:221], v[70:73]
	v_mfma_f32_16x16x32_bf16 v[118:121], v[182:185], v[198:201], v[118:121]
	v_mfma_f32_16x16x32_bf16 v[114:117], v[190:193], v[198:201], v[114:117]
	v_mfma_f32_16x16x32_bf16 v[98:101], v[190:193], v[206:209], v[98:101]
	v_mfma_f32_16x16x32_bf16 v[102:105], v[182:185], v[206:209], v[102:105]
	v_mfma_f32_16x16x32_bf16 v[86:89], v[182:185], v[214:217], v[86:89]
	v_mfma_f32_16x16x32_bf16 v[82:85], v[190:193], v[214:217], v[82:85]
	v_mfma_f32_16x16x32_bf16 v[66:69], v[190:193], v[222:225], v[66:69]
	v_mfma_f32_16x16x32_bf16 v[70:73], v[182:185], v[222:225], v[70:73]
	s_barrier
	s_setprio 0
	s_add_i32 s10, s64, s3
	v_lshl_add_u64 v[176:177], s[48:49], 0, v[0:1]
	s_mov_b32 m0, s10
	ds_read_b128 v[194:197], v181 offset:16384
	ds_read_b128 v[198:201], v181 offset:17408
	ds_read_b128 v[202:205], v181 offset:18432
	ds_read_b128 v[206:209], v181 offset:19456
	ds_read_b128 v[210:213], v181 offset:20480
	ds_read_b128 v[214:217], v181 offset:21504
	ds_read_b128 v[218:221], v181 offset:22528
	ds_read_b128 v[222:225], v181 offset:23552
	global_load_lds_dwordx4 v[176:177], off
	s_add_i32 m0, s10, 0x2000
	s_add_u32 s10, s48, 0x40000
	v_lshl_add_u64 v[226:227], s[48:49], 0, v[146:147]
	s_addc_u32 s11, s49, 0
	s_add_i32 s64, s65, s3
	global_load_lds_dwordx4 v[226:227], off
	v_lshl_add_u64 v[238:239], s[10:11], 0, v[0:1]
	s_mov_b32 m0, s64
	v_lshl_add_u64 v[240:241], s[50:51], 0, v[148:149]
	global_load_lds_dwordx4 v[238:239], off
	v_lshl_add_u64 v[238:239], s[10:11], 0, v[146:147]
	s_add_i32 m0, s64, 0x2000
	s_nop 0
	global_load_lds_dwordx4 v[238:239], off
	v_lshl_add_u64 v[238:239], s[50:51], 0, v[150:151]
	s_mov_b32 m0, s4
	s_nop 0
	global_load_lds_dwordx4 v[238:239], off
	s_mov_b32 m0, s5
	s_nop 0
	global_load_lds_dwordx4 v[240:241], off
	s_waitcnt vmcnt(8)
	s_waitcnt lgkmcnt(0)
	s_setprio 1
	s_barrier
; #define PG8_STAGE(bufoff, gbase, voff) do { _Pragma("unroll") for (int _i = 0; _i < 2; ++_i) \
;         __builtin_amdgcn_global_load_lds((const unsigned*)((const char*)(gbase) + (voff)[_i]), (PG8_LAS unsigned*)(lds + (bufoff) + ldsw + _i * 8192), 16, 0, 0); } while (0)
; #define PG8_LDA(dst, b, h) do { _Pragma("unroll") for (int m = 0; m < 4; ++m) _Pragma("unroll") for (int k = 0; k < 2; ++k) dst[m][k] = *(const PG8_LAS bf16x8*)(lds + PG8_SA(b, h) + aoff + m * 2048 + k * 1024); } while (0)
; #define PG8_LDB(dst, b, h) do { _Pragma("unroll") for (int n = 0; n < 2; ++n) _Pragma("unroll") for (int k = 0; k < 2; ++k) dst[n][k] = *(const PG8_LAS bf16x8*)(lds + PG8_SB(b, h) + boff + n * 2048 + k * 1024); } while (0)
; #define PG8_MMA(ai, bj, At, Bt) do { __builtin_amdgcn_s_setprio(1); _Pragma("unroll") for (int m = 0; m < 4; ++m) _Pragma("unroll") for (int n = 0; n < 2; ++n) _Pragma("unroll") for (int k = 0; k < 2; ++k) \
;         acc[ai][bj][m][n] = __builtin_amdgcn_mfma_f32_16x16x32_bf16(Bt[n][k], At[m][k], acc[ai][bj][m][n], 0, 0, 0); __builtin_amdgcn_s_setprio(0); } while (0)
; #define PG8_WAIT_V(n) asm volatile("s_waitcnt vmcnt(" #n ")" ::: "memory")
; #define PG8_WAIT_L(n) asm volatile("s_waitcnt lgkmcnt(" #n ")" ::: "memory")
; #define PG8_BAR __builtin_amdgcn_s_barrier()
; #define PG8_SCHED __builtin_amdgcn_sched_barrier(0)
; template <class Epi, class Sched, bool ALIGN_EPI = false, bool SP2 = false>
; __device__ __forceinline__ void gemm_phase(PG8_LAS unsigned char* lds, const Gemm g, const Sched& S, const Epi& E) {
;     ...
;             PG8_WAIT_V(8); PG8_WAIT_L(0); PG8_BAR; PG8_MMA(1, 0, At, B0); PG8_MMA(1, 1, At, B1); PG8_BAR; PG8_SCHED;
;             PG8_LDB(B0, 1, 0); PG8_LDB(B1, 1, 1); PG8_SCHED; PG8_LDA(At, 1, 0); PG8_STAGE(PG8_SA(0, 1), a2 + hstep, voffA);
;             PG8_WAIT_V(8); PG8_WAIT_L(0); PG8_BAR; PG8_MMA(0, 0, At, B0); PG8_MMA(0, 1, At, B1); PG8_BAR; PG8_SCHED;
	v_mfma_f32_16x16x32_bf16 v[62:65], v[130:133], v[194:197], v[62:65]
	v_mfma_f32_16x16x32_bf16 v[58:61], v[138:141], v[194:197], v[58:61]
	v_mfma_f32_16x16x32_bf16 v[42:45], v[138:141], v[202:205], v[42:45]
	v_mfma_f32_16x16x32_bf16 v[46:49], v[130:133], v[202:205], v[46:49]
	v_mfma_f32_16x16x32_bf16 v[30:33], v[130:133], v[210:213], v[30:33]
	v_mfma_f32_16x16x32_bf16 v[26:29], v[138:141], v[210:213], v[26:29]
	v_mfma_f32_16x16x32_bf16 v[10:13], v[138:141], v[218:221], v[10:13]
	v_mfma_f32_16x16x32_bf16 v[14:17], v[130:133], v[218:221], v[14:17]
	v_mfma_f32_16x16x32_bf16 v[62:65], v[134:137], v[198:201], v[62:65]
	v_mfma_f32_16x16x32_bf16 v[58:61], v[142:145], v[198:201], v[58:61]
	v_mfma_f32_16x16x32_bf16 v[42:45], v[142:145], v[206:209], v[42:45]
	v_mfma_f32_16x16x32_bf16 v[46:49], v[134:137], v[206:209], v[46:49]
	v_mfma_f32_16x16x32_bf16 v[30:33], v[134:137], v[214:217], v[30:33]
	v_mfma_f32_16x16x32_bf16 v[26:29], v[142:145], v[214:217], v[26:29]
	v_mfma_f32_16x16x32_bf16 v[10:13], v[142:145], v[222:225], v[10:13]
	v_mfma_f32_16x16x32_bf16 v[14:17], v[134:137], v[222:225], v[14:17]
	v_mfma_f32_16x16x32_bf16 v[54:57], v[158:161], v[194:197], v[54:57]
	v_mfma_f32_16x16x32_bf16 v[50:53], v[186:189], v[194:197], v[50:53]
	v_mfma_f32_16x16x32_bf16 v[34:37], v[186:189], v[202:205], v[34:37]
	v_mfma_f32_16x16x32_bf16 v[38:41], v[158:161], v[202:205], v[38:41]
	v_mfma_f32_16x16x32_bf16 v[22:25], v[158:161], v[210:213], v[22:25]
	v_mfma_f32_16x16x32_bf16 v[18:21], v[186:189], v[210:213], v[18:21]
	v_mfma_f32_16x16x32_bf16 v[2:5], v[186:189], v[218:221], v[2:5]
	v_mfma_f32_16x16x32_bf16 v[6:9], v[158:161], v[218:221], v[6:9]
	v_mfma_f32_16x16x32_bf16 v[54:57], v[182:185], v[198:201], v[54:57]
	v_mfma_f32_16x16x32_bf16 v[50:53], v[190:193], v[198:201], v[50:53]
	v_mfma_f32_16x16x32_bf16 v[34:37], v[190:193], v[206:209], v[34:37]
	v_mfma_f32_16x16x32_bf16 v[38:41], v[182:185], v[206:209], v[38:41]
	v_mfma_f32_16x16x32_bf16 v[22:25], v[182:185], v[214:217], v[22:25]
	v_mfma_f32_16x16x32_bf16 v[18:21], v[190:193], v[214:217], v[18:21]
	v_mfma_f32_16x16x32_bf16 v[2:5], v[190:193], v[222:225], v[2:5]
	v_mfma_f32_16x16x32_bf16 v[6:9], v[182:185], v[222:225], v[6:9]
	s_barrier
	s_setprio 0
	s_add_i32 s64, 16, 0x18000
	s_add_i32 s65, 16, 0x1c000
	v_add_u32_e32 v142, s64, v179
	v_add_u32_e32 v190, s65, v179
	ds_read_b128 v[130:133], v142
	ds_read_b128 v[134:137], v142 offset:1024
	ds_read_b128 v[138:141], v142 offset:2048
	ds_read_b128 v[142:145], v142 offset:3072
	ds_read_b128 v[158:161], v190
	ds_read_b128 v[182:185], v190 offset:1024
	ds_read_b128 v[186:189], v190 offset:2048
	ds_read_b128 v[190:193], v190 offset:3072
	s_add_u32 s10, s50, 0x40000
	s_addc_u32 s11, s51, 0
	s_mov_b32 m0, s6
	v_lshl_add_u64 v[242:243], s[10:11], 0, v[150:151]
	ds_read_b128 v[194:197], v181 offset:32768
	ds_read_b128 v[198:201], v181 offset:33792
	ds_read_b128 v[202:205], v181 offset:34816
	ds_read_b128 v[206:209], v181 offset:35840
	ds_read_b128 v[210:213], v181 offset:36864
	ds_read_b128 v[214:217], v181 offset:37888
	ds_read_b128 v[218:221], v181 offset:38912
	ds_read_b128 v[222:225], v181 offset:39936
	global_load_lds_dwordx4 v[242:243], off
	v_lshl_add_u64 v[242:243], s[10:11], 0, v[148:149]
	s_mov_b32 m0, s7
	s_nop 0
	global_load_lds_dwordx4 v[242:243], off
	s_waitcnt vmcnt(8)
	s_waitcnt lgkmcnt(0)
	s_setprio 1
	s_barrier
	v_mfma_f32_16x16x32_bf16 v[126:129], v[130:133], v[194:197], v[126:129]
	v_mfma_f32_16x16x32_bf16 v[122:125], v[138:141], v[194:197], v[122:125]
	v_mfma_f32_16x16x32_bf16 v[106:109], v[138:141], v[202:205], v[106:109]
	v_mfma_f32_16x16x32_bf16 v[110:113], v[130:133], v[202:205], v[110:113]
	v_mfma_f32_16x16x32_bf16 v[94:97], v[130:133], v[210:213], v[94:97]
	v_mfma_f32_16x16x32_bf16 v[90:93], v[138:141], v[210:213], v[90:93]
	v_mfma_f32_16x16x32_bf16 v[74:77], v[138:141], v[218:221], v[74:77]
	v_mfma_f32_16x16x32_bf16 v[78:81], v[130:133], v[218:221], v[78:81]
	v_mfma_f32_16x16x32_bf16 v[126:129], v[134:137], v[198:201], v[126:129]
	v_mfma_f32_16x16x32_bf16 v[122:125], v[142:145], v[198:201], v[122:125]
	v_mfma_f32_16x16x32_bf16 v[106:109], v[142:145], v[206:209], v[106:109]
	v_mfma_f32_16x16x32_bf16 v[110:113], v[134:137], v[206:209], v[110:113]
	v_mfma_f32_16x16x32_bf16 v[94:97], v[134:137], v[214:217], v[94:97]
	v_mfma_f32_16x16x32_bf16 v[90:93], v[142:145], v[214:217], v[90:93]
	v_mfma_f32_16x16x32_bf16 v[74:77], v[142:145], v[222:225], v[74:77]
	v_mfma_f32_16x16x32_bf16 v[78:81], v[134:137], v[222:225], v[78:81]
	v_mfma_f32_16x16x32_bf16 v[118:121], v[158:161], v[194:197], v[118:121]
	v_mfma_f32_16x16x32_bf16 v[114:117], v[186:189], v[194:197], v[114:117]
	v_mfma_f32_16x16x32_bf16 v[98:101], v[186:189], v[202:205], v[98:101]
	v_mfma_f32_16x16x32_bf16 v[102:105], v[158:161], v[202:205], v[102:105]
	v_mfma_f32_16x16x32_bf16 v[86:89], v[158:161], v[210:213], v[86:89]
	v_mfma_f32_16x16x32_bf16 v[82:85], v[186:189], v[210:213], v[82:85]
	v_mfma_f32_16x16x32_bf16 v[66:69], v[186:189], v[218:221], v[66:69]
	v_mfma_f32_16x16x32_bf16 v[70:73], v[158:161], v[218:221], v[70:73]
	v_mfma_f32_16x16x32_bf16 v[118:121], v[182:185], v[198:201], v[118:121]
	v_mfma_f32_16x16x32_bf16 v[114:117], v[190:193], v[198:201], v[114:117]
	v_mfma_f32_16x16x32_bf16 v[98:101], v[190:193], v[206:209], v[98:101]
	v_mfma_f32_16x16x32_bf16 v[102:105], v[182:185], v[206:209], v[102:105]
	v_mfma_f32_16x16x32_bf16 v[86:89], v[182:185], v[214:217], v[86:89]
	v_mfma_f32_16x16x32_bf16 v[82:85], v[190:193], v[214:217], v[82:85]
	v_mfma_f32_16x16x32_bf16 v[66:69], v[190:193], v[222:225], v[66:69]
	v_mfma_f32_16x16x32_bf16 v[70:73], v[182:185], v[222:225], v[70:73]
	s_barrier
; #define PG8_STAGE(bufoff, gbase, voff) do { _Pragma("unroll") for (int _i = 0; _i < 2; ++_i) \
;         __builtin_amdgcn_global_load_lds((const unsigned*)((const char*)(gbase) + (voff)[_i]), (PG8_LAS unsigned*)(lds + (bufoff) + ldsw + _i * 8192), 16, 0, 0); } while (0)
; #define PG8_LDA(dst, b, h) do { _Pragma("unroll") for (int m = 0; m < 4; ++m) _Pragma("unroll") for (int k = 0; k < 2; ++k) dst[m][k] = *(const PG8_LAS bf16x8*)(lds + PG8_SA(b, h) + aoff + m * 2048 + k * 1024); } while (0)
; #define PG8_MMA(ai, bj, At, Bt) do { __builtin_amdgcn_s_setprio(1); _Pragma("unroll") for (int m = 0; m < 4; ++m) _Pragma("unroll") for (int n = 0; n < 2; ++n) _Pragma("unroll") for (int k = 0; k < 2; ++k) \
;         acc[ai][bj][m][n] = __builtin_amdgcn_mfma_f32_16x16x32_bf16(Bt[n][k], At[m][k], acc[ai][bj][m][n], 0, 0, 0); __builtin_amdgcn_s_setprio(0); } while (0)
; #define PG8_WAIT_V(n) asm volatile("s_waitcnt vmcnt(" #n ")" ::: "memory")
; #define PG8_WAIT_L(n) asm volatile("s_waitcnt lgkmcnt(" #n ")" ::: "memory")
; #define PG8_BAR __builtin_amdgcn_s_barrier()
; #define PG8_SCHED __builtin_amdgcn_sched_barrier(0)
; template <class Epi, class Sched, bool ALIGN_EPI = false, bool SP2 = false>
; __device__ __forceinline__ void gemm_phase(PG8_LAS unsigned char* lds, const Gemm g, const Sched& S, const Epi& E) {
;     ...
;         for (int t = 0; t < nt; t += 2) {
;     ...
;             PG8_LDA(At, 1, 1); PG8_STAGE(PG8_SB(1, 0), b3, voffB); PG8_STAGE(PG8_SB(1, 1), b3 + hstep, voffB); PG8_STAGE(PG8_SA(1, 0), a3, voffA);
;             PG8_WAIT_V(8); PG8_WAIT_L(0); PG8_BAR; PG8_MMA(1, 0, At, B0); PG8_MMA(1, 1, At, B1); PG8_BAR; PG8_SCHED;
	s_setprio 0
	s_add_i32 s10, s64, s3
	v_lshl_add_u64 v[176:177], v[176:177], 0, s[28:29]
	s_mov_b32 m0, s10
	ds_read_b128 v[194:197], v181 offset:49152
	ds_read_b128 v[198:201], v181 offset:50176
	ds_read_b128 v[202:205], v181 offset:51200
	ds_read_b128 v[206:209], v181 offset:52224
	ds_read_b128 v[210:213], v181 offset:53248
	ds_read_b128 v[214:217], v181 offset:54272
	ds_read_b128 v[218:221], v181 offset:55296
	ds_read_b128 v[222:225], v181 offset:56320
	global_load_lds_dwordx4 v[176:177], off
	s_add_i32 m0, s10, 0x2000
	s_add_u32 s10, s48, 0x40080
	v_lshl_add_u64 v[176:177], v[226:227], 0, s[28:29]
	s_addc_u32 s11, s49, 0
	s_add_i32 s48, s65, s3
	global_load_lds_dwordx4 v[176:177], off
	v_lshl_add_u64 v[176:177], s[10:11], 0, v[0:1]
	s_mov_b32 m0, s48
	s_nop 0
	global_load_lds_dwordx4 v[176:177], off
	v_lshl_add_u64 v[176:177], s[10:11], 0, v[146:147]
	s_add_i32 m0, s48, 0x2000
	s_nop 0
	global_load_lds_dwordx4 v[176:177], off
	v_lshl_add_u64 v[176:177], v[238:239], 0, s[28:29]
	s_mov_b32 m0, s54
	s_nop 0
	global_load_lds_dwordx4 v[176:177], off
	v_lshl_add_u64 v[176:177], v[240:241], 0, s[28:29]
	s_mov_b32 m0, s55
	s_nop 0
	global_load_lds_dwordx4 v[176:177], off
	s_waitcnt vmcnt(8)
	s_waitcnt lgkmcnt(0)
	s_setprio 1
	s_barrier
	v_mfma_f32_16x16x32_bf16 v[62:65], v[130:133], v[194:197], v[62:65]
	v_mfma_f32_16x16x32_bf16 v[58:61], v[138:141], v[194:197], v[58:61]
	v_mfma_f32_16x16x32_bf16 v[42:45], v[138:141], v[202:205], v[42:45]
	v_mfma_f32_16x16x32_bf16 v[46:49], v[130:133], v[202:205], v[46:49]
	v_mfma_f32_16x16x32_bf16 v[30:33], v[130:133], v[210:213], v[30:33]
	v_mfma_f32_16x16x32_bf16 v[26:29], v[138:141], v[210:213], v[26:29]
	v_mfma_f32_16x16x32_bf16 v[10:13], v[138:141], v[218:221], v[10:13]
	v_mfma_f32_16x16x32_bf16 v[14:17], v[130:133], v[218:221], v[14:17]
	v_mfma_f32_16x16x32_bf16 v[62:65], v[134:137], v[198:201], v[62:65]
	v_mfma_f32_16x16x32_bf16 v[58:61], v[142:145], v[198:201], v[58:61]
	v_mfma_f32_16x16x32_bf16 v[42:45], v[142:145], v[206:209], v[42:45]
	v_mfma_f32_16x16x32_bf16 v[46:49], v[134:137], v[206:209], v[46:49]
	v_mfma_f32_16x16x32_bf16 v[30:33], v[134:137], v[214:217], v[30:33]
	v_mfma_f32_16x16x32_bf16 v[26:29], v[142:145], v[214:217], v[26:29]
	v_mfma_f32_16x16x32_bf16 v[10:13], v[142:145], v[222:225], v[10:13]
	v_mfma_f32_16x16x32_bf16 v[14:17], v[134:137], v[222:225], v[14:17]
	v_mfma_f32_16x16x32_bf16 v[54:57], v[158:161], v[194:197], v[54:57]
	v_mfma_f32_16x16x32_bf16 v[50:53], v[186:189], v[194:197], v[50:53]
	v_mfma_f32_16x16x32_bf16 v[34:37], v[186:189], v[202:205], v[34:37]
	v_mfma_f32_16x16x32_bf16 v[38:41], v[158:161], v[202:205], v[38:41]
	v_mfma_f32_16x16x32_bf16 v[22:25], v[158:161], v[210:213], v[22:25]
	v_mfma_f32_16x16x32_bf16 v[18:21], v[186:189], v[210:213], v[18:21]
	v_mfma_f32_16x16x32_bf16 v[2:5], v[186:189], v[218:221], v[2:5]
	v_mfma_f32_16x16x32_bf16 v[6:9], v[158:161], v[218:221], v[6:9]
	v_mfma_f32_16x16x32_bf16 v[54:57], v[182:185], v[198:201], v[54:57]
	v_mfma_f32_16x16x32_bf16 v[50:53], v[190:193], v[198:201], v[50:53]
	v_mfma_f32_16x16x32_bf16 v[34:37], v[190:193], v[206:209], v[34:37]
	v_mfma_f32_16x16x32_bf16 v[38:41], v[182:185], v[206:209], v[38:41]
	v_mfma_f32_16x16x32_bf16 v[22:25], v[182:185], v[214:217], v[22:25]
	v_mfma_f32_16x16x32_bf16 v[18:21], v[190:193], v[214:217], v[18:21]
	v_mfma_f32_16x16x32_bf16 v[2:5], v[190:193], v[222:225], v[2:5]
	v_mfma_f32_16x16x32_bf16 v[6:9], v[182:185], v[222:225], v[6:9]
	s_barrier
	s_setprio 0
	s_add_i32 s63, s63, 2
	s_add_u32 s59, s59, 0x100
	s_addc_u32 s62, s62, 0
	s_add_u32 s40, s40, 0x100
	s_addc_u32 s41, s41, 0
	s_cmp_gt_u32 s63, 13
	s_cbranch_scc0 .LBB0_1275
	s_and_b64 vcc, exec, s[24:25]
	s_cbranch_vccz .LBB0_1278
	s_barrier

; #define PG8_STAGE(bufoff, gbase, voff) do { _Pragma("unroll") for (int _i = 0; _i < 2; ++_i) \
;         __builtin_amdgcn_global_load_lds((const unsigned*)((const char*)(gbase) + (voff)[_i]), (PG8_LAS unsigned*)(lds + (bufoff) + ldsw + _i * 8192), 16, 0, 0); } while (0)
; #define PG8_LDA(dst, b, h) do { _Pragma("unroll") for (int m = 0; m < 4; ++m) _Pragma("unroll") for (int k = 0; k < 2; ++k) dst[m][k] = *(const PG8_LAS bf16x8*)(lds + PG8_SA(b, h) + aoff + m * 2048 + k * 1024); } while (0)
; #define PG8_LDB(dst, b, h) do { _Pragma("unroll") for (int n = 0; n < 2; ++n) _Pragma("unroll") for (int k = 0; k < 2; ++k) dst[n][k] = *(const PG8_LAS bf16x8*)(lds + PG8_SB(b, h) + boff + n * 2048 + k * 1024); } while (0)
; #define PG8_MMA(ai, bj, At, Bt) do { __builtin_amdgcn_s_setprio(1); _Pragma("unroll") for (int m = 0; m < 4; ++m) _Pragma("unroll") for (int n = 0; n < 2; ++n) _Pragma("unroll") for (int k = 0; k < 2; ++k) \
;         acc[ai][bj][m][n] = __builtin_amdgcn_mfma_f32_16x16x32_bf16(Bt[n][k], At[m][k], acc[ai][bj][m][n], 0, 0, 0); __builtin_amdgcn_s_setprio(0); } while (0)
; #define PG8_WAIT_V(n) asm volatile("s_waitcnt vmcnt(" #n ")" ::: "memory")
; #define PG8_WAIT_L(n) asm volatile("s_waitcnt lgkmcnt(" #n ")" ::: "memory")
; #define PG8_BAR __builtin_amdgcn_s_barrier()
; #define PG8_SCHED __builtin_amdgcn_sched_barrier(0)
; template <class Epi, class Sched, bool ALIGN_EPI = false, bool SP2 = false>
; __device__ __forceinline__ void gemm_phase(PG8_LAS unsigned char* lds, const Gemm g, const Sched& S, const Epi& E) {
;     ...
;             const bool last = (t == nt - 2);
;             const char* a1 = cA + (size_t)(t + 1) * kstep;
;             const char* a2 = last ? nA : cA + (size_t)(t + 2) * kstep; const char* b2 = last ? nB : cB + (size_t)(t + 2) * kstep;
;             const char* a3 = a2 + kstep; const char* b3 = b2 + kstep;
;             if (last && has_next) S.a_ready(nxt);
;             if constexpr (SP2) {
;             PG8_LDB(B0, 0, 0); PG8_LDB(B1, 0, 1); PG8_SCHED; PG8_LDA(At, 0, 0); PG8_STAGE(PG8_SA(1, 1), a1 + hstep, voffA);
;             PG8_WAIT_V(8); PG8_WAIT_L(0); PG8_BAR; PG8_MMA(0, 0, At, B0); PG8_MMA(0, 1, At, B1); PG8_BAR; PG8_SCHED;
;             PG8_LDA(At, 0, 1); PG8_STAGE(PG8_SB(0, 0), b2, voffB); PG8_STAGE(PG8_SB(0, 1), b2 + hstep, voffB); PG8_STAGE(PG8_SA(0, 0), a2, voffA);
.LBB0_1295:
	s_add_u32 s40, s42, 0x100
	s_addc_u32 s41, s43, 0
	s_add_i32 s10, 16, 0x10000
	s_cmp_eq_u32 s68, 40
	s_cselect_b32 s49, s25, s41
	s_cselect_b32 s48, s24, s40
	v_add_u32_e32 v140, s10, v143
	s_cselect_b32 s47, s27, s67
	s_cselect_b32 s46, s26, s66
	s_add_i32 s69, 16, 0x14000
	ds_read_b128 v[146:149], v140
	ds_read_b128 v[150:153], v140 offset:1024
	ds_read_b128 v[154:157], v140 offset:2048
	ds_read_b128 v[158:161], v140 offset:3072
	v_add_u32_e32 v140, s69, v143
	ds_read_b128 v[176:179], v140
	ds_read_b128 v[180:183], v140 offset:1024
	ds_read_b128 v[184:187], v140 offset:2048
	ds_read_b128 v[188:191], v140 offset:3072
	v_lshl_add_u64 v[140:141], s[42:43], 0, v[138:139]
	s_add_i32 m0, s9, 0xc000
	ds_read_b128 v[192:195], v145
	ds_read_b128 v[196:199], v145 offset:1024
	ds_read_b128 v[200:203], v145 offset:2048
	ds_read_b128 v[204:207], v145 offset:3072
	ds_read_b128 v[208:211], v145 offset:4096
	ds_read_b128 v[212:215], v145 offset:5120
	ds_read_b128 v[216:219], v145 offset:6144
	ds_read_b128 v[220:223], v145 offset:7168
	global_load_lds_dwordx4 v[140:141], off
	v_lshl_add_u64 v[140:141], s[42:43], 0, v[136:137]
	s_add_i32 m0, s9, 0xe000
	s_nop 0
	global_load_lds_dwordx4 v[140:141], off
	s_waitcnt vmcnt(8)
	s_waitcnt lgkmcnt(0)
	s_setprio 1
	s_barrier
	v_mfma_f32_16x16x32_bf16 v[126:129], v[146:149], v[192:195], v[126:129]
	v_mfma_f32_16x16x32_bf16 v[122:125], v[154:157], v[192:195], v[122:125]
	v_mfma_f32_16x16x32_bf16 v[110:113], v[154:157], v[200:203], v[110:113]
	v_mfma_f32_16x16x32_bf16 v[114:117], v[146:149], v[200:203], v[114:117]
	v_mfma_f32_16x16x32_bf16 v[98:101], v[146:149], v[208:211], v[98:101]
	v_mfma_f32_16x16x32_bf16 v[94:97], v[154:157], v[208:211], v[94:97]
	v_mfma_f32_16x16x32_bf16 v[78:81], v[154:157], v[216:219], v[78:81]
	v_mfma_f32_16x16x32_bf16 v[82:85], v[146:149], v[216:219], v[82:85]
	v_mfma_f32_16x16x32_bf16 v[126:129], v[150:153], v[196:199], v[126:129]
	v_mfma_f32_16x16x32_bf16 v[122:125], v[158:161], v[196:199], v[122:125]
	v_mfma_f32_16x16x32_bf16 v[110:113], v[158:161], v[204:207], v[110:113]
	v_mfma_f32_16x16x32_bf16 v[114:117], v[150:153], v[204:207], v[114:117]
	v_mfma_f32_16x16x32_bf16 v[98:101], v[150:153], v[212:215], v[98:101]
	v_mfma_f32_16x16x32_bf16 v[94:97], v[158:161], v[212:215], v[94:97]
	v_mfma_f32_16x16x32_bf16 v[78:81], v[158:161], v[220:223], v[78:81]
	v_mfma_f32_16x16x32_bf16 v[82:85], v[150:153], v[220:223], v[82:85]
	v_mfma_f32_16x16x32_bf16 v[118:121], v[176:179], v[192:195], v[118:121]
	v_mfma_f32_16x16x32_bf16 v[106:109], v[184:187], v[192:195], v[106:109]
	v_mfma_f32_16x16x32_bf16 v[90:93], v[184:187], v[200:203], v[90:93]
	v_mfma_f32_16x16x32_bf16 v[102:105], v[176:179], v[200:203], v[102:105]
	v_mfma_f32_16x16x32_bf16 v[86:89], v[176:179], v[208:211], v[86:89]
	v_mfma_f32_16x16x32_bf16 v[74:77], v[184:187], v[208:211], v[74:77]
	v_mfma_f32_16x16x32_bf16 v[66:69], v[184:187], v[216:219], v[66:69]
	v_mfma_f32_16x16x32_bf16 v[70:73], v[176:179], v[216:219], v[70:73]
	v_mfma_f32_16x16x32_bf16 v[118:121], v[180:183], v[196:199], v[118:121]
	v_mfma_f32_16x16x32_bf16 v[106:109], v[188:191], v[196:199], v[106:109]
	v_mfma_f32_16x16x32_bf16 v[90:93], v[188:191], v[204:207], v[90:93]
	v_mfma_f32_16x16x32_bf16 v[102:105], v[180:183], v[204:207], v[102:105]
	v_mfma_f32_16x16x32_bf16 v[86:89], v[180:183], v[212:215], v[86:89]
	v_mfma_f32_16x16x32_bf16 v[74:77], v[188:191], v[212:215], v[74:77]
	v_mfma_f32_16x16x32_bf16 v[66:69], v[188:191], v[220:223], v[66:69]
	v_mfma_f32_16x16x32_bf16 v[70:73], v[180:183], v[220:223], v[70:73]
	s_barrier
	s_setprio 0
	s_add_i32 s10, s10, s6
	v_lshl_add_u64 v[140:141], s[46:47], 0, v[0:1]
	s_mov_b32 m0, s10
	ds_read_b128 v[192:195], v145 offset:16384
	ds_read_b128 v[196:199], v145 offset:17408
	ds_read_b128 v[200:203], v145 offset:18432
	ds_read_b128 v[204:207], v145 offset:19456
	ds_read_b128 v[208:211], v145 offset:20480
	ds_read_b128 v[212:215], v145 offset:21504
	ds_read_b128 v[216:219], v145 offset:22528
	ds_read_b128 v[220:223], v145 offset:23552
	global_load_lds_dwordx4 v[140:141], off
	s_add_i32 m0, s10, 0x2000
	s_add_u32 s10, s46, 0xb0000
	v_lshl_add_u64 v[224:225], s[46:47], 0, v[130:131]
	s_addc_u32 s11, s47, 0
	s_add_i32 s42, s69, s6
	global_load_lds_dwordx4 v[224:225], off
	v_lshl_add_u64 v[226:227], s[10:11], 0, v[0:1]
	s_mov_b32 m0, s42
	v_lshl_add_u64 v[238:239], s[48:49], 0, v[132:133]
	global_load_lds_dwordx4 v[226:227], off
	v_lshl_add_u64 v[226:227], s[10:11], 0, v[130:131]
	s_add_i32 m0, s42, 0x2000
	s_nop 0
	global_load_lds_dwordx4 v[226:227], off
	v_lshl_add_u64 v[226:227], s[48:49], 0, v[134:135]
	s_mov_b32 m0, s9
	s_nop 0
	global_load_lds_dwordx4 v[226:227], off
	s_mov_b32 m0, s50
	s_nop 0
	global_load_lds_dwordx4 v[238:239], off
	s_waitcnt vmcnt(8)
	s_waitcnt lgkmcnt(0)
	s_setprio 1
	s_barrier
; #define PG8_STAGE(bufoff, gbase, voff) do { _Pragma("unroll") for (int _i = 0; _i < 2; ++_i) \
;         __builtin_amdgcn_global_load_lds((const unsigned*)((const char*)(gbase) + (voff)[_i]), (PG8_LAS unsigned*)(lds + (bufoff) + ldsw + _i * 8192), 16, 0, 0); } while (0)
; #define PG8_LDA(dst, b, h) do { _Pragma("unroll") for (int m = 0; m < 4; ++m) _Pragma("unroll") for (int k = 0; k < 2; ++k) dst[m][k] = *(const PG8_LAS bf16x8*)(lds + PG8_SA(b, h) + aoff + m * 2048 + k * 1024); } while (0)
; #define PG8_LDB(dst, b, h) do { _Pragma("unroll") for (int n = 0; n < 2; ++n) _Pragma("unroll") for (int k = 0; k < 2; ++k) dst[n][k] = *(const PG8_LAS bf16x8*)(lds + PG8_SB(b, h) + boff + n * 2048 + k * 1024); } while (0)
; #define PG8_MMA(ai, bj, At, Bt) do { __builtin_amdgcn_s_setprio(1); _Pragma("unroll") for (int m = 0; m < 4; ++m) _Pragma("unroll") for (int n = 0; n < 2; ++n) _Pragma("unroll") for (int k = 0; k < 2; ++k) \
;         acc[ai][bj][m][n] = __builtin_amdgcn_mfma_f32_16x16x32_bf16(Bt[n][k], At[m][k], acc[ai][bj][m][n], 0, 0, 0); __builtin_amdgcn_s_setprio(0); } while (0)
; #define PG8_WAIT_V(n) asm volatile("s_waitcnt vmcnt(" #n ")" ::: "memory")
; #define PG8_WAIT_L(n) asm volatile("s_waitcnt lgkmcnt(" #n ")" ::: "memory")
; #define PG8_BAR __builtin_amdgcn_s_barrier()
; #define PG8_SCHED __builtin_amdgcn_sched_barrier(0)
; template <class Epi, class Sched, bool ALIGN_EPI = false, bool SP2 = false>
; __device__ __forceinline__ void gemm_phase(PG8_LAS unsigned char* lds, const Gemm g, const Sched& S, const Epi& E) {
;     ...
;             PG8_WAIT_V(8); PG8_WAIT_L(0); PG8_BAR; PG8_MMA(1, 0, At, B0); PG8_MMA(1, 1, At, B1); PG8_BAR; PG8_SCHED;
;             PG8_LDB(B0, 1, 0); PG8_LDB(B1, 1, 1); PG8_SCHED; PG8_LDA(At, 1, 0); PG8_STAGE(PG8_SA(0, 1), a2 + hstep, voffA);
;             PG8_WAIT_V(8); PG8_WAIT_L(0); PG8_BAR; PG8_MMA(0, 0, At, B0); PG8_MMA(0, 1, At, B1); PG8_BAR; PG8_SCHED;
	v_mfma_f32_16x16x32_bf16 v[62:65], v[146:149], v[192:195], v[62:65]
	v_mfma_f32_16x16x32_bf16 v[58:61], v[154:157], v[192:195], v[58:61]
	v_mfma_f32_16x16x32_bf16 v[46:49], v[154:157], v[200:203], v[46:49]
	v_mfma_f32_16x16x32_bf16 v[50:53], v[146:149], v[200:203], v[50:53]
	v_mfma_f32_16x16x32_bf16 v[34:37], v[146:149], v[208:211], v[34:37]
	v_mfma_f32_16x16x32_bf16 v[30:33], v[154:157], v[208:211], v[30:33]
	v_mfma_f32_16x16x32_bf16 v[14:17], v[154:157], v[216:219], v[14:17]
	v_mfma_f32_16x16x32_bf16 v[18:21], v[146:149], v[216:219], v[18:21]
	v_mfma_f32_16x16x32_bf16 v[62:65], v[150:153], v[196:199], v[62:65]
	v_mfma_f32_16x16x32_bf16 v[58:61], v[158:161], v[196:199], v[58:61]
	v_mfma_f32_16x16x32_bf16 v[46:49], v[158:161], v[204:207], v[46:49]
	v_mfma_f32_16x16x32_bf16 v[50:53], v[150:153], v[204:207], v[50:53]
	v_mfma_f32_16x16x32_bf16 v[34:37], v[150:153], v[212:215], v[34:37]
	v_mfma_f32_16x16x32_bf16 v[30:33], v[158:161], v[212:215], v[30:33]
	v_mfma_f32_16x16x32_bf16 v[14:17], v[158:161], v[220:223], v[14:17]
	v_mfma_f32_16x16x32_bf16 v[18:21], v[150:153], v[220:223], v[18:21]
	v_mfma_f32_16x16x32_bf16 v[54:57], v[176:179], v[192:195], v[54:57]
	v_mfma_f32_16x16x32_bf16 v[42:45], v[184:187], v[192:195], v[42:45]
	v_mfma_f32_16x16x32_bf16 v[26:29], v[184:187], v[200:203], v[26:29]
	v_mfma_f32_16x16x32_bf16 v[38:41], v[176:179], v[200:203], v[38:41]
	v_mfma_f32_16x16x32_bf16 v[22:25], v[176:179], v[208:211], v[22:25]
	v_mfma_f32_16x16x32_bf16 v[10:13], v[184:187], v[208:211], v[10:13]
	v_mfma_f32_16x16x32_bf16 v[2:5], v[184:187], v[216:219], v[2:5]
	v_mfma_f32_16x16x32_bf16 v[6:9], v[176:179], v[216:219], v[6:9]
	v_mfma_f32_16x16x32_bf16 v[54:57], v[180:183], v[196:199], v[54:57]
	v_mfma_f32_16x16x32_bf16 v[42:45], v[188:191], v[196:199], v[42:45]
	v_mfma_f32_16x16x32_bf16 v[26:29], v[188:191], v[204:207], v[26:29]
	v_mfma_f32_16x16x32_bf16 v[38:41], v[180:183], v[204:207], v[38:41]
	v_mfma_f32_16x16x32_bf16 v[22:25], v[180:183], v[212:215], v[22:25]
	v_mfma_f32_16x16x32_bf16 v[10:13], v[188:191], v[212:215], v[10:13]
	v_mfma_f32_16x16x32_bf16 v[2:5], v[188:191], v[220:223], v[2:5]
	v_mfma_f32_16x16x32_bf16 v[6:9], v[180:183], v[220:223], v[6:9]
	s_barrier
	s_setprio 0
	s_add_i32 s42, 16, 0x18000
	s_add_i32 s43, 16, 0x1c000
	v_add_u32_e32 v158, s42, v143
	v_add_u32_e32 v188, s43, v143
	ds_read_b128 v[146:149], v158
	ds_read_b128 v[150:153], v158 offset:1024
	ds_read_b128 v[154:157], v158 offset:2048
	ds_read_b128 v[158:161], v158 offset:3072
	ds_read_b128 v[176:179], v188
	ds_read_b128 v[180:183], v188 offset:1024
	ds_read_b128 v[184:187], v188 offset:2048
	ds_read_b128 v[188:191], v188 offset:3072
	s_add_u32 s10, s48, 0xb0000
	s_addc_u32 s11, s49, 0
	s_mov_b32 m0, s51
	v_lshl_add_u64 v[240:241], s[10:11], 0, v[134:135]
	ds_read_b128 v[192:195], v145 offset:32768
	ds_read_b128 v[196:199], v145 offset:33792
	ds_read_b128 v[200:203], v145 offset:34816
	ds_read_b128 v[204:207], v145 offset:35840
	ds_read_b128 v[208:211], v145 offset:36864
	ds_read_b128 v[212:215], v145 offset:37888
	ds_read_b128 v[216:219], v145 offset:38912
	ds_read_b128 v[220:223], v145 offset:39936
	global_load_lds_dwordx4 v[240:241], off
	v_lshl_add_u64 v[240:241], s[10:11], 0, v[132:133]
	s_mov_b32 m0, s54
	s_nop 0
	global_load_lds_dwordx4 v[240:241], off
	s_waitcnt vmcnt(8)
	s_waitcnt lgkmcnt(0)
	s_setprio 1
	s_barrier
	v_mfma_f32_16x16x32_bf16 v[126:129], v[146:149], v[192:195], v[126:129]
	v_mfma_f32_16x16x32_bf16 v[122:125], v[154:157], v[192:195], v[122:125]
	v_mfma_f32_16x16x32_bf16 v[110:113], v[154:157], v[200:203], v[110:113]
	v_mfma_f32_16x16x32_bf16 v[114:117], v[146:149], v[200:203], v[114:117]
	v_mfma_f32_16x16x32_bf16 v[98:101], v[146:149], v[208:211], v[98:101]
	v_mfma_f32_16x16x32_bf16 v[94:97], v[154:157], v[208:211], v[94:97]
	v_mfma_f32_16x16x32_bf16 v[78:81], v[154:157], v[216:219], v[78:81]
	v_mfma_f32_16x16x32_bf16 v[82:85], v[146:149], v[216:219], v[82:85]
	v_mfma_f32_16x16x32_bf16 v[126:129], v[150:153], v[196:199], v[126:129]
	v_mfma_f32_16x16x32_bf16 v[122:125], v[158:161], v[196:199], v[122:125]
	v_mfma_f32_16x16x32_bf16 v[110:113], v[158:161], v[204:207], v[110:113]
	v_mfma_f32_16x16x32_bf16 v[114:117], v[150:153], v[204:207], v[114:117]
	v_mfma_f32_16x16x32_bf16 v[98:101], v[150:153], v[212:215], v[98:101]
	v_mfma_f32_16x16x32_bf16 v[94:97], v[158:161], v[212:215], v[94:97]
	v_mfma_f32_16x16x32_bf16 v[78:81], v[158:161], v[220:223], v[78:81]
	v_mfma_f32_16x16x32_bf16 v[82:85], v[150:153], v[220:223], v[82:85]
	v_mfma_f32_16x16x32_bf16 v[118:121], v[176:179], v[192:195], v[118:121]
	v_mfma_f32_16x16x32_bf16 v[106:109], v[184:187], v[192:195], v[106:109]
	v_mfma_f32_16x16x32_bf16 v[90:93], v[184:187], v[200:203], v[90:93]
	v_mfma_f32_16x16x32_bf16 v[102:105], v[176:179], v[200:203], v[102:105]
	v_mfma_f32_16x16x32_bf16 v[86:89], v[176:179], v[208:211], v[86:89]
	v_mfma_f32_16x16x32_bf16 v[74:77], v[184:187], v[208:211], v[74:77]
	v_mfma_f32_16x16x32_bf16 v[66:69], v[184:187], v[216:219], v[66:69]
	v_mfma_f32_16x16x32_bf16 v[70:73], v[176:179], v[216:219], v[70:73]
	v_mfma_f32_16x16x32_bf16 v[118:121], v[180:183], v[196:199], v[118:121]
	v_mfma_f32_16x16x32_bf16 v[106:109], v[188:191], v[196:199], v[106:109]
	v_mfma_f32_16x16x32_bf16 v[90:93], v[188:191], v[204:207], v[90:93]
	v_mfma_f32_16x16x32_bf16 v[102:105], v[180:183], v[204:207], v[102:105]
	v_mfma_f32_16x16x32_bf16 v[86:89], v[180:183], v[212:215], v[86:89]
	v_mfma_f32_16x16x32_bf16 v[74:77], v[188:191], v[212:215], v[74:77]
	v_mfma_f32_16x16x32_bf16 v[66:69], v[188:191], v[220:223], v[66:69]
	v_mfma_f32_16x16x32_bf16 v[70:73], v[180:183], v[220:223], v[70:73]
	s_barrier
; #define PG8_STAGE(bufoff, gbase, voff) do { _Pragma("unroll") for (int _i = 0; _i < 2; ++_i) \
;         __builtin_amdgcn_global_load_lds((const unsigned*)((const char*)(gbase) + (voff)[_i]), (PG8_LAS unsigned*)(lds + (bufoff) + ldsw + _i * 8192), 16, 0, 0); } while (0)
; #define PG8_LDA(dst, b, h) do { _Pragma("unroll") for (int m = 0; m < 4; ++m) _Pragma("unroll") for (int k = 0; k < 2; ++k) dst[m][k] = *(const PG8_LAS bf16x8*)(lds + PG8_SA(b, h) + aoff + m * 2048 + k * 1024); } while (0)
; #define PG8_MMA(ai, bj, At, Bt) do { __builtin_amdgcn_s_setprio(1); _Pragma("unroll") for (int m = 0; m < 4; ++m) _Pragma("unroll") for (int n = 0; n < 2; ++n) _Pragma("unroll") for (int k = 0; k < 2; ++k) \
;         acc[ai][bj][m][n] = __builtin_amdgcn_mfma_f32_16x16x32_bf16(Bt[n][k], At[m][k], acc[ai][bj][m][n], 0, 0, 0); __builtin_amdgcn_s_setprio(0); } while (0)
; #define PG8_WAIT_V(n) asm volatile("s_waitcnt vmcnt(" #n ")" ::: "memory")
; #define PG8_WAIT_L(n) asm volatile("s_waitcnt lgkmcnt(" #n ")" ::: "memory")
; #define PG8_BAR __builtin_amdgcn_s_barrier()
; #define PG8_SCHED __builtin_amdgcn_sched_barrier(0)
; template <class Epi, class Sched, bool ALIGN_EPI = false, bool SP2 = false>
; __device__ __forceinline__ void gemm_phase(PG8_LAS unsigned char* lds, const Gemm g, const Sched& S, const Epi& E) {
;     ...
;         for (int t = 0; t < nt; t += 2) {
;     ...
;             PG8_LDA(At, 1, 1); PG8_STAGE(PG8_SB(1, 0), b3, voffB); PG8_STAGE(PG8_SB(1, 1), b3 + hstep, voffB); PG8_STAGE(PG8_SA(1, 0), a3, voffA);
;             PG8_WAIT_V(8); PG8_WAIT_L(0); PG8_BAR; PG8_MMA(1, 0, At, B0); PG8_MMA(1, 1, At, B1); PG8_BAR; PG8_SCHED;
	s_setprio 0
	s_add_i32 s10, s42, s6
	v_lshl_add_u64 v[140:141], v[140:141], 0, s[28:29]
	s_mov_b32 m0, s10
	ds_read_b128 v[192:195], v145 offset:49152
	ds_read_b128 v[196:199], v145 offset:50176
	ds_read_b128 v[200:203], v145 offset:51200
	ds_read_b128 v[204:207], v145 offset:52224
	ds_read_b128 v[208:211], v145 offset:53248
	ds_read_b128 v[212:215], v145 offset:54272
	ds_read_b128 v[216:219], v145 offset:55296
	ds_read_b128 v[220:223], v145 offset:56320
	global_load_lds_dwordx4 v[140:141], off
	s_add_i32 m0, s10, 0x2000
	s_add_u32 s10, s46, 0xb0080
	v_lshl_add_u64 v[140:141], v[224:225], 0, s[28:29]
	s_addc_u32 s11, s47, 0
	s_add_i32 s42, s43, s6
	global_load_lds_dwordx4 v[140:141], off
	v_lshl_add_u64 v[140:141], s[10:11], 0, v[0:1]
	s_mov_b32 m0, s42
	s_nop 0
	global_load_lds_dwordx4 v[140:141], off
	v_lshl_add_u64 v[140:141], s[10:11], 0, v[130:131]
	s_add_i32 m0, s42, 0x2000
	s_nop 0
	global_load_lds_dwordx4 v[140:141], off
	v_lshl_add_u64 v[140:141], v[226:227], 0, s[28:29]
	s_mov_b32 m0, s57
	s_nop 0
	global_load_lds_dwordx4 v[140:141], off
	v_lshl_add_u64 v[140:141], v[238:239], 0, s[28:29]
	s_mov_b32 m0, s58
	s_nop 0
	global_load_lds_dwordx4 v[140:141], off
	s_waitcnt vmcnt(8)
	s_waitcnt lgkmcnt(0)
	s_setprio 1
	s_barrier
	v_mfma_f32_16x16x32_bf16 v[62:65], v[146:149], v[192:195], v[62:65]
	v_mfma_f32_16x16x32_bf16 v[58:61], v[154:157], v[192:195], v[58:61]
	v_mfma_f32_16x16x32_bf16 v[46:49], v[154:157], v[200:203], v[46:49]
	v_mfma_f32_16x16x32_bf16 v[50:53], v[146:149], v[200:203], v[50:53]
	v_mfma_f32_16x16x32_bf16 v[34:37], v[146:149], v[208:211], v[34:37]
	v_mfma_f32_16x16x32_bf16 v[30:33], v[154:157], v[208:211], v[30:33]
	v_mfma_f32_16x16x32_bf16 v[14:17], v[154:157], v[216:219], v[14:17]
	v_mfma_f32_16x16x32_bf16 v[18:21], v[146:149], v[216:219], v[18:21]
	v_mfma_f32_16x16x32_bf16 v[62:65], v[150:153], v[196:199], v[62:65]
	v_mfma_f32_16x16x32_bf16 v[58:61], v[158:161], v[196:199], v[58:61]
	v_mfma_f32_16x16x32_bf16 v[46:49], v[158:161], v[204:207], v[46:49]
	v_mfma_f32_16x16x32_bf16 v[50:53], v[150:153], v[204:207], v[50:53]
	v_mfma_f32_16x16x32_bf16 v[34:37], v[150:153], v[212:215], v[34:37]
	v_mfma_f32_16x16x32_bf16 v[30:33], v[158:161], v[212:215], v[30:33]
	v_mfma_f32_16x16x32_bf16 v[14:17], v[158:161], v[220:223], v[14:17]
	v_mfma_f32_16x16x32_bf16 v[18:21], v[150:153], v[220:223], v[18:21]
	v_mfma_f32_16x16x32_bf16 v[54:57], v[176:179], v[192:195], v[54:57]
	v_mfma_f32_16x16x32_bf16 v[42:45], v[184:187], v[192:195], v[42:45]
	v_mfma_f32_16x16x32_bf16 v[26:29], v[184:187], v[200:203], v[26:29]
	v_mfma_f32_16x16x32_bf16 v[38:41], v[176:179], v[200:203], v[38:41]
	v_mfma_f32_16x16x32_bf16 v[22:25], v[176:179], v[208:211], v[22:25]
	v_mfma_f32_16x16x32_bf16 v[10:13], v[184:187], v[208:211], v[10:13]
	v_mfma_f32_16x16x32_bf16 v[2:5], v[184:187], v[216:219], v[2:5]
	v_mfma_f32_16x16x32_bf16 v[6:9], v[176:179], v[216:219], v[6:9]
	v_mfma_f32_16x16x32_bf16 v[54:57], v[180:183], v[196:199], v[54:57]
	v_mfma_f32_16x16x32_bf16 v[42:45], v[188:191], v[196:199], v[42:45]
	v_mfma_f32_16x16x32_bf16 v[26:29], v[188:191], v[204:207], v[26:29]
	v_mfma_f32_16x16x32_bf16 v[38:41], v[180:183], v[204:207], v[38:41]
	v_mfma_f32_16x16x32_bf16 v[22:25], v[180:183], v[212:215], v[22:25]
	v_mfma_f32_16x16x32_bf16 v[10:13], v[188:191], v[212:215], v[10:13]
	v_mfma_f32_16x16x32_bf16 v[2:5], v[188:191], v[220:223], v[2:5]
	v_mfma_f32_16x16x32_bf16 v[6:9], v[180:183], v[220:223], v[6:9]
	s_barrier
	s_setprio 0
	s_add_i32 s68, s68, 2
	s_add_u32 s66, s66, 0x100
	s_addc_u32 s67, s67, 0
	s_cmp_gt_u32 s68, 41
	s_mov_b64 s[42:43], s[40:41]
	s_cbranch_scc0 .LBB0_1295
	s_and_b64 vcc, exec, s[22:23]
	s_cbranch_vccz .LBB0_1298
	s_barrier
